# speedup vs baseline: 1.0494x; 1.0494x over previous
; DI unsigned pk2(float lo, float hi) { const f32x2_t v = {lo, hi}; const bf16x2_t b = __builtin_convertvector(v, bf16x2_t); return __builtin_bit_cast(unsigned, b); }
; DI float lo16(unsigned w) { return __uint_as_float(w << 16); }
; DI float hi16(unsigned w) { return __uint_as_float(w & 0xffff0000u); }
;     DI void operator()(const pg8::f32x4 (&acc)[2][2][4][2], const pg8::Unit& u, int wr, int wc, int fr, int fq) const {
;         const int row0 = u.pm * 256 + wr * 64 + fr, col0 = u.pn * 256 + wc * 32 + 8 * fq;
; #pragma unroll
;         for (int ai = 0; ai < 2; ++ai)
; #pragma unroll
;             for (int m = 0; m < 4; ++m) {
;                 const int row = row0 + ai * 128 + m * 16;
;                 bf16_t* xrow = xb + (size_t)row * 1024 + col0;
;                 u32x4 xo[2];
; #pragma unroll
;                 for (int bj = 0; bj < 2; ++bj) xo[bj] = *(const u32x4*)(xrow + bj * 128);
;                 float part = 0.f;
; #pragma unroll
;                 for (int bj = 0; bj < 2; ++bj) { const pg8::f32x4 a0 = acc[ai][bj][m][0], a1 = acc[ai][bj][m][1];
;                     const float o0 = lo16(xo[bj].x) + a0[0], o1 = hi16(xo[bj].x) + a0[1], o2 = lo16(xo[bj].y) + a0[2], o3 = hi16(xo[bj].y) + a0[3];
;                     const float o4 = lo16(xo[bj].z) + a1[0], o5 = hi16(xo[bj].z) + a1[1], o6 = lo16(xo[bj].w) + a1[2], o7 = hi16(xo[bj].w) + a1[3];
;                     u32x4 w; w.x = pk2(o0, o1); w.y = pk2(o2, o3); w.z = pk2(o4, o5); w.w = pk2(o6, o7); *(u32x4*)(xrow + bj * 128) = w;
;                     part += ((o0 * o0 + o1 * o1) + (o2 * o2 + o3 * o3)) + ((o4 * o4 + o5 * o5) + (o6 * o6 + o7 * o7)); }
;                 part += __shfl_xor(part, 16); part += __shfl_xor(part, 32);
;                 if (fq == 0) ssout[(size_t)row * 16 + u.pn * 4 + wc] = part;
;             }
;     }
.LBB0_63:
	v_and_b32_e32 v146, 64, v177
	v_xor_b32_e32 v141, 16, v177
	v_add_u32_e32 v146, 64, v146
	v_cmp_lt_i32_e32 vcc, v141, v146
	v_lshl_add_u32 v140, s62, 8, v142
	v_lshl_or_b32 v138, s56, 8, v144
	v_cndmask_b32_e32 v141, v177, v141, vcc
	v_lshlrev_b32_e32 v147, 2, v141
	v_xor_b32_e32 v141, 32, v177
	v_cmp_lt_i32_e32 vcc, v141, v146
	v_ashrrev_i32_e32 v139, 31, v138
	s_lshl_b32 s26, s56, 2
	v_cndmask_b32_e32 v141, v177, v141, vcc
	v_lshlrev_b32_e32 v146, 2, v141
	v_ashrrev_i32_e32 v141, 31, v140
	v_lshlrev_b64 v[148:149], 11, v[140:141]
	v_lshl_add_u64 v[148:149], s[2:3], 0, v[148:149]
	v_lshl_add_u64 v[156:157], v[138:139], 1, v[148:149]
	global_load_dwordx4 v[148:151], v[156:157], off
	global_load_dwordx4 v[152:155], v[156:157], off offset:256
	s_ashr_i32 s27, s26, 31
	s_waitcnt vmcnt(0)
	v_lshlrev_b32_e32 v158, 16, v148
	v_and_b32_e32 v159, 0xffff0000, v148
	v_lshlrev_b32_e32 v148, 16, v149
	v_and_b32_e32 v149, 0xffff0000, v149
	v_pk_add_f32 v[126:127], v[126:127], v[148:149]
	v_lshlrev_b32_e32 v148, 16, v150
	v_and_b32_e32 v149, 0xffff0000, v150
	v_pk_add_f32 v[148:149], v[120:121], v[148:149]
	v_lshlrev_b32_e32 v120, 16, v151
	v_and_b32_e32 v121, 0xffff0000, v151
	v_pk_add_f32 v[124:125], v[124:125], v[158:159]
	v_pk_add_f32 v[150:151], v[122:123], v[120:121]
	v_cvt_pk_bf16_f32 v120, v124, v125
	v_cvt_pk_bf16_f32 v121, v126, v127
	v_cvt_pk_bf16_f32 v122, v148, v149
	v_cvt_pk_bf16_f32 v123, v150, v151
	global_store_dwordx4 v[156:157], v[120:123], off
	s_nop 1
	v_pk_mul_f32 v[120:121], v[124:125], v[124:125]
	v_pk_mul_f32 v[124:125], v[148:149], v[148:149]
	v_lshlrev_b32_e32 v148, 16, v152
	v_and_b32_e32 v149, 0xffff0000, v152
	v_pk_add_f32 v[116:117], v[116:117], v[148:149]
	v_lshlrev_b32_e32 v148, 16, v153
	v_and_b32_e32 v149, 0xffff0000, v153
	v_pk_add_f32 v[118:119], v[118:119], v[148:149]
	v_lshlrev_b32_e32 v148, 16, v154
	v_and_b32_e32 v149, 0xffff0000, v154
	v_pk_add_f32 v[148:149], v[112:113], v[148:149]
	v_lshlrev_b32_e32 v112, 16, v155
	v_and_b32_e32 v113, 0xffff0000, v155
	v_pk_mul_f32 v[122:123], v[126:127], v[126:127]
	v_pk_mul_f32 v[126:127], v[150:151], v[150:151]
	v_pk_add_f32 v[150:151], v[114:115], v[112:113]
	v_cvt_pk_bf16_f32 v112, v116, v117
	v_cvt_pk_bf16_f32 v113, v118, v119
	v_cvt_pk_bf16_f32 v114, v148, v149
	v_cvt_pk_bf16_f32 v115, v150, v151
	global_store_dwordx4 v[156:157], v[112:115], off offset:256
	s_nop 1
	v_pk_mul_f32 v[112:113], v[116:117], v[116:117]
	v_pk_mul_f32 v[114:115], v[118:119], v[118:119]
	v_add_f32_e32 v112, v112, v113
	v_add_f32_e32 v114, v114, v115
	v_pk_mul_f32 v[116:117], v[148:149], v[148:149]
	v_pk_mul_f32 v[118:119], v[150:151], v[150:151]
	v_add_f32_e32 v112, v112, v114
	v_add_f32_e32 v113, v126, v127
	v_add_f32_e32 v114, v124, v125
	v_add_f32_e32 v118, v118, v119
	v_add_f32_e32 v116, v116, v117
	v_add_f32_e32 v113, v114, v113
	v_add_f32_e32 v114, v122, v123
	v_add_f32_e32 v115, v120, v121
	v_add_f32_e32 v116, v116, v118
	v_add_f32_e32 v114, v115, v114
	v_add_f32_e32 v112, v112, v116
	v_add_f32_e32 v113, v114, v113
	v_add_f32_e32 v112, v113, v112
	ds_bpermute_b32 v113, v147, v112
	s_waitcnt lgkmcnt(0)
	v_add_f32_e32 v112, v112, v113
	ds_bpermute_b32 v113, v146, v112
	s_and_saveexec_b64 s[30:31], s[40:41]
	s_cbranch_execz .LBB0_65
	v_lshlrev_b64 v[114:115], 6, v[140:141]
	v_lshl_add_u64 v[114:115], s[6:7], 0, v[114:115]
	v_lshl_add_u64 v[114:115], s[26:27], 2, v[114:115]
	s_lshl_b32 s94, s53, 2
	v_lshl_add_u64 v[114:115], v[114:115], 0, s[94:95]
	s_waitcnt lgkmcnt(0)
	v_add_f32_e32 v112, v112, v113
	global_store_dword v[114:115], v112, off
.LBB0_65:
	s_or_b64 exec, exec, s[30:31]
	v_or_b32_e32 v112, 16, v140
	s_waitcnt lgkmcnt(0)
	v_ashrrev_i32_e32 v113, 31, v112
	v_lshlrev_b64 v[114:115], 11, v[112:113]
	v_lshl_add_u64 v[114:115], s[2:3], 0, v[114:115]
	v_lshl_add_u64 v[122:123], v[138:139], 1, v[114:115]
	global_load_dwordx4 v[114:117], v[122:123], off
	global_load_dwordx4 v[118:121], v[122:123], off offset:256
	s_waitcnt vmcnt(1)
	v_lshlrev_b32_e32 v124, 16, v114
	v_and_b32_e32 v125, 0xffff0000, v114
	v_lshlrev_b32_e32 v114, 16, v115
	v_and_b32_e32 v115, 0xffff0000, v115
	v_pk_add_f32 v[110:111], v[110:111], v[114:115]
	v_lshlrev_b32_e32 v114, 16, v116
	v_and_b32_e32 v115, 0xffff0000, v116
	v_pk_add_f32 v[114:115], v[104:105], v[114:115]
	v_lshlrev_b32_e32 v104, 16, v117
	v_and_b32_e32 v105, 0xffff0000, v117
	v_pk_add_f32 v[108:109], v[108:109], v[124:125]
	v_pk_add_f32 v[116:117], v[106:107], v[104:105]
	v_cvt_pk_bf16_f32 v104, v108, v109
	v_cvt_pk_bf16_f32 v105, v110, v111
	v_cvt_pk_bf16_f32 v106, v114, v115
	v_cvt_pk_bf16_f32 v107, v116, v117
	global_store_dwordx4 v[122:123], v[104:107], off
	s_nop 1
	v_pk_mul_f32 v[104:105], v[108:109], v[108:109]
	v_pk_mul_f32 v[108:109], v[114:115], v[114:115]
	s_waitcnt vmcnt(1)
	v_lshlrev_b32_e32 v114, 16, v118
	v_and_b32_e32 v115, 0xffff0000, v118
	v_pk_add_f32 v[100:101], v[100:101], v[114:115]
	v_lshlrev_b32_e32 v114, 16, v119
	v_and_b32_e32 v115, 0xffff0000, v119
	v_pk_add_f32 v[102:103], v[102:103], v[114:115]
	v_lshlrev_b32_e32 v114, 16, v120
	v_and_b32_e32 v115, 0xffff0000, v120
	v_pk_add_f32 v[114:115], v[96:97], v[114:115]
	v_lshlrev_b32_e32 v96, 16, v121
	v_and_b32_e32 v97, 0xffff0000, v121
	v_pk_mul_f32 v[106:107], v[110:111], v[110:111]
	v_pk_mul_f32 v[110:111], v[116:117], v[116:117]
	v_pk_add_f32 v[116:117], v[98:99], v[96:97]
	v_cvt_pk_bf16_f32 v96, v100, v101
	v_cvt_pk_bf16_f32 v97, v102, v103
	v_cvt_pk_bf16_f32 v98, v114, v115
	v_cvt_pk_bf16_f32 v99, v116, v117
	global_store_dwordx4 v[122:123], v[96:99], off offset:256
	s_nop 1
	v_pk_mul_f32 v[96:97], v[100:101], v[100:101]
	v_pk_mul_f32 v[98:99], v[102:103], v[102:103]
	v_add_f32_e32 v96, v96, v97
	v_add_f32_e32 v98, v98, v99
	v_pk_mul_f32 v[100:101], v[114:115], v[114:115]
	v_pk_mul_f32 v[102:103], v[116:117], v[116:117]
	v_add_f32_e32 v96, v96, v98
	v_add_f32_e32 v97, v110, v111
	v_add_f32_e32 v98, v108, v109
	v_add_f32_e32 v102, v102, v103
	v_add_f32_e32 v100, v100, v101
	v_add_f32_e32 v97, v98, v97
	v_add_f32_e32 v98, v106, v107
	v_add_f32_e32 v99, v104, v105
	v_add_f32_e32 v100, v100, v102
	v_add_f32_e32 v98, v99, v98
	v_add_f32_e32 v96, v96, v100
	v_add_f32_e32 v97, v98, v97
	v_add_f32_e32 v96, v97, v96
	ds_bpermute_b32 v97, v147, v96
	s_waitcnt lgkmcnt(0)
	v_add_f32_e32 v96, v96, v97
	ds_bpermute_b32 v97, v146, v96
	s_and_saveexec_b64 s[30:31], s[40:41]
	s_cbranch_execz .LBB0_67
	v_lshlrev_b64 v[98:99], 6, v[112:113]
	v_lshl_add_u64 v[98:99], s[6:7], 0, v[98:99]
	v_lshl_add_u64 v[98:99], s[26:27], 2, v[98:99]
	s_lshl_b32 s94, s53, 2
	v_lshl_add_u64 v[98:99], v[98:99], 0, s[94:95]
	s_waitcnt lgkmcnt(0)
	v_add_f32_e32 v96, v96, v97
	global_store_dword v[98:99], v96, off
; DI unsigned pk2(float lo, float hi) { const f32x2_t v = {lo, hi}; const bf16x2_t b = __builtin_convertvector(v, bf16x2_t); return __builtin_bit_cast(unsigned, b); }
; DI float lo16(unsigned w) { return __uint_as_float(w << 16); }
; DI float hi16(unsigned w) { return __uint_as_float(w & 0xffff0000u); }
;     DI void operator()(const pg8::f32x4 (&acc)[2][2][4][2], const pg8::Unit& u, int wr, int wc, int fr, int fq) const {
;         const int row0 = u.pm * 256 + wr * 64 + fr, col0 = u.pn * 256 + wc * 32 + 8 * fq;
; #pragma unroll
;         for (int ai = 0; ai < 2; ++ai)
; #pragma unroll
;             for (int m = 0; m < 4; ++m) {
;                 const int row = row0 + ai * 128 + m * 16;
;                 bf16_t* xrow = xb + (size_t)row * 1024 + col0;
;                 u32x4 xo[2];
; #pragma unroll
;                 for (int bj = 0; bj < 2; ++bj) xo[bj] = *(const u32x4*)(xrow + bj * 128);
;                 float part = 0.f;
; #pragma unroll
;                 for (int bj = 0; bj < 2; ++bj) { const pg8::f32x4 a0 = acc[ai][bj][m][0], a1 = acc[ai][bj][m][1];
;                     const float o0 = lo16(xo[bj].x) + a0[0], o1 = hi16(xo[bj].x) + a0[1], o2 = lo16(xo[bj].y) + a0[2], o3 = hi16(xo[bj].y) + a0[3];
;                     const float o4 = lo16(xo[bj].z) + a1[0], o5 = hi16(xo[bj].z) + a1[1], o6 = lo16(xo[bj].w) + a1[2], o7 = hi16(xo[bj].w) + a1[3];
;                     u32x4 w; w.x = pk2(o0, o1); w.y = pk2(o2, o3); w.z = pk2(o4, o5); w.w = pk2(o6, o7); *(u32x4*)(xrow + bj * 128) = w;
;                     part += ((o0 * o0 + o1 * o1) + (o2 * o2 + o3 * o3)) + ((o4 * o4 + o5 * o5) + (o6 * o6 + o7 * o7)); }
;                 part += __shfl_xor(part, 16); part += __shfl_xor(part, 32);
;                 if (fq == 0) ssout[(size_t)row * 16 + u.pn * 4 + wc] = part;
;             }
;     }
.LBB0_67:
	s_or_b64 exec, exec, s[30:31]
	v_or_b32_e32 v96, 32, v140
	s_waitcnt lgkmcnt(0)
	v_ashrrev_i32_e32 v97, 31, v96
	v_lshlrev_b64 v[98:99], 11, v[96:97]
	v_lshl_add_u64 v[98:99], s[2:3], 0, v[98:99]
	v_lshl_add_u64 v[106:107], v[138:139], 1, v[98:99]
	global_load_dwordx4 v[98:101], v[106:107], off
	global_load_dwordx4 v[102:105], v[106:107], off offset:256
	s_waitcnt vmcnt(1)
	v_lshlrev_b32_e32 v108, 16, v98
	v_and_b32_e32 v109, 0xffff0000, v98
	v_lshlrev_b32_e32 v98, 16, v99
	v_and_b32_e32 v99, 0xffff0000, v99
	v_pk_add_f32 v[94:95], v[94:95], v[98:99]
	v_lshlrev_b32_e32 v98, 16, v100
	v_and_b32_e32 v99, 0xffff0000, v100
	v_pk_add_f32 v[98:99], v[88:89], v[98:99]
	v_lshlrev_b32_e32 v88, 16, v101
	v_and_b32_e32 v89, 0xffff0000, v101
	v_pk_add_f32 v[92:93], v[92:93], v[108:109]
	v_pk_add_f32 v[100:101], v[90:91], v[88:89]
	v_cvt_pk_bf16_f32 v88, v92, v93
	v_cvt_pk_bf16_f32 v89, v94, v95
	v_cvt_pk_bf16_f32 v90, v98, v99
	v_cvt_pk_bf16_f32 v91, v100, v101
	global_store_dwordx4 v[106:107], v[88:91], off
	s_nop 1
	v_pk_mul_f32 v[88:89], v[92:93], v[92:93]
	v_pk_mul_f32 v[92:93], v[98:99], v[98:99]
	s_waitcnt vmcnt(1)
	v_lshlrev_b32_e32 v98, 16, v102
	v_and_b32_e32 v99, 0xffff0000, v102
	v_pk_add_f32 v[84:85], v[84:85], v[98:99]
	v_lshlrev_b32_e32 v98, 16, v103
	v_and_b32_e32 v99, 0xffff0000, v103
	v_pk_add_f32 v[86:87], v[86:87], v[98:99]
	v_lshlrev_b32_e32 v98, 16, v104
	v_and_b32_e32 v99, 0xffff0000, v104
	v_pk_add_f32 v[98:99], v[80:81], v[98:99]
	v_lshlrev_b32_e32 v80, 16, v105
	v_and_b32_e32 v81, 0xffff0000, v105
	v_pk_mul_f32 v[90:91], v[94:95], v[94:95]
	v_pk_mul_f32 v[94:95], v[100:101], v[100:101]
	v_pk_add_f32 v[100:101], v[82:83], v[80:81]
	v_cvt_pk_bf16_f32 v80, v84, v85
	v_cvt_pk_bf16_f32 v81, v86, v87
	v_cvt_pk_bf16_f32 v82, v98, v99
	v_cvt_pk_bf16_f32 v83, v100, v101
	global_store_dwordx4 v[106:107], v[80:83], off offset:256
	s_nop 1
	v_pk_mul_f32 v[80:81], v[84:85], v[84:85]
	v_pk_mul_f32 v[82:83], v[86:87], v[86:87]
	v_add_f32_e32 v80, v80, v81
	v_add_f32_e32 v82, v82, v83
	v_pk_mul_f32 v[84:85], v[98:99], v[98:99]
	v_pk_mul_f32 v[86:87], v[100:101], v[100:101]
	v_add_f32_e32 v80, v80, v82
	v_add_f32_e32 v81, v94, v95
	v_add_f32_e32 v82, v92, v93
	v_add_f32_e32 v86, v86, v87
	v_add_f32_e32 v84, v84, v85
	v_add_f32_e32 v81, v82, v81
	v_add_f32_e32 v82, v90, v91
	v_add_f32_e32 v83, v88, v89
	v_add_f32_e32 v84, v84, v86
	v_add_f32_e32 v82, v83, v82
	v_add_f32_e32 v80, v80, v84
	v_add_f32_e32 v81, v82, v81
	v_add_f32_e32 v80, v81, v80
	ds_bpermute_b32 v81, v147, v80
	s_waitcnt lgkmcnt(0)
	v_add_f32_e32 v80, v80, v81
	ds_bpermute_b32 v81, v146, v80
	s_and_saveexec_b64 s[30:31], s[40:41]
	s_cbranch_execz .LBB0_69
	v_lshlrev_b64 v[82:83], 6, v[96:97]
	v_lshl_add_u64 v[82:83], s[6:7], 0, v[82:83]
	v_lshl_add_u64 v[82:83], s[26:27], 2, v[82:83]
	s_lshl_b32 s94, s53, 2
	v_lshl_add_u64 v[82:83], v[82:83], 0, s[94:95]
	s_waitcnt lgkmcnt(0)
	v_add_f32_e32 v80, v80, v81
	global_store_dword v[82:83], v80, off
.LBB0_69:
	s_or_b64 exec, exec, s[30:31]
	v_or_b32_e32 v80, 48, v140
	s_waitcnt lgkmcnt(0)
	v_ashrrev_i32_e32 v81, 31, v80
	v_lshlrev_b64 v[82:83], 11, v[80:81]
	v_lshl_add_u64 v[82:83], s[2:3], 0, v[82:83]
	v_lshl_add_u64 v[90:91], v[138:139], 1, v[82:83]
	global_load_dwordx4 v[82:85], v[90:91], off
	global_load_dwordx4 v[86:89], v[90:91], off offset:256
	s_waitcnt vmcnt(1)
	v_lshlrev_b32_e32 v92, 16, v82
	v_and_b32_e32 v93, 0xffff0000, v82
	v_lshlrev_b32_e32 v82, 16, v83
	v_and_b32_e32 v83, 0xffff0000, v83
	v_pk_add_f32 v[78:79], v[78:79], v[82:83]
	v_lshlrev_b32_e32 v82, 16, v84
	v_and_b32_e32 v83, 0xffff0000, v84
	v_pk_add_f32 v[82:83], v[72:73], v[82:83]
	v_lshlrev_b32_e32 v72, 16, v85
	v_and_b32_e32 v73, 0xffff0000, v85
	v_pk_add_f32 v[76:77], v[76:77], v[92:93]
	v_pk_add_f32 v[84:85], v[74:75], v[72:73]
	v_cvt_pk_bf16_f32 v72, v76, v77
	v_cvt_pk_bf16_f32 v73, v78, v79
	v_cvt_pk_bf16_f32 v74, v82, v83
	v_cvt_pk_bf16_f32 v75, v84, v85
	global_store_dwordx4 v[90:91], v[72:75], off
	s_nop 1
	v_pk_mul_f32 v[72:73], v[76:77], v[76:77]
	v_pk_mul_f32 v[76:77], v[82:83], v[82:83]
	s_waitcnt vmcnt(1)
	v_lshlrev_b32_e32 v82, 16, v86
	v_and_b32_e32 v83, 0xffff0000, v86
	v_pk_add_f32 v[68:69], v[68:69], v[82:83]
	v_lshlrev_b32_e32 v82, 16, v87
	v_and_b32_e32 v83, 0xffff0000, v87
	v_pk_add_f32 v[70:71], v[70:71], v[82:83]
	v_lshlrev_b32_e32 v82, 16, v88
	v_and_b32_e32 v83, 0xffff0000, v88
	v_pk_add_f32 v[82:83], v[64:65], v[82:83]
	v_lshlrev_b32_e32 v64, 16, v89
	v_and_b32_e32 v65, 0xffff0000, v89
	v_pk_mul_f32 v[74:75], v[78:79], v[78:79]
	v_pk_mul_f32 v[78:79], v[84:85], v[84:85]
	v_pk_add_f32 v[84:85], v[66:67], v[64:65]
	v_cvt_pk_bf16_f32 v64, v68, v69
	v_cvt_pk_bf16_f32 v65, v70, v71
	v_cvt_pk_bf16_f32 v66, v82, v83
	v_cvt_pk_bf16_f32 v67, v84, v85
	global_store_dwordx4 v[90:91], v[64:67], off offset:256
	s_nop 1
	v_pk_mul_f32 v[64:65], v[68:69], v[68:69]
	v_pk_mul_f32 v[66:67], v[70:71], v[70:71]
	v_add_f32_e32 v64, v64, v65
	v_add_f32_e32 v66, v66, v67
	v_pk_mul_f32 v[68:69], v[82:83], v[82:83]
	v_pk_mul_f32 v[70:71], v[84:85], v[84:85]
	v_add_f32_e32 v64, v64, v66
	v_add_f32_e32 v65, v78, v79
	v_add_f32_e32 v66, v76, v77
	v_add_f32_e32 v70, v70, v71
	v_add_f32_e32 v68, v68, v69
	v_add_f32_e32 v65, v66, v65
	v_add_f32_e32 v66, v74, v75
	v_add_f32_e32 v67, v72, v73
	v_add_f32_e32 v68, v68, v70
	v_add_f32_e32 v66, v67, v66
	v_add_f32_e32 v64, v64, v68
	v_add_f32_e32 v65, v66, v65
	v_add_f32_e32 v64, v65, v64
	ds_bpermute_b32 v65, v147, v64
	s_waitcnt lgkmcnt(0)
	v_add_f32_e32 v64, v64, v65
	ds_bpermute_b32 v65, v146, v64
	s_and_saveexec_b64 s[30:31], s[40:41]
	s_cbranch_execz .LBB0_71
	v_lshlrev_b64 v[66:67], 6, v[80:81]
	v_lshl_add_u64 v[66:67], s[6:7], 0, v[66:67]
	v_lshl_add_u64 v[66:67], s[26:27], 2, v[66:67]
	s_lshl_b32 s94, s53, 2
	v_lshl_add_u64 v[66:67], v[66:67], 0, s[94:95]
	s_waitcnt lgkmcnt(0)
	v_add_f32_e32 v64, v64, v65
	global_store_dword v[66:67], v64, off
; DI unsigned pk2(float lo, float hi) { const f32x2_t v = {lo, hi}; const bf16x2_t b = __builtin_convertvector(v, bf16x2_t); return __builtin_bit_cast(unsigned, b); }
; DI float lo16(unsigned w) { return __uint_as_float(w << 16); }
; DI float hi16(unsigned w) { return __uint_as_float(w & 0xffff0000u); }
;     DI void operator()(const pg8::f32x4 (&acc)[2][2][4][2], const pg8::Unit& u, int wr, int wc, int fr, int fq) const {
;         const int row0 = u.pm * 256 + wr * 64 + fr, col0 = u.pn * 256 + wc * 32 + 8 * fq;
; #pragma unroll
;         for (int ai = 0; ai < 2; ++ai)
; #pragma unroll
;             for (int m = 0; m < 4; ++m) {
;                 const int row = row0 + ai * 128 + m * 16;
;                 bf16_t* xrow = xb + (size_t)row * 1024 + col0;
;                 u32x4 xo[2];
; #pragma unroll
;                 for (int bj = 0; bj < 2; ++bj) xo[bj] = *(const u32x4*)(xrow + bj * 128);
;                 float part = 0.f;
; #pragma unroll
;                 for (int bj = 0; bj < 2; ++bj) { const pg8::f32x4 a0 = acc[ai][bj][m][0], a1 = acc[ai][bj][m][1];
;                     const float o0 = lo16(xo[bj].x) + a0[0], o1 = hi16(xo[bj].x) + a0[1], o2 = lo16(xo[bj].y) + a0[2], o3 = hi16(xo[bj].y) + a0[3];
;                     const float o4 = lo16(xo[bj].z) + a1[0], o5 = hi16(xo[bj].z) + a1[1], o6 = lo16(xo[bj].w) + a1[2], o7 = hi16(xo[bj].w) + a1[3];
;                     u32x4 w; w.x = pk2(o0, o1); w.y = pk2(o2, o3); w.z = pk2(o4, o5); w.w = pk2(o6, o7); *(u32x4*)(xrow + bj * 128) = w;
;                     part += ((o0 * o0 + o1 * o1) + (o2 * o2 + o3 * o3)) + ((o4 * o4 + o5 * o5) + (o6 * o6 + o7 * o7)); }
;                 part += __shfl_xor(part, 16); part += __shfl_xor(part, 32);
;                 if (fq == 0) ssout[(size_t)row * 16 + u.pn * 4 + wc] = part;
;             }
;     }
.LBB0_71:
	s_or_b64 exec, exec, s[30:31]
	v_add_u32_e32 v64, 0x80, v140
	s_waitcnt lgkmcnt(0)
	v_ashrrev_i32_e32 v65, 31, v64
	v_lshlrev_b64 v[66:67], 11, v[64:65]
	v_lshl_add_u64 v[66:67], s[2:3], 0, v[66:67]
	v_lshl_add_u64 v[74:75], v[138:139], 1, v[66:67]
	global_load_dwordx4 v[66:69], v[74:75], off
	global_load_dwordx4 v[70:73], v[74:75], off offset:256
	s_waitcnt vmcnt(1)
	v_lshlrev_b32_e32 v76, 16, v66
	v_and_b32_e32 v77, 0xffff0000, v66
	v_lshlrev_b32_e32 v66, 16, v67
	v_and_b32_e32 v67, 0xffff0000, v67
	v_pk_add_f32 v[62:63], v[62:63], v[66:67]
	v_lshlrev_b32_e32 v66, 16, v68
	v_and_b32_e32 v67, 0xffff0000, v68
	v_pk_add_f32 v[66:67], v[56:57], v[66:67]
	v_lshlrev_b32_e32 v56, 16, v69
	v_and_b32_e32 v57, 0xffff0000, v69
	v_pk_add_f32 v[60:61], v[60:61], v[76:77]
	v_pk_add_f32 v[68:69], v[58:59], v[56:57]
	v_cvt_pk_bf16_f32 v56, v60, v61
	v_cvt_pk_bf16_f32 v57, v62, v63
	v_cvt_pk_bf16_f32 v58, v66, v67
	v_cvt_pk_bf16_f32 v59, v68, v69
	global_store_dwordx4 v[74:75], v[56:59], off
	s_nop 1
	v_pk_mul_f32 v[56:57], v[60:61], v[60:61]
	v_pk_mul_f32 v[60:61], v[66:67], v[66:67]
	s_waitcnt vmcnt(1)
	v_lshlrev_b32_e32 v66, 16, v70
	v_and_b32_e32 v67, 0xffff0000, v70
	v_pk_add_f32 v[52:53], v[52:53], v[66:67]
	v_lshlrev_b32_e32 v66, 16, v71
	v_and_b32_e32 v67, 0xffff0000, v71
	v_pk_add_f32 v[54:55], v[54:55], v[66:67]
	v_lshlrev_b32_e32 v66, 16, v72
	v_and_b32_e32 v67, 0xffff0000, v72
	v_pk_add_f32 v[66:67], v[48:49], v[66:67]
	v_lshlrev_b32_e32 v48, 16, v73
	v_and_b32_e32 v49, 0xffff0000, v73
	v_pk_mul_f32 v[58:59], v[62:63], v[62:63]
	v_pk_mul_f32 v[62:63], v[68:69], v[68:69]
	v_pk_add_f32 v[68:69], v[50:51], v[48:49]
	v_cvt_pk_bf16_f32 v48, v52, v53
	v_cvt_pk_bf16_f32 v49, v54, v55
	v_cvt_pk_bf16_f32 v50, v66, v67
	v_cvt_pk_bf16_f32 v51, v68, v69
	global_store_dwordx4 v[74:75], v[48:51], off offset:256
	s_nop 1
	v_pk_mul_f32 v[48:49], v[52:53], v[52:53]
	v_pk_mul_f32 v[50:51], v[54:55], v[54:55]
	v_add_f32_e32 v48, v48, v49
	v_add_f32_e32 v50, v50, v51
	v_pk_mul_f32 v[52:53], v[66:67], v[66:67]
	v_pk_mul_f32 v[54:55], v[68:69], v[68:69]
	v_add_f32_e32 v48, v48, v50
	v_add_f32_e32 v49, v62, v63
	v_add_f32_e32 v50, v60, v61
	v_add_f32_e32 v54, v54, v55
	v_add_f32_e32 v52, v52, v53
	v_add_f32_e32 v49, v50, v49
	v_add_f32_e32 v50, v58, v59
	v_add_f32_e32 v51, v56, v57
	v_add_f32_e32 v52, v52, v54
	v_add_f32_e32 v50, v51, v50
	v_add_f32_e32 v48, v48, v52
	v_add_f32_e32 v49, v50, v49
	v_add_f32_e32 v48, v49, v48
	ds_bpermute_b32 v49, v147, v48
	s_waitcnt lgkmcnt(0)
	v_add_f32_e32 v48, v48, v49
	ds_bpermute_b32 v49, v146, v48
	s_and_saveexec_b64 s[30:31], s[40:41]
	s_cbranch_execz .LBB0_73
	v_lshlrev_b64 v[50:51], 6, v[64:65]
	v_lshl_add_u64 v[50:51], s[6:7], 0, v[50:51]
	v_lshl_add_u64 v[50:51], s[26:27], 2, v[50:51]
	s_lshl_b32 s94, s53, 2
	v_lshl_add_u64 v[50:51], v[50:51], 0, s[94:95]
	s_waitcnt lgkmcnt(0)
	v_add_f32_e32 v48, v48, v49
	global_store_dword v[50:51], v48, off
.LBB0_73:
	s_or_b64 exec, exec, s[30:31]
	v_add_u32_e32 v48, 0x90, v140
	s_waitcnt lgkmcnt(0)
	v_ashrrev_i32_e32 v49, 31, v48
	v_lshlrev_b64 v[50:51], 11, v[48:49]
	v_lshl_add_u64 v[50:51], s[2:3], 0, v[50:51]
	v_lshl_add_u64 v[58:59], v[138:139], 1, v[50:51]
	global_load_dwordx4 v[50:53], v[58:59], off
	global_load_dwordx4 v[54:57], v[58:59], off offset:256
	s_waitcnt vmcnt(1)
	v_lshlrev_b32_e32 v60, 16, v50
	v_and_b32_e32 v61, 0xffff0000, v50
	v_lshlrev_b32_e32 v50, 16, v51
	v_and_b32_e32 v51, 0xffff0000, v51
	v_pk_add_f32 v[46:47], v[46:47], v[50:51]
	v_lshlrev_b32_e32 v50, 16, v52
	v_and_b32_e32 v51, 0xffff0000, v52
	v_pk_add_f32 v[50:51], v[40:41], v[50:51]
	v_lshlrev_b32_e32 v40, 16, v53
	v_and_b32_e32 v41, 0xffff0000, v53
	v_pk_add_f32 v[44:45], v[44:45], v[60:61]
	v_pk_add_f32 v[52:53], v[42:43], v[40:41]
	v_cvt_pk_bf16_f32 v40, v44, v45
	v_cvt_pk_bf16_f32 v41, v46, v47
	v_cvt_pk_bf16_f32 v42, v50, v51
	v_cvt_pk_bf16_f32 v43, v52, v53
	global_store_dwordx4 v[58:59], v[40:43], off
	s_nop 1
	v_pk_mul_f32 v[40:41], v[44:45], v[44:45]
	v_pk_mul_f32 v[44:45], v[50:51], v[50:51]
	s_waitcnt vmcnt(1)
	v_lshlrev_b32_e32 v50, 16, v54
	v_and_b32_e32 v51, 0xffff0000, v54
	v_pk_add_f32 v[36:37], v[36:37], v[50:51]
	v_lshlrev_b32_e32 v50, 16, v55
	v_and_b32_e32 v51, 0xffff0000, v55
	v_pk_add_f32 v[38:39], v[38:39], v[50:51]
	v_lshlrev_b32_e32 v50, 16, v56
	v_and_b32_e32 v51, 0xffff0000, v56
	v_pk_add_f32 v[50:51], v[32:33], v[50:51]
	v_lshlrev_b32_e32 v32, 16, v57
	v_and_b32_e32 v33, 0xffff0000, v57
	v_pk_mul_f32 v[42:43], v[46:47], v[46:47]
	v_pk_mul_f32 v[46:47], v[52:53], v[52:53]
	v_pk_add_f32 v[52:53], v[34:35], v[32:33]
	v_cvt_pk_bf16_f32 v32, v36, v37
	v_cvt_pk_bf16_f32 v33, v38, v39
	v_cvt_pk_bf16_f32 v34, v50, v51
	v_cvt_pk_bf16_f32 v35, v52, v53
	global_store_dwordx4 v[58:59], v[32:35], off offset:256
	s_nop 1
	v_pk_mul_f32 v[32:33], v[36:37], v[36:37]
	v_pk_mul_f32 v[34:35], v[38:39], v[38:39]
	v_add_f32_e32 v32, v32, v33
	v_add_f32_e32 v34, v34, v35
	v_pk_mul_f32 v[36:37], v[50:51], v[50:51]
	v_pk_mul_f32 v[38:39], v[52:53], v[52:53]
	v_add_f32_e32 v32, v32, v34
	v_add_f32_e32 v33, v46, v47
	v_add_f32_e32 v34, v44, v45
	v_add_f32_e32 v38, v38, v39
	v_add_f32_e32 v36, v36, v37
	v_add_f32_e32 v33, v34, v33
	v_add_f32_e32 v34, v42, v43
	v_add_f32_e32 v35, v40, v41
	v_add_f32_e32 v36, v36, v38
	v_add_f32_e32 v34, v35, v34
	v_add_f32_e32 v32, v32, v36
	v_add_f32_e32 v33, v34, v33
	v_add_f32_e32 v32, v33, v32
	ds_bpermute_b32 v33, v147, v32
	s_waitcnt lgkmcnt(0)
	v_add_f32_e32 v32, v32, v33
	ds_bpermute_b32 v33, v146, v32
	s_and_saveexec_b64 s[30:31], s[40:41]
	s_cbranch_execz .LBB0_75
	v_lshlrev_b64 v[34:35], 6, v[48:49]
	v_lshl_add_u64 v[34:35], s[6:7], 0, v[34:35]
	v_lshl_add_u64 v[34:35], s[26:27], 2, v[34:35]
	s_lshl_b32 s94, s53, 2
	v_lshl_add_u64 v[34:35], v[34:35], 0, s[94:95]
	s_waitcnt lgkmcnt(0)
	v_add_f32_e32 v32, v32, v33
	global_store_dword v[34:35], v32, off
; DI unsigned pk2(float lo, float hi) { const f32x2_t v = {lo, hi}; const bf16x2_t b = __builtin_convertvector(v, bf16x2_t); return __builtin_bit_cast(unsigned, b); }
; DI float lo16(unsigned w) { return __uint_as_float(w << 16); }
; DI float hi16(unsigned w) { return __uint_as_float(w & 0xffff0000u); }
;     DI void operator()(const pg8::f32x4 (&acc)[2][2][4][2], const pg8::Unit& u, int wr, int wc, int fr, int fq) const {
;         const int row0 = u.pm * 256 + wr * 64 + fr, col0 = u.pn * 256 + wc * 32 + 8 * fq;
; #pragma unroll
;         for (int ai = 0; ai < 2; ++ai)
; #pragma unroll
;             for (int m = 0; m < 4; ++m) {
;                 const int row = row0 + ai * 128 + m * 16;
;                 bf16_t* xrow = xb + (size_t)row * 1024 + col0;
;                 u32x4 xo[2];
; #pragma unroll
;                 for (int bj = 0; bj < 2; ++bj) xo[bj] = *(const u32x4*)(xrow + bj * 128);
;                 float part = 0.f;
; #pragma unroll
;                 for (int bj = 0; bj < 2; ++bj) { const pg8::f32x4 a0 = acc[ai][bj][m][0], a1 = acc[ai][bj][m][1];
;                     const float o0 = lo16(xo[bj].x) + a0[0], o1 = hi16(xo[bj].x) + a0[1], o2 = lo16(xo[bj].y) + a0[2], o3 = hi16(xo[bj].y) + a0[3];
;                     const float o4 = lo16(xo[bj].z) + a1[0], o5 = hi16(xo[bj].z) + a1[1], o6 = lo16(xo[bj].w) + a1[2], o7 = hi16(xo[bj].w) + a1[3];
;                     u32x4 w; w.x = pk2(o0, o1); w.y = pk2(o2, o3); w.z = pk2(o4, o5); w.w = pk2(o6, o7); *(u32x4*)(xrow + bj * 128) = w;
;                     part += ((o0 * o0 + o1 * o1) + (o2 * o2 + o3 * o3)) + ((o4 * o4 + o5 * o5) + (o6 * o6 + o7 * o7)); }
;                 part += __shfl_xor(part, 16); part += __shfl_xor(part, 32);
;                 if (fq == 0) ssout[(size_t)row * 16 + u.pn * 4 + wc] = part;
;             }
;     }
.LBB0_75:
	s_or_b64 exec, exec, s[30:31]
	v_add_u32_e32 v32, 0xa0, v140
	s_waitcnt lgkmcnt(0)
	v_ashrrev_i32_e32 v33, 31, v32
	v_lshlrev_b64 v[34:35], 11, v[32:33]
	v_lshl_add_u64 v[34:35], s[2:3], 0, v[34:35]
	v_lshl_add_u64 v[42:43], v[138:139], 1, v[34:35]
	global_load_dwordx4 v[34:37], v[42:43], off
	global_load_dwordx4 v[38:41], v[42:43], off offset:256
	s_waitcnt vmcnt(1)
	v_lshlrev_b32_e32 v44, 16, v34
	v_and_b32_e32 v45, 0xffff0000, v34
	v_lshlrev_b32_e32 v34, 16, v35
	v_and_b32_e32 v35, 0xffff0000, v35
	v_pk_add_f32 v[30:31], v[30:31], v[34:35]
	v_lshlrev_b32_e32 v34, 16, v36
	v_and_b32_e32 v35, 0xffff0000, v36
	v_pk_add_f32 v[34:35], v[24:25], v[34:35]
	v_lshlrev_b32_e32 v24, 16, v37
	v_and_b32_e32 v25, 0xffff0000, v37
	v_pk_add_f32 v[28:29], v[28:29], v[44:45]
	v_pk_add_f32 v[36:37], v[26:27], v[24:25]
	v_cvt_pk_bf16_f32 v24, v28, v29
	v_cvt_pk_bf16_f32 v25, v30, v31
	v_cvt_pk_bf16_f32 v26, v34, v35
	v_cvt_pk_bf16_f32 v27, v36, v37
	global_store_dwordx4 v[42:43], v[24:27], off
	s_nop 1
	v_pk_mul_f32 v[24:25], v[28:29], v[28:29]
	v_pk_mul_f32 v[28:29], v[34:35], v[34:35]
	s_waitcnt vmcnt(1)
	v_lshlrev_b32_e32 v34, 16, v38
	v_and_b32_e32 v35, 0xffff0000, v38
	v_pk_add_f32 v[20:21], v[20:21], v[34:35]
	v_lshlrev_b32_e32 v34, 16, v39
	v_and_b32_e32 v35, 0xffff0000, v39
	v_pk_add_f32 v[22:23], v[22:23], v[34:35]
	v_lshlrev_b32_e32 v34, 16, v40
	v_and_b32_e32 v35, 0xffff0000, v40
	v_pk_add_f32 v[34:35], v[16:17], v[34:35]
	v_lshlrev_b32_e32 v16, 16, v41
	v_and_b32_e32 v17, 0xffff0000, v41
	v_pk_mul_f32 v[26:27], v[30:31], v[30:31]
	v_pk_mul_f32 v[30:31], v[36:37], v[36:37]
	v_pk_add_f32 v[36:37], v[18:19], v[16:17]
	v_cvt_pk_bf16_f32 v16, v20, v21
	v_cvt_pk_bf16_f32 v17, v22, v23
	v_cvt_pk_bf16_f32 v18, v34, v35
	v_cvt_pk_bf16_f32 v19, v36, v37
	global_store_dwordx4 v[42:43], v[16:19], off offset:256
	s_nop 1
	v_pk_mul_f32 v[16:17], v[20:21], v[20:21]
	v_pk_mul_f32 v[18:19], v[22:23], v[22:23]
	v_add_f32_e32 v16, v16, v17
	v_add_f32_e32 v18, v18, v19
	v_pk_mul_f32 v[20:21], v[34:35], v[34:35]
	v_pk_mul_f32 v[22:23], v[36:37], v[36:37]
	v_add_f32_e32 v16, v16, v18
	v_add_f32_e32 v17, v30, v31
	v_add_f32_e32 v18, v28, v29
	v_add_f32_e32 v22, v22, v23
	v_add_f32_e32 v20, v20, v21
	v_add_f32_e32 v17, v18, v17
	v_add_f32_e32 v18, v26, v27
	v_add_f32_e32 v19, v24, v25
	v_add_f32_e32 v20, v20, v22
	v_add_f32_e32 v18, v19, v18
	v_add_f32_e32 v16, v16, v20
	v_add_f32_e32 v17, v18, v17
	v_add_f32_e32 v16, v17, v16
	ds_bpermute_b32 v17, v147, v16
	s_waitcnt lgkmcnt(0)
	v_add_f32_e32 v16, v16, v17
	ds_bpermute_b32 v17, v146, v16
	s_and_saveexec_b64 s[30:31], s[40:41]
	s_cbranch_execz .LBB0_77
	v_lshlrev_b64 v[18:19], 6, v[32:33]
	v_lshl_add_u64 v[18:19], s[6:7], 0, v[18:19]
	v_lshl_add_u64 v[18:19], s[26:27], 2, v[18:19]
	s_lshl_b32 s94, s53, 2
	v_lshl_add_u64 v[18:19], v[18:19], 0, s[94:95]
	s_waitcnt lgkmcnt(0)
	v_add_f32_e32 v16, v16, v17
	global_store_dword v[18:19], v16, off
.LBB0_77:
	s_or_b64 exec, exec, s[30:31]
	v_add_u32_e32 v16, 0xb0, v140
	s_waitcnt lgkmcnt(0)
	v_ashrrev_i32_e32 v17, 31, v16
	v_lshlrev_b64 v[18:19], 11, v[16:17]
	v_lshl_add_u64 v[18:19], s[2:3], 0, v[18:19]
	v_lshl_add_u64 v[26:27], v[138:139], 1, v[18:19]
	global_load_dwordx4 v[18:21], v[26:27], off
	global_load_dwordx4 v[22:25], v[26:27], off offset:256
	s_waitcnt vmcnt(1)
	v_lshlrev_b32_e32 v28, 16, v18
	v_and_b32_e32 v29, 0xffff0000, v18
	v_lshlrev_b32_e32 v18, 16, v19
	v_and_b32_e32 v19, 0xffff0000, v19
	v_pk_add_f32 v[14:15], v[14:15], v[18:19]
	v_lshlrev_b32_e32 v18, 16, v20
	v_and_b32_e32 v19, 0xffff0000, v20
	v_pk_add_f32 v[18:19], v[8:9], v[18:19]
	v_lshlrev_b32_e32 v8, 16, v21
	v_and_b32_e32 v9, 0xffff0000, v21
	v_pk_add_f32 v[12:13], v[12:13], v[28:29]
	v_pk_add_f32 v[20:21], v[10:11], v[8:9]
	v_cvt_pk_bf16_f32 v8, v12, v13
	v_cvt_pk_bf16_f32 v9, v14, v15
	v_cvt_pk_bf16_f32 v10, v18, v19
	v_cvt_pk_bf16_f32 v11, v20, v21
	global_store_dwordx4 v[26:27], v[8:11], off
	s_nop 1
	v_pk_mul_f32 v[8:9], v[12:13], v[12:13]
	v_pk_mul_f32 v[12:13], v[18:19], v[18:19]
	s_waitcnt vmcnt(1)
	v_lshlrev_b32_e32 v18, 16, v22
	v_and_b32_e32 v19, 0xffff0000, v22
	v_pk_add_f32 v[4:5], v[4:5], v[18:19]
	v_lshlrev_b32_e32 v18, 16, v23
	v_and_b32_e32 v19, 0xffff0000, v23
	v_pk_add_f32 v[6:7], v[6:7], v[18:19]
	v_lshlrev_b32_e32 v18, 16, v24
	v_and_b32_e32 v19, 0xffff0000, v24
	v_pk_add_f32 v[18:19], v[0:1], v[18:19]
	v_lshlrev_b32_e32 v0, 16, v25
	v_and_b32_e32 v1, 0xffff0000, v25
	v_pk_mul_f32 v[10:11], v[14:15], v[14:15]
	v_pk_mul_f32 v[14:15], v[20:21], v[20:21]
	v_pk_add_f32 v[20:21], v[2:3], v[0:1]
	v_cvt_pk_bf16_f32 v0, v4, v5
	v_cvt_pk_bf16_f32 v1, v6, v7
	v_cvt_pk_bf16_f32 v2, v18, v19
	v_cvt_pk_bf16_f32 v3, v20, v21
	global_store_dwordx4 v[26:27], v[0:3], off offset:256
	s_nop 1
	v_pk_mul_f32 v[0:1], v[4:5], v[4:5]
	v_pk_mul_f32 v[2:3], v[6:7], v[6:7]
	v_add_f32_e32 v0, v0, v1
	v_add_f32_e32 v2, v2, v3
	v_pk_mul_f32 v[4:5], v[18:19], v[18:19]
	v_pk_mul_f32 v[6:7], v[20:21], v[20:21]
	v_add_f32_e32 v0, v0, v2
	v_add_f32_e32 v1, v14, v15
	v_add_f32_e32 v2, v12, v13
	v_add_f32_e32 v6, v6, v7
	v_add_f32_e32 v4, v4, v5
	v_add_f32_e32 v1, v2, v1
	v_add_f32_e32 v2, v10, v11
	v_add_f32_e32 v3, v8, v9
	v_add_f32_e32 v4, v4, v6
	v_add_f32_e32 v2, v3, v2
	v_add_f32_e32 v0, v0, v4
	v_add_f32_e32 v1, v2, v1
	v_add_f32_e32 v0, v1, v0
	ds_bpermute_b32 v1, v147, v0
	s_waitcnt lgkmcnt(0)
	v_add_f32_e32 v0, v0, v1
	ds_bpermute_b32 v1, v146, v0
	s_and_saveexec_b64 s[30:31], s[40:41]
	s_cbranch_execz .LBB0_79
	v_lshlrev_b64 v[2:3], 6, v[16:17]
	v_lshl_add_u64 v[2:3], s[6:7], 0, v[2:3]
	v_lshl_add_u64 v[2:3], s[26:27], 2, v[2:3]
	s_lshl_b32 s94, s53, 2
	v_lshl_add_u64 v[2:3], v[2:3], 0, s[94:95]
	s_waitcnt lgkmcnt(0)
	v_add_f32_e32 v0, v0, v1
	global_store_dword v[2:3], v0, off

; DI unsigned pk2(float lo, float hi) { const f32x2_t v = {lo, hi}; const bf16x2_t b = __builtin_convertvector(v, bf16x2_t); return __builtin_bit_cast(unsigned, b); }
; DI float lo16(unsigned w) { return __uint_as_float(w << 16); }
; DI float hi16(unsigned w) { return __uint_as_float(w & 0xffff0000u); }
; DI void gatenorm_pass(const Args& a, int G, const int tid) {
;     ...
;     for (int m0 = gw; m0 < R; m0 += 4 * NGW) {
;         u32x4 yw[4][2], zw[4][2];
; #pragma unroll
;         for (int q = 0; q < 4; ++q) { const int m = m0 + q * NGW; if (m < R) {
; #pragma unroll
;             for (int g = 0; g < 2; ++g) { yw[q][g] = *((const u32x4*)(MIX + (size_t)m * LDMIX + 512 + g * 512) + lane); zw[q][g] = *((const u32x4*)(HIN + (size_t)m * LDH + C_Z + g * 512) + lane); } } }
; #pragma unroll
;         for (int q = 0; q < 4; ++q) { const int m = m0 + q * NGW; if (m < R) {
; #pragma unroll
;             for (int g = 0; g < 2; ++g) {
;                 float v[8]; float s = 0.f;
; #pragma unroll
;                 for (int e = 0; e < 4; ++e) { const float z0 = lo16(zw[q][g][e]), z1 = hi16(zw[q][g][e]); v[2 * e] = lo16(yw[q][g][e]) * z0 * __frcp_rn(1.0f + __expf(-z0)); v[2 * e + 1] = hi16(yw[q][g][e]) * z1 * __frcp_rn(1.0f + __expf(-z1)); s += v[2 * e] * v[2 * e] + v[2 * e + 1] * v[2 * e + 1]; }
;                 s = wave_sum(s); const float r = rsqrtf(s * (1.0f / 512.0f) + EPS);
;                 u32x4 w;
; #pragma unroll
;                 for (int e = 0; e < 4; ++e) w[e] = pk2(v[2 * e] * r, v[2 * e + 1] * r);
;                 *((u32x4*)(MIX + (size_t)m * LDMIX + 512 + g * 512) + lane) = w;
;             } } }
;     }
.LBB0_103:
	s_or_b64 exec, exec, s[4:5]
	s_waitcnt vmcnt(1)
	v_lshlrev_b32_e32 v70, 16, v63
	v_and_b32_e32 v71, 0xffff0000, v63
	v_mul_f32_e32 v63, 0xbfb8aa3b, v70
	v_lshlrev_b32_e32 v74, 16, v59
	v_and_b32_e32 v75, 0xffff0000, v59
	v_mul_f32_e32 v59, 0xbfb8aa3b, v71
	v_exp_f32_e32 v72, v63
	v_exp_f32_e32 v73, v59
	v_pk_mul_f32 v[74:75], v[74:75], v[70:71]
	v_and_b32_e32 v85, 0xffff0000, v57
	v_and_b32_e32 v87, 0xffff0000, v51
	v_pk_add_f32 v[70:71], v[72:73], 1.0 op_sel_hi:[1,0]
	v_and_b32_e32 v89, 0xffff0000, v49
	s_nop 0
	v_rcp_f32_e32 v71, v71
	s_nop 0
	v_lshlrev_b32_e32 v72, 16, v62
	v_and_b32_e32 v73, 0xffff0000, v62
	v_rcp_f32_e32 v70, v70
	v_mul_f32_e32 v59, 0xbfb8aa3b, v72
	v_mul_f32_e32 v63, 0xbfb8aa3b, v73
	v_exp_f32_e32 v62, v59
	v_exp_f32_e32 v63, v63
	v_pk_mul_f32 v[70:71], v[74:75], v[70:71]
	v_lshlrev_b32_e32 v74, 16, v58
	v_and_b32_e32 v75, 0xffff0000, v58
	v_pk_add_f32 v[62:63], v[62:63], 1.0 op_sel_hi:[1,0]
	v_pk_mul_f32 v[58:59], v[74:75], v[72:73]
	s_nop 0
	v_rcp_f32_e32 v63, v63
	s_nop 0
	v_rcp_f32_e32 v62, v62
	s_nop 0
	v_pk_mul_f32 v[58:59], v[58:59], v[62:63]
	v_mov_b32_e32 v62, v70
	v_mov_b32_e32 v63, v58
	v_pk_mul_f32 v[62:63], v[62:63], v[62:63]
	v_mov_b32_e32 v72, v71
	v_mov_b32_e32 v73, v59
	v_pk_fma_f32 v[62:63], v[72:73], v[72:73], v[62:63]
	v_lshlrev_b32_e32 v72, 16, v61
	v_and_b32_e32 v73, 0xffff0000, v61
	v_mul_f32_e32 v61, 0xbfb8aa3b, v72
	v_lshlrev_b32_e32 v84, 16, v57
	v_mul_f32_e32 v57, 0xbfb8aa3b, v73
	v_exp_f32_e32 v74, v61
	v_exp_f32_e32 v75, v57
	v_pk_mul_f32 v[84:85], v[84:85], v[72:73]
	v_pk_add_f32 v[72:73], v[74:75], 1.0 op_sel_hi:[1,0]
	s_nop 0
	s_nop 0
	v_rcp_f32_e32 v73, v73
	s_nop 0
	v_lshlrev_b32_e32 v74, 16, v60
	v_and_b32_e32 v75, 0xffff0000, v60
	v_rcp_f32_e32 v72, v72
	v_mul_f32_e32 v57, 0xbfb8aa3b, v74
	v_mul_f32_e32 v61, 0xbfb8aa3b, v75
	v_exp_f32_e32 v60, v57
	v_exp_f32_e32 v61, v61
	v_pk_mul_f32 v[72:73], v[84:85], v[72:73]
	v_lshlrev_b32_e32 v84, 16, v56
	v_and_b32_e32 v85, 0xffff0000, v56
	v_pk_add_f32 v[60:61], v[60:61], 1.0 op_sel_hi:[1,0]
	v_pk_mul_f32 v[56:57], v[84:85], v[74:75]
	s_nop 0
	v_rcp_f32_e32 v61, v61
	s_nop 0
	v_rcp_f32_e32 v60, v60
	s_nop 0
	v_pk_mul_f32 v[56:57], v[56:57], v[60:61]
	v_mov_b32_e32 v61, v72
	v_mov_b32_e32 v60, v56
	v_pk_mul_f32 v[60:61], v[60:61], v[60:61]
	v_mov_b32_e32 v74, v57
	v_mov_b32_e32 v75, v73
	v_pk_fma_f32 v[60:61], v[74:75], v[74:75], v[60:61]
	s_waitcnt vmcnt(0)
	v_lshlrev_b32_e32 v74, 16, v55
	v_and_b32_e32 v75, 0xffff0000, v55
	v_mul_f32_e32 v55, 0xbfb8aa3b, v74
	v_lshlrev_b32_e32 v86, 16, v51
	v_mul_f32_e32 v51, 0xbfb8aa3b, v75
	v_exp_f32_e32 v84, v55
	v_exp_f32_e32 v85, v51
	v_pk_mul_f32 v[86:87], v[86:87], v[74:75]
	v_pk_add_f32 v[74:75], v[84:85], 1.0 op_sel_hi:[1,0]
	s_nop 0
	s_nop 0
	v_rcp_f32_e32 v75, v75
	s_nop 0
	v_lshlrev_b32_e32 v84, 16, v54
	v_and_b32_e32 v85, 0xffff0000, v54
	v_rcp_f32_e32 v74, v74
	v_mul_f32_e32 v51, 0xbfb8aa3b, v84
	v_mul_f32_e32 v55, 0xbfb8aa3b, v85
	v_exp_f32_e32 v54, v51
	v_exp_f32_e32 v55, v55
	v_pk_mul_f32 v[74:75], v[86:87], v[74:75]
	v_lshlrev_b32_e32 v86, 16, v50
	v_and_b32_e32 v87, 0xffff0000, v50
	v_pk_add_f32 v[54:55], v[54:55], 1.0 op_sel_hi:[1,0]
	v_pk_mul_f32 v[50:51], v[86:87], v[84:85]
	s_nop 0
	v_rcp_f32_e32 v55, v55
	s_nop 0
	v_rcp_f32_e32 v54, v54
	s_nop 0
	v_pk_mul_f32 v[50:51], v[50:51], v[54:55]
	v_mov_b32_e32 v54, v74
	v_mov_b32_e32 v55, v50
	v_pk_mul_f32 v[54:55], v[54:55], v[54:55]
	v_mov_b32_e32 v84, v75
	v_mov_b32_e32 v85, v51
	v_pk_fma_f32 v[54:55], v[84:85], v[84:85], v[54:55]
	v_lshlrev_b32_e32 v84, 16, v53
	v_and_b32_e32 v85, 0xffff0000, v53
	v_mul_f32_e32 v53, 0xbfb8aa3b, v84
	v_lshlrev_b32_e32 v88, 16, v49
	v_mul_f32_e32 v49, 0xbfb8aa3b, v85
	v_exp_f32_e32 v86, v53
	v_exp_f32_e32 v87, v49
	v_pk_mul_f32 v[88:89], v[88:89], v[84:85]
	v_pk_add_f32 v[84:85], v[86:87], 1.0 op_sel_hi:[1,0]
	s_nop 0
	s_nop 0
	v_rcp_f32_e32 v85, v85
	s_nop 0
	v_lshlrev_b32_e32 v86, 16, v52
	v_and_b32_e32 v87, 0xffff0000, v52
	v_rcp_f32_e32 v84, v84
	v_mul_f32_e32 v49, 0xbfb8aa3b, v86
	v_mul_f32_e32 v53, 0xbfb8aa3b, v87
	v_exp_f32_e32 v52, v49
	v_exp_f32_e32 v53, v53
	v_pk_mul_f32 v[84:85], v[88:89], v[84:85]
	v_lshlrev_b32_e32 v88, 16, v48
	v_and_b32_e32 v89, 0xffff0000, v48
	v_pk_add_f32 v[52:53], v[52:53], 1.0 op_sel_hi:[1,0]
	v_pk_mul_f32 v[48:49], v[88:89], v[86:87]
	s_nop 0
	v_rcp_f32_e32 v53, v53
	v_div_scale_f32 v86, s[4:5], v52, v52, 1.0
	v_rcp_f32_e32 v87, v86
	s_mov_b32 s4, 0x3b000000
	v_fma_f32 v88, -v86, v87, 1.0
	v_fmac_f32_e32 v87, v88, v87
	v_div_scale_f32 v88, vcc, 1.0, v52, 1.0
	v_mul_f32_e32 v89, v88, v87
	v_fma_f32 v90, -v86, v89, v88
	v_fmac_f32_e32 v89, v90, v87
	v_fma_f32 v86, -v86, v89, v88
	v_div_fmas_f32 v86, v86, v87, v89
	v_div_fixup_f32 v52, v86, v52, 1.0
	v_pk_mul_f32 v[48:49], v[48:49], v[52:53]
	v_mov_b32_e32 v53, v84
	v_mov_b32_e32 v52, v48
	v_pk_mul_f32 v[52:53], v[52:53], v[52:53]
	v_mov_b32_e32 v86, v49
	v_mov_b32_e32 v87, v85
	v_pk_fma_f32 v[52:53], v[86:87], v[86:87], v[52:53]
	v_mov_b32_e32 v87, v60
	v_mov_b32_e32 v86, v52
	v_mov_b32_e32 v60, v53
	v_pk_add_f32 v[52:53], v[86:87], v[60:61]
	v_mov_b32_e32 v60, v55
	v_mov_b32_e32 v61, v63
	v_pk_add_f32 v[52:53], v[60:61], v[52:53]
	v_mov_b32_e32 v55, v62
	v_pk_add_f32 v[52:53], v[54:55], v[52:53]
	ds_bpermute_b32 v55, v65, v53
	ds_bpermute_b32 v54, v65, v52
	s_waitcnt lgkmcnt(0)
	v_pk_add_f32 v[52:53], v[52:53], v[54:55]
	ds_bpermute_b32 v55, v76, v53
	ds_bpermute_b32 v54, v76, v52
	s_waitcnt lgkmcnt(0)
	v_pk_add_f32 v[52:53], v[52:53], v[54:55]
	ds_bpermute_b32 v55, v77, v53
	ds_bpermute_b32 v54, v77, v52
	s_waitcnt lgkmcnt(0)
	v_pk_add_f32 v[52:53], v[52:53], v[54:55]
	ds_bpermute_b32 v55, v78, v53
	ds_bpermute_b32 v54, v78, v52
	s_waitcnt lgkmcnt(0)
; DI unsigned pk2(float lo, float hi) { const f32x2_t v = {lo, hi}; const bf16x2_t b = __builtin_convertvector(v, bf16x2_t); return __builtin_bit_cast(unsigned, b); }
; DI float lo16(unsigned w) { return __uint_as_float(w << 16); }
; DI float hi16(unsigned w) { return __uint_as_float(w & 0xffff0000u); }
; DI void gatenorm_pass(const Args& a, int G, const int tid) {
;     ...
;     for (int m0 = gw; m0 < R; m0 += 4 * NGW) {
;         u32x4 yw[4][2], zw[4][2];
; #pragma unroll
;         for (int q = 0; q < 4; ++q) { const int m = m0 + q * NGW; if (m < R) {
; #pragma unroll
;             for (int g = 0; g < 2; ++g) { yw[q][g] = *((const u32x4*)(MIX + (size_t)m * LDMIX + 512 + g * 512) + lane); zw[q][g] = *((const u32x4*)(HIN + (size_t)m * LDH + C_Z + g * 512) + lane); } } }
; #pragma unroll
;         for (int q = 0; q < 4; ++q) { const int m = m0 + q * NGW; if (m < R) {
; #pragma unroll
;             for (int g = 0; g < 2; ++g) {
;                 float v[8]; float s = 0.f;
; #pragma unroll
;                 for (int e = 0; e < 4; ++e) { const float z0 = lo16(zw[q][g][e]), z1 = hi16(zw[q][g][e]); v[2 * e] = lo16(yw[q][g][e]) * z0 * __frcp_rn(1.0f + __expf(-z0)); v[2 * e + 1] = hi16(yw[q][g][e]) * z1 * __frcp_rn(1.0f + __expf(-z1)); s += v[2 * e] * v[2 * e] + v[2 * e + 1] * v[2 * e + 1]; }
;                 s = wave_sum(s); const float r = rsqrtf(s * (1.0f / 512.0f) + EPS);
;                 u32x4 w;
; #pragma unroll
;                 for (int e = 0; e < 4; ++e) w[e] = pk2(v[2 * e] * r, v[2 * e + 1] * r);
;                 *((u32x4*)(MIX + (size_t)m * LDMIX + 512 + g * 512) + lane) = w;
;             } } }
;     }
	v_pk_add_f32 v[52:53], v[52:53], v[54:55]
	ds_bpermute_b32 v55, v79, v53
	ds_bpermute_b32 v54, v79, v52
	s_waitcnt lgkmcnt(0)
	v_pk_add_f32 v[52:53], v[52:53], v[54:55]
	ds_bpermute_b32 v55, v80, v53
	ds_bpermute_b32 v54, v80, v52
	s_waitcnt lgkmcnt(0)
	v_pk_add_f32 v[52:53], v[52:53], v[54:55]
	s_nop 0
	v_pk_fma_f32 v[60:61], v[52:53], s[4:5], v[176:177] op_sel_hi:[1,0,0]
	s_nop 0
	v_mul_f32_e32 v52, 0x4b800000, v61
	v_cmp_gt_f32_e64 s[46:47], s39, v61
	v_cmp_gt_f32_e32 vcc, s39, v60
	s_nop 0
	v_cndmask_b32_e64 v52, v61, v52, s[46:47]
	v_rsq_f32_e32 v52, v52
	s_nop 0
	v_mul_f32_e32 v53, 0x45800000, v52
	v_cndmask_b32_e64 v62, v52, v53, s[46:47]
	v_pk_mul_f32 v[52:53], v[56:57], v[62:63] op_sel_hi:[1,0]
	v_pk_mul_f32 v[54:55], v[72:73], v[62:63] op_sel_hi:[1,0]
	v_cvt_pk_bf16_f32 v52, v52, v53
	v_cvt_pk_bf16_f32 v53, v54, v55
	v_pk_mul_f32 v[54:55], v[58:59], v[62:63] op_sel_hi:[1,0]
	v_pk_mul_f32 v[56:57], v[70:71], v[62:63] op_sel_hi:[1,0]
	v_cvt_pk_bf16_f32 v54, v54, v55
	v_cvt_pk_bf16_f32 v55, v56, v57
	global_store_dwordx4 v[68:69], v[52:55], off offset:1024
	s_nop 1
	v_mul_f32_e32 v52, 0x4b800000, v60
	v_cndmask_b32_e32 v52, v60, v52, vcc
	v_rsq_f32_e32 v52, v52
	s_nop 0
	v_mul_f32_e32 v53, 0x45800000, v52
	v_cndmask_b32_e32 v52, v52, v53, vcc
	v_pk_mul_f32 v[48:49], v[48:49], v[52:53] op_sel_hi:[1,0]
	v_pk_mul_f32 v[54:55], v[84:85], v[52:53] op_sel_hi:[1,0]
	v_pk_mul_f32 v[50:51], v[50:51], v[52:53] op_sel_hi:[1,0]
	v_pk_mul_f32 v[52:53], v[74:75], v[52:53] op_sel_hi:[1,0]
	v_cvt_pk_bf16_f32 v48, v48, v49
	v_cvt_pk_bf16_f32 v49, v54, v55
	v_cvt_pk_bf16_f32 v50, v50, v51
	v_cvt_pk_bf16_f32 v51, v52, v53
	global_store_dwordx4 v[68:69], v[48:51], off offset:2048
	s_and_saveexec_b64 s[4:5], s[44:45]
	s_cbranch_execz .LBB0_106
	v_lshlrev_b32_e32 v48, 16, v39
	v_and_b32_e32 v49, 0xffff0000, v39
	v_mul_f32_e32 v50, 0xbfb8aa3b, v48
	v_mul_f32_e32 v51, 0xbfb8aa3b, v49
	v_exp_f32_e32 v50, v50
	v_exp_f32_e32 v51, v51
	v_lshlrev_b32_e32 v52, 16, v7
	v_and_b32_e32 v53, 0xffff0000, v7
	v_pk_mul_f32 v[48:49], v[52:53], v[48:49]
	v_pk_add_f32 v[50:51], v[50:51], 1.0 op_sel_hi:[1,0]
	s_nop 0
	s_nop 0
	v_rcp_f32_e32 v51, v51
	v_lshlrev_b32_e32 v52, 16, v38
	v_and_b32_e32 v53, 0xffff0000, v38
	v_mul_f32_e32 v54, 0xbfb8aa3b, v52
	v_mul_f32_e32 v55, 0xbfb8aa3b, v53
	v_exp_f32_e32 v54, v54
	v_exp_f32_e32 v55, v55
	v_rcp_f32_e32 v50, v50
	s_nop 0
	v_pk_mul_f32 v[48:49], v[48:49], v[50:51]
	v_pk_add_f32 v[50:51], v[54:55], 1.0 op_sel_hi:[1,0]
	v_lshlrev_b32_e32 v54, 16, v6
	v_and_b32_e32 v55, 0xffff0000, v6
	v_pk_mul_f32 v[52:53], v[54:55], v[52:53]
	v_rcp_f32_e32 v51, v51
	v_rcp_f32_e32 v50, v50
	v_lshlrev_b32_e32 v54, 16, v37
	v_and_b32_e32 v55, 0xffff0000, v37
	v_mul_f32_e32 v56, 0xbfb8aa3b, v54
	v_mul_f32_e32 v57, 0xbfb8aa3b, v55
	v_exp_f32_e32 v56, v56
	v_exp_f32_e32 v57, v57
	v_pk_mul_f32 v[50:51], v[52:53], v[50:51]
	v_mov_b32_e32 v52, v48
	v_mov_b32_e32 v53, v50
	v_pk_add_f32 v[56:57], v[56:57], 1.0 op_sel_hi:[1,0]
	v_pk_mul_f32 v[52:53], v[52:53], v[52:53]
	v_mov_b32_e32 v58, v49
	v_mov_b32_e32 v59, v51
	v_pk_fma_f32 v[52:53], v[58:59], v[58:59], v[52:53]
	v_lshlrev_b32_e32 v58, 16, v5
	v_and_b32_e32 v59, 0xffff0000, v5
	v_pk_mul_f32 v[54:55], v[58:59], v[54:55]
	v_rcp_f32_e32 v57, v57
	v_lshlrev_b32_e32 v58, 16, v36
	v_and_b32_e32 v59, 0xffff0000, v36
	v_mul_f32_e32 v60, 0xbfb8aa3b, v58
	v_mul_f32_e32 v61, 0xbfb8aa3b, v59
	v_exp_f32_e32 v60, v60
	v_exp_f32_e32 v61, v61
	v_rcp_f32_e32 v56, v56
	s_nop 0
	v_pk_mul_f32 v[54:55], v[54:55], v[56:57]
	v_pk_add_f32 v[56:57], v[60:61], 1.0 op_sel_hi:[1,0]
	v_lshlrev_b32_e32 v60, 16, v4
	v_and_b32_e32 v61, 0xffff0000, v4
	v_pk_mul_f32 v[58:59], v[60:61], v[58:59]
	v_mov_b32_e32 v69, v55
	v_rcp_f32_e32 v57, v57
	v_rcp_f32_e32 v56, v56
	v_lshlrev_b32_e32 v60, 16, v35
	v_and_b32_e32 v61, 0xffff0000, v35
	v_mul_f32_e32 v62, 0xbfb8aa3b, v60
	v_mul_f32_e32 v63, 0xbfb8aa3b, v61
	v_exp_f32_e32 v62, v62
	v_exp_f32_e32 v63, v63
	v_pk_mul_f32 v[56:57], v[58:59], v[56:57]
	v_mov_b32_e32 v59, v54
	v_mov_b32_e32 v58, v56
	v_pk_mul_f32 v[58:59], v[58:59], v[58:59]
	v_mov_b32_e32 v68, v57
	v_pk_fma_f32 v[68:69], v[68:69], v[68:69], v[58:59]
	v_pk_add_f32 v[58:59], v[62:63], 1.0 op_sel_hi:[1,0]
	v_lshlrev_b32_e32 v62, 16, v19
	v_and_b32_e32 v63, 0xffff0000, v19
	v_pk_mul_f32 v[60:61], v[62:63], v[60:61]
	v_rcp_f32_e32 v59, v59
	v_lshlrev_b32_e32 v62, 16, v34
	v_and_b32_e32 v63, 0xffff0000, v34
	v_mul_f32_e32 v70, 0xbfb8aa3b, v62
	v_mul_f32_e32 v71, 0xbfb8aa3b, v63
	v_exp_f32_e32 v70, v70
	v_exp_f32_e32 v71, v71
	v_rcp_f32_e32 v58, v58
	s_nop 0
	v_pk_mul_f32 v[58:59], v[60:61], v[58:59]
	v_pk_add_f32 v[60:61], v[70:71], 1.0 op_sel_hi:[1,0]
	v_lshlrev_b32_e32 v70, 16, v18
	v_and_b32_e32 v71, 0xffff0000, v18
	v_pk_mul_f32 v[62:63], v[70:71], v[62:63]
	v_rcp_f32_e32 v61, v61
	v_rcp_f32_e32 v60, v60
	v_lshlrev_b32_e32 v70, 16, v33
	v_and_b32_e32 v71, 0xffff0000, v33
	v_mul_f32_e32 v72, 0xbfb8aa3b, v70
	v_mul_f32_e32 v73, 0xbfb8aa3b, v71
	v_exp_f32_e32 v72, v72
	v_exp_f32_e32 v73, v73
	v_pk_mul_f32 v[60:61], v[62:63], v[60:61]
	v_mov_b32_e32 v62, v58
	v_mov_b32_e32 v63, v60
	v_pk_add_f32 v[72:73], v[72:73], 1.0 op_sel_hi:[1,0]
	v_pk_mul_f32 v[62:63], v[62:63], v[62:63]
	v_mov_b32_e32 v74, v59
	v_mov_b32_e32 v75, v61
	v_pk_fma_f32 v[62:63], v[74:75], v[74:75], v[62:63]
	v_lshlrev_b32_e32 v74, 16, v17
	v_and_b32_e32 v75, 0xffff0000, v17
	v_pk_mul_f32 v[70:71], v[74:75], v[70:71]
	v_rcp_f32_e32 v73, v73
	v_lshlrev_b32_e32 v74, 16, v32
	v_and_b32_e32 v75, 0xffff0000, v32
	v_mul_f32_e32 v84, 0xbfb8aa3b, v74
	v_mul_f32_e32 v85, 0xbfb8aa3b, v75
	v_exp_f32_e32 v84, v84
	v_exp_f32_e32 v85, v85
	v_rcp_f32_e32 v72, v72
	s_nop 0
	v_pk_mul_f32 v[70:71], v[70:71], v[72:73]
	v_pk_add_f32 v[72:73], v[84:85], 1.0 op_sel_hi:[1,0]
	v_lshlrev_b32_e32 v84, 16, v16
	v_and_b32_e32 v85, 0xffff0000, v16
	v_pk_mul_f32 v[74:75], v[84:85], v[74:75]
	v_div_scale_f32 v86, s[6:7], v72, v72, 1.0
	v_rcp_f32_e32 v88, v86
	v_rcp_f32_e32 v73, v73
	s_mov_b32 s6, 0x3b000000
	v_fma_f32 v84, -v86, v88, 1.0
	v_fmac_f32_e32 v88, v84, v88
	v_div_scale_f32 v84, vcc, 1.0, v72, 1.0
	v_mul_f32_e32 v85, v84, v88
	v_fma_f32 v87, -v86, v85, v84
	v_fmac_f32_e32 v85, v87, v88
	v_fma_f32 v84, -v86, v85, v84
	v_div_fmas_f32 v84, v84, v88, v85
	v_div_fixup_f32 v72, v84, v72, 1.0
	v_pk_mul_f32 v[72:73], v[74:75], v[72:73]
	v_mov_b32_e32 v75, v70
	v_mov_b32_e32 v74, v72
	v_pk_mul_f32 v[74:75], v[74:75], v[74:75]
	v_mov_b32_e32 v84, v73
	v_mov_b32_e32 v85, v71
	v_pk_fma_f32 v[74:75], v[84:85], v[84:85], v[74:75]
	v_mov_b32_e32 v85, v68
	v_mov_b32_e32 v84, v74
	v_mov_b32_e32 v68, v75
	v_pk_add_f32 v[68:69], v[84:85], v[68:69]
	v_mov_b32_e32 v74, v63
	v_mov_b32_e32 v75, v53
	v_pk_add_f32 v[68:69], v[74:75], v[68:69]
	v_mov_b32_e32 v63, v52
	v_pk_add_f32 v[52:53], v[62:63], v[68:69]
	ds_bpermute_b32 v63, v65, v53
	ds_bpermute_b32 v62, v65, v52
	s_waitcnt lgkmcnt(0)
; DI unsigned pk2(float lo, float hi) { const f32x2_t v = {lo, hi}; const bf16x2_t b = __builtin_convertvector(v, bf16x2_t); return __builtin_bit_cast(unsigned, b); }
; DI float lo16(unsigned w) { return __uint_as_float(w << 16); }
; DI float hi16(unsigned w) { return __uint_as_float(w & 0xffff0000u); }
; DI void gatenorm_pass(const Args& a, int G, const int tid) {
;     ...
;                 for (int e = 0; e < 4; ++e) { const float z0 = lo16(zw[q][g][e]), z1 = hi16(zw[q][g][e]); v[2 * e] = lo16(yw[q][g][e]) * z0 * __frcp_rn(1.0f + __expf(-z0)); v[2 * e + 1] = hi16(yw[q][g][e]) * z1 * __frcp_rn(1.0f + __expf(-z1)); s += v[2 * e] * v[2 * e] + v[2 * e + 1] * v[2 * e + 1]; }
;                 s = wave_sum(s); const float r = rsqrtf(s * (1.0f / 512.0f) + EPS);
;                 u32x4 w;
; #pragma unroll
;                 for (int e = 0; e < 4; ++e) w[e] = pk2(v[2 * e] * r, v[2 * e + 1] * r);
;                 *((u32x4*)(MIX + (size_t)m * LDMIX + 512 + g * 512) + lane) = w;
	v_pk_add_f32 v[52:53], v[52:53], v[62:63]
	ds_bpermute_b32 v63, v76, v53
	ds_bpermute_b32 v62, v76, v52
	s_waitcnt lgkmcnt(0)
	v_pk_add_f32 v[52:53], v[52:53], v[62:63]
	ds_bpermute_b32 v63, v77, v53
	ds_bpermute_b32 v62, v77, v52
	s_waitcnt lgkmcnt(0)
	v_pk_add_f32 v[52:53], v[52:53], v[62:63]
	ds_bpermute_b32 v63, v78, v53
	ds_bpermute_b32 v62, v78, v52
	s_waitcnt lgkmcnt(0)
	v_pk_add_f32 v[52:53], v[52:53], v[62:63]
	ds_bpermute_b32 v63, v79, v53
	ds_bpermute_b32 v62, v79, v52
	s_waitcnt lgkmcnt(0)
	v_pk_add_f32 v[52:53], v[52:53], v[62:63]
	ds_bpermute_b32 v63, v80, v53
	ds_bpermute_b32 v62, v80, v52
	s_waitcnt lgkmcnt(0)
	v_pk_add_f32 v[52:53], v[52:53], v[62:63]
	s_nop 0
	v_pk_fma_f32 v[62:63], v[52:53], s[6:7], v[176:177] op_sel_hi:[1,0,0]
	v_mad_i64_i32 v[68:69], s[6:7], v81, s27, v[66:67]
	v_mul_f32_e32 v52, 0x4b800000, v63
	v_cmp_gt_f32_e32 vcc, s39, v63
	s_nop 1
	v_cndmask_b32_e32 v52, v63, v52, vcc
	v_rsq_f32_e32 v52, v52
	s_nop 0
	v_mul_f32_e32 v53, 0x45800000, v52
	v_cndmask_b32_e32 v74, v52, v53, vcc
	v_pk_mul_f32 v[52:53], v[56:57], v[74:75] op_sel_hi:[1,0]
	v_pk_mul_f32 v[54:55], v[54:55], v[74:75] op_sel_hi:[1,0]
	v_pk_mul_f32 v[50:51], v[50:51], v[74:75] op_sel_hi:[1,0]
	v_cvt_pk_bf16_f32 v52, v52, v53
	v_cvt_pk_bf16_f32 v53, v54, v55
	v_cvt_pk_bf16_f32 v54, v50, v51
	v_mul_f32_e32 v50, 0x4b800000, v62
	v_cmp_gt_f32_e32 vcc, s39, v62
	v_pk_mul_f32 v[48:49], v[48:49], v[74:75] op_sel_hi:[1,0]
	s_nop 0
	v_cndmask_b32_e32 v50, v62, v50, vcc
	v_rsq_f32_e32 v50, v50
	v_cvt_pk_bf16_f32 v55, v48, v49
	global_store_dwordx4 v[68:69], v[52:55], off offset:1024
	v_mul_f32_e32 v48, 0x45800000, v50
	s_nop 0
	v_cndmask_b32_e32 v52, v50, v48, vcc
	v_pk_mul_f32 v[48:49], v[72:73], v[52:53] op_sel_hi:[1,0]
	v_pk_mul_f32 v[50:51], v[70:71], v[52:53] op_sel_hi:[1,0]
	v_cvt_pk_bf16_f32 v48, v48, v49
	v_cvt_pk_bf16_f32 v49, v50, v51
	v_pk_mul_f32 v[50:51], v[60:61], v[52:53] op_sel_hi:[1,0]
	v_pk_mul_f32 v[52:53], v[58:59], v[52:53] op_sel_hi:[1,0]
	v_cvt_pk_bf16_f32 v50, v50, v51
	v_cvt_pk_bf16_f32 v51, v52, v53
	global_store_dwordx4 v[68:69], v[48:51], off offset:2048
	s_or_b64 exec, exec, s[4:5]
	s_and_saveexec_b64 s[4:5], s[42:43]
	s_cbranch_execnz .LBB0_107

; DI unsigned pk2(float lo, float hi) { const f32x2_t v = {lo, hi}; const bf16x2_t b = __builtin_convertvector(v, bf16x2_t); return __builtin_bit_cast(unsigned, b); }
; DI float lo16(unsigned w) { return __uint_as_float(w << 16); }
; DI float hi16(unsigned w) { return __uint_as_float(w & 0xffff0000u); }
; DI void gatenorm_pass(const Args& a, int G, const int tid) {
;     ...
;     for (int m0 = gw; m0 < R; m0 += 4 * NGW) {
;         u32x4 yw[4][2], zw[4][2];
; #pragma unroll
;         for (int q = 0; q < 4; ++q) { const int m = m0 + q * NGW; if (m < R) {
; #pragma unroll
;             for (int g = 0; g < 2; ++g) { yw[q][g] = *((const u32x4*)(MIX + (size_t)m * LDMIX + 512 + g * 512) + lane); zw[q][g] = *((const u32x4*)(HIN + (size_t)m * LDH + C_Z + g * 512) + lane); } } }
; #pragma unroll
;         for (int q = 0; q < 4; ++q) { const int m = m0 + q * NGW; if (m < R) {
; #pragma unroll
;             for (int g = 0; g < 2; ++g) {
;                 float v[8]; float s = 0.f;
; #pragma unroll
;                 for (int e = 0; e < 4; ++e) { const float z0 = lo16(zw[q][g][e]), z1 = hi16(zw[q][g][e]); v[2 * e] = lo16(yw[q][g][e]) * z0 * __frcp_rn(1.0f + __expf(-z0)); v[2 * e + 1] = hi16(yw[q][g][e]) * z1 * __frcp_rn(1.0f + __expf(-z1)); s += v[2 * e] * v[2 * e] + v[2 * e + 1] * v[2 * e + 1]; }
;                 s = wave_sum(s); const float r = rsqrtf(s * (1.0f / 512.0f) + EPS);
;                 u32x4 w;
; #pragma unroll
;                 for (int e = 0; e < 4; ++e) w[e] = pk2(v[2 * e] * r, v[2 * e + 1] * r);
;                 *((u32x4*)(MIX + (size_t)m * LDMIX + 512 + g * 512) + lane) = w;
;             } } }
;     }
.LBB0_107:
	v_lshlrev_b32_e32 v48, 16, v47
	v_and_b32_e32 v49, 0xffff0000, v47
	v_mul_f32_e32 v50, 0xbfb8aa3b, v48
	v_mul_f32_e32 v51, 0xbfb8aa3b, v49
	v_exp_f32_e32 v50, v50
	v_exp_f32_e32 v51, v51
	v_lshlrev_b32_e32 v52, 16, v11
	v_and_b32_e32 v53, 0xffff0000, v11
	v_pk_mul_f32 v[48:49], v[52:53], v[48:49]
	v_pk_add_f32 v[50:51], v[50:51], 1.0 op_sel_hi:[1,0]
	s_nop 0
	s_nop 0
	v_rcp_f32_e32 v51, v51
	v_lshlrev_b32_e32 v52, 16, v46
	v_and_b32_e32 v53, 0xffff0000, v46
	v_mul_f32_e32 v54, 0xbfb8aa3b, v52
	v_mul_f32_e32 v55, 0xbfb8aa3b, v53
	v_exp_f32_e32 v54, v54
	v_exp_f32_e32 v55, v55
	v_rcp_f32_e32 v50, v50
	s_nop 0
	v_pk_mul_f32 v[48:49], v[48:49], v[50:51]
	v_pk_add_f32 v[50:51], v[54:55], 1.0 op_sel_hi:[1,0]
	v_lshlrev_b32_e32 v54, 16, v10
	v_and_b32_e32 v55, 0xffff0000, v10
	v_pk_mul_f32 v[52:53], v[54:55], v[52:53]
	v_rcp_f32_e32 v51, v51
	v_rcp_f32_e32 v50, v50
	v_lshlrev_b32_e32 v54, 16, v45
	v_and_b32_e32 v55, 0xffff0000, v45
	v_mul_f32_e32 v56, 0xbfb8aa3b, v54
	v_mul_f32_e32 v57, 0xbfb8aa3b, v55
	v_exp_f32_e32 v56, v56
	v_exp_f32_e32 v57, v57
	v_pk_mul_f32 v[50:51], v[52:53], v[50:51]
	v_mov_b32_e32 v52, v48
	v_mov_b32_e32 v53, v50
	v_pk_add_f32 v[56:57], v[56:57], 1.0 op_sel_hi:[1,0]
	v_pk_mul_f32 v[52:53], v[52:53], v[52:53]
	v_mov_b32_e32 v58, v49
	v_mov_b32_e32 v59, v51
	v_pk_fma_f32 v[52:53], v[58:59], v[58:59], v[52:53]
	v_lshlrev_b32_e32 v58, 16, v9
	v_and_b32_e32 v59, 0xffff0000, v9
	v_pk_mul_f32 v[54:55], v[58:59], v[54:55]
	v_rcp_f32_e32 v57, v57
	v_lshlrev_b32_e32 v58, 16, v44
	v_and_b32_e32 v59, 0xffff0000, v44
	v_mul_f32_e32 v60, 0xbfb8aa3b, v58
	v_mul_f32_e32 v61, 0xbfb8aa3b, v59
	v_exp_f32_e32 v60, v60
	v_exp_f32_e32 v61, v61
	v_rcp_f32_e32 v56, v56
	s_nop 0
	v_pk_mul_f32 v[54:55], v[54:55], v[56:57]
	v_pk_add_f32 v[56:57], v[60:61], 1.0 op_sel_hi:[1,0]
	v_lshlrev_b32_e32 v60, 16, v8
	v_and_b32_e32 v61, 0xffff0000, v8
	v_pk_mul_f32 v[58:59], v[60:61], v[58:59]
	v_mov_b32_e32 v69, v55
	v_rcp_f32_e32 v57, v57
	v_rcp_f32_e32 v56, v56
	v_lshlrev_b32_e32 v60, 16, v43
	v_and_b32_e32 v61, 0xffff0000, v43
	v_mul_f32_e32 v62, 0xbfb8aa3b, v60
	v_mul_f32_e32 v63, 0xbfb8aa3b, v61
	v_exp_f32_e32 v62, v62
	v_exp_f32_e32 v63, v63
	v_pk_mul_f32 v[56:57], v[58:59], v[56:57]
	v_mov_b32_e32 v59, v54
	v_mov_b32_e32 v58, v56
	v_pk_mul_f32 v[58:59], v[58:59], v[58:59]
	v_mov_b32_e32 v68, v57
	v_pk_fma_f32 v[68:69], v[68:69], v[68:69], v[58:59]
	v_pk_add_f32 v[58:59], v[62:63], 1.0 op_sel_hi:[1,0]
	v_lshlrev_b32_e32 v62, 16, v23
	v_and_b32_e32 v63, 0xffff0000, v23
	v_pk_mul_f32 v[60:61], v[62:63], v[60:61]
	v_rcp_f32_e32 v59, v59
	v_lshlrev_b32_e32 v62, 16, v42
	v_and_b32_e32 v63, 0xffff0000, v42
	v_mul_f32_e32 v70, 0xbfb8aa3b, v62
	v_mul_f32_e32 v71, 0xbfb8aa3b, v63
	v_exp_f32_e32 v70, v70
	v_exp_f32_e32 v71, v71
	v_rcp_f32_e32 v58, v58
	s_nop 0
	v_pk_mul_f32 v[58:59], v[60:61], v[58:59]
	v_pk_add_f32 v[60:61], v[70:71], 1.0 op_sel_hi:[1,0]
	v_lshlrev_b32_e32 v70, 16, v22
	v_and_b32_e32 v71, 0xffff0000, v22
	v_pk_mul_f32 v[62:63], v[70:71], v[62:63]
	v_rcp_f32_e32 v61, v61
	v_rcp_f32_e32 v60, v60
	v_lshlrev_b32_e32 v70, 16, v41
	v_and_b32_e32 v71, 0xffff0000, v41
	v_mul_f32_e32 v72, 0xbfb8aa3b, v70
	v_mul_f32_e32 v73, 0xbfb8aa3b, v71
	v_exp_f32_e32 v72, v72
	v_exp_f32_e32 v73, v73
	v_pk_mul_f32 v[60:61], v[62:63], v[60:61]
	v_mov_b32_e32 v62, v58
	v_mov_b32_e32 v63, v60
	v_pk_add_f32 v[72:73], v[72:73], 1.0 op_sel_hi:[1,0]
	v_pk_mul_f32 v[62:63], v[62:63], v[62:63]
	v_mov_b32_e32 v74, v59
	v_mov_b32_e32 v75, v61
	v_pk_fma_f32 v[62:63], v[74:75], v[74:75], v[62:63]
	v_lshlrev_b32_e32 v74, 16, v21
	v_and_b32_e32 v75, 0xffff0000, v21
	v_pk_mul_f32 v[70:71], v[74:75], v[70:71]
	v_rcp_f32_e32 v73, v73
	v_lshlrev_b32_e32 v74, 16, v40
	v_and_b32_e32 v75, 0xffff0000, v40
	v_mul_f32_e32 v84, 0xbfb8aa3b, v74
	v_mul_f32_e32 v85, 0xbfb8aa3b, v75
	v_exp_f32_e32 v84, v84
	v_exp_f32_e32 v85, v85
	v_rcp_f32_e32 v72, v72
	s_nop 0
	v_pk_mul_f32 v[70:71], v[70:71], v[72:73]
	v_pk_add_f32 v[72:73], v[84:85], 1.0 op_sel_hi:[1,0]
	v_lshlrev_b32_e32 v84, 16, v20
	v_and_b32_e32 v85, 0xffff0000, v20
	v_pk_mul_f32 v[74:75], v[84:85], v[74:75]
	v_div_scale_f32 v86, s[6:7], v72, v72, 1.0
	v_rcp_f32_e32 v88, v86
	v_rcp_f32_e32 v73, v73
	s_mov_b32 s6, 0x3b000000
	v_fma_f32 v84, -v86, v88, 1.0
	v_fmac_f32_e32 v88, v84, v88
	v_div_scale_f32 v84, vcc, 1.0, v72, 1.0
	v_mul_f32_e32 v85, v84, v88
	v_fma_f32 v87, -v86, v85, v84
	v_fmac_f32_e32 v85, v87, v88
	v_fma_f32 v84, -v86, v85, v84
	v_div_fmas_f32 v84, v84, v88, v85
	v_div_fixup_f32 v72, v84, v72, 1.0
	v_pk_mul_f32 v[72:73], v[74:75], v[72:73]
	v_mov_b32_e32 v75, v70
	v_mov_b32_e32 v74, v72
	v_pk_mul_f32 v[74:75], v[74:75], v[74:75]
	v_mov_b32_e32 v84, v73
	v_mov_b32_e32 v85, v71
	v_pk_fma_f32 v[74:75], v[84:85], v[84:85], v[74:75]
	v_mov_b32_e32 v85, v68
	v_mov_b32_e32 v84, v74
	v_mov_b32_e32 v68, v75
	v_pk_add_f32 v[68:69], v[84:85], v[68:69]
	v_mov_b32_e32 v74, v63
	v_mov_b32_e32 v75, v53
	v_pk_add_f32 v[68:69], v[74:75], v[68:69]
	v_mov_b32_e32 v63, v52
	v_pk_add_f32 v[52:53], v[62:63], v[68:69]
	ds_bpermute_b32 v63, v65, v53
	ds_bpermute_b32 v62, v65, v52
	s_waitcnt lgkmcnt(0)
	v_pk_add_f32 v[52:53], v[52:53], v[62:63]
	ds_bpermute_b32 v63, v76, v53
	ds_bpermute_b32 v62, v76, v52
	s_waitcnt lgkmcnt(0)
	v_pk_add_f32 v[52:53], v[52:53], v[62:63]
	ds_bpermute_b32 v63, v77, v53
	ds_bpermute_b32 v62, v77, v52
	s_waitcnt lgkmcnt(0)
	v_pk_add_f32 v[52:53], v[52:53], v[62:63]
	ds_bpermute_b32 v63, v78, v53
	ds_bpermute_b32 v62, v78, v52
	s_waitcnt lgkmcnt(0)
	v_pk_add_f32 v[52:53], v[52:53], v[62:63]
	ds_bpermute_b32 v63, v79, v53
	ds_bpermute_b32 v62, v79, v52
	s_waitcnt lgkmcnt(0)
; DI unsigned pk2(float lo, float hi) { const f32x2_t v = {lo, hi}; const bf16x2_t b = __builtin_convertvector(v, bf16x2_t); return __builtin_bit_cast(unsigned, b); }
; DI float lo16(unsigned w) { return __uint_as_float(w << 16); }
; DI float hi16(unsigned w) { return __uint_as_float(w & 0xffff0000u); }
; DI void gatenorm_pass(const Args& a, int G, const int tid) {
;     ...
;     for (int m0 = gw; m0 < R; m0 += 4 * NGW) {
;         u32x4 yw[4][2], zw[4][2];
; #pragma unroll
;         for (int q = 0; q < 4; ++q) { const int m = m0 + q * NGW; if (m < R) {
; #pragma unroll
;             for (int g = 0; g < 2; ++g) { yw[q][g] = *((const u32x4*)(MIX + (size_t)m * LDMIX + 512 + g * 512) + lane); zw[q][g] = *((const u32x4*)(HIN + (size_t)m * LDH + C_Z + g * 512) + lane); } } }
; #pragma unroll
;         for (int q = 0; q < 4; ++q) { const int m = m0 + q * NGW; if (m < R) {
; #pragma unroll
;             for (int g = 0; g < 2; ++g) {
;                 float v[8]; float s = 0.f;
; #pragma unroll
;                 for (int e = 0; e < 4; ++e) { const float z0 = lo16(zw[q][g][e]), z1 = hi16(zw[q][g][e]); v[2 * e] = lo16(yw[q][g][e]) * z0 * __frcp_rn(1.0f + __expf(-z0)); v[2 * e + 1] = hi16(yw[q][g][e]) * z1 * __frcp_rn(1.0f + __expf(-z1)); s += v[2 * e] * v[2 * e] + v[2 * e + 1] * v[2 * e + 1]; }
;                 s = wave_sum(s); const float r = rsqrtf(s * (1.0f / 512.0f) + EPS);
;                 u32x4 w;
; #pragma unroll
;                 for (int e = 0; e < 4; ++e) w[e] = pk2(v[2 * e] * r, v[2 * e + 1] * r);
;                 *((u32x4*)(MIX + (size_t)m * LDMIX + 512 + g * 512) + lane) = w;
;             } } }
;     }
	v_pk_add_f32 v[52:53], v[52:53], v[62:63]
	ds_bpermute_b32 v63, v80, v53
	ds_bpermute_b32 v62, v80, v52
	s_waitcnt lgkmcnt(0)
	v_pk_add_f32 v[52:53], v[52:53], v[62:63]
	s_nop 0
	v_pk_fma_f32 v[62:63], v[52:53], s[6:7], v[176:177] op_sel_hi:[1,0,0]
	v_mad_i64_i32 v[68:69], s[6:7], v83, s27, v[66:67]
	v_mul_f32_e32 v52, 0x4b800000, v63
	v_cmp_gt_f32_e32 vcc, s39, v63
	s_nop 1
	v_cndmask_b32_e32 v52, v63, v52, vcc
	v_rsq_f32_e32 v52, v52
	s_nop 0
	v_mul_f32_e32 v53, 0x45800000, v52
	v_cndmask_b32_e32 v74, v52, v53, vcc
	v_pk_mul_f32 v[52:53], v[56:57], v[74:75] op_sel_hi:[1,0]
	v_pk_mul_f32 v[54:55], v[54:55], v[74:75] op_sel_hi:[1,0]
	v_pk_mul_f32 v[50:51], v[50:51], v[74:75] op_sel_hi:[1,0]
	v_cvt_pk_bf16_f32 v52, v52, v53
	v_cvt_pk_bf16_f32 v53, v54, v55
	v_cvt_pk_bf16_f32 v54, v50, v51
	v_mul_f32_e32 v50, 0x4b800000, v62
	v_cmp_gt_f32_e32 vcc, s39, v62
	v_pk_mul_f32 v[48:49], v[48:49], v[74:75] op_sel_hi:[1,0]
	s_nop 0
	v_cndmask_b32_e32 v50, v62, v50, vcc
	v_rsq_f32_e32 v50, v50
	v_cvt_pk_bf16_f32 v55, v48, v49
	global_store_dwordx4 v[68:69], v[52:55], off offset:1024
	v_mul_f32_e32 v48, 0x45800000, v50
	s_nop 0
	v_cndmask_b32_e32 v52, v50, v48, vcc
	v_pk_mul_f32 v[48:49], v[72:73], v[52:53] op_sel_hi:[1,0]
	v_pk_mul_f32 v[50:51], v[70:71], v[52:53] op_sel_hi:[1,0]
	v_cvt_pk_bf16_f32 v48, v48, v49
	v_cvt_pk_bf16_f32 v49, v50, v51
	v_pk_mul_f32 v[50:51], v[60:61], v[52:53] op_sel_hi:[1,0]
	v_pk_mul_f32 v[52:53], v[58:59], v[52:53] op_sel_hi:[1,0]
	v_cvt_pk_bf16_f32 v50, v50, v51
	v_cvt_pk_bf16_f32 v51, v52, v53
	global_store_dwordx4 v[68:69], v[48:51], off offset:2048
	s_or_b64 exec, exec, s[4:5]
	s_and_saveexec_b64 s[4:5], s[40:41]
	s_cbranch_execz .LBB0_96
.LBB0_108:
	v_lshlrev_b32_e32 v48, 16, v31
	v_and_b32_e32 v49, 0xffff0000, v31
	v_mul_f32_e32 v50, 0xbfb8aa3b, v48
	v_mul_f32_e32 v51, 0xbfb8aa3b, v49
	v_exp_f32_e32 v50, v50
	v_exp_f32_e32 v51, v51
	v_lshlrev_b32_e32 v52, 16, v3
	v_and_b32_e32 v53, 0xffff0000, v3
	v_pk_mul_f32 v[48:49], v[52:53], v[48:49]
	v_pk_add_f32 v[50:51], v[50:51], 1.0 op_sel_hi:[1,0]
	s_nop 0
	s_nop 0
	v_rcp_f32_e32 v51, v51
	v_lshlrev_b32_e32 v52, 16, v30
	v_and_b32_e32 v53, 0xffff0000, v30
	v_mul_f32_e32 v54, 0xbfb8aa3b, v52
	v_mul_f32_e32 v55, 0xbfb8aa3b, v53
	v_exp_f32_e32 v54, v54
	v_exp_f32_e32 v55, v55
	v_rcp_f32_e32 v50, v50
	s_nop 0
	v_pk_mul_f32 v[48:49], v[48:49], v[50:51]
	v_pk_add_f32 v[50:51], v[54:55], 1.0 op_sel_hi:[1,0]
	v_lshlrev_b32_e32 v54, 16, v2
	v_and_b32_e32 v55, 0xffff0000, v2
	v_pk_mul_f32 v[52:53], v[54:55], v[52:53]
	v_rcp_f32_e32 v51, v51
	v_rcp_f32_e32 v50, v50
	v_lshlrev_b32_e32 v54, 16, v29
	v_and_b32_e32 v55, 0xffff0000, v29
	v_mul_f32_e32 v56, 0xbfb8aa3b, v54
	v_mul_f32_e32 v57, 0xbfb8aa3b, v55
	v_exp_f32_e32 v56, v56
	v_exp_f32_e32 v57, v57
	v_pk_mul_f32 v[50:51], v[52:53], v[50:51]
	v_mov_b32_e32 v52, v48
	v_mov_b32_e32 v53, v50
	v_pk_add_f32 v[56:57], v[56:57], 1.0 op_sel_hi:[1,0]
	v_pk_mul_f32 v[52:53], v[52:53], v[52:53]
	v_mov_b32_e32 v58, v49
	v_mov_b32_e32 v59, v51
	v_pk_fma_f32 v[52:53], v[58:59], v[58:59], v[52:53]
	v_lshlrev_b32_e32 v58, 16, v1
	v_and_b32_e32 v59, 0xffff0000, v1
	v_pk_mul_f32 v[54:55], v[58:59], v[54:55]
	v_rcp_f32_e32 v57, v57
	v_lshlrev_b32_e32 v58, 16, v28
	v_and_b32_e32 v59, 0xffff0000, v28
	v_mul_f32_e32 v60, 0xbfb8aa3b, v58
	v_mul_f32_e32 v61, 0xbfb8aa3b, v59
	v_exp_f32_e32 v60, v60
	v_exp_f32_e32 v61, v61
	v_rcp_f32_e32 v56, v56
	s_nop 0
	v_pk_mul_f32 v[54:55], v[54:55], v[56:57]
	v_pk_add_f32 v[56:57], v[60:61], 1.0 op_sel_hi:[1,0]
	v_lshlrev_b32_e32 v60, 16, v0
	v_and_b32_e32 v61, 0xffff0000, v0
	v_pk_mul_f32 v[58:59], v[60:61], v[58:59]
	v_mov_b32_e32 v69, v55
	v_rcp_f32_e32 v57, v57
	v_rcp_f32_e32 v56, v56
	v_lshlrev_b32_e32 v60, 16, v27
	v_and_b32_e32 v61, 0xffff0000, v27
	v_mul_f32_e32 v62, 0xbfb8aa3b, v60
	v_mul_f32_e32 v63, 0xbfb8aa3b, v61
	v_exp_f32_e32 v62, v62
	v_exp_f32_e32 v63, v63
	v_pk_mul_f32 v[56:57], v[58:59], v[56:57]
	v_mov_b32_e32 v59, v54
	v_mov_b32_e32 v58, v56
	v_pk_mul_f32 v[58:59], v[58:59], v[58:59]
	v_mov_b32_e32 v68, v57
	v_pk_fma_f32 v[68:69], v[68:69], v[68:69], v[58:59]
	v_pk_add_f32 v[58:59], v[62:63], 1.0 op_sel_hi:[1,0]
	v_lshlrev_b32_e32 v62, 16, v15
	v_and_b32_e32 v63, 0xffff0000, v15
	v_pk_mul_f32 v[60:61], v[62:63], v[60:61]
	v_rcp_f32_e32 v59, v59
	v_lshlrev_b32_e32 v62, 16, v26
	v_and_b32_e32 v63, 0xffff0000, v26
	v_mul_f32_e32 v70, 0xbfb8aa3b, v62
	v_mul_f32_e32 v71, 0xbfb8aa3b, v63
	v_exp_f32_e32 v70, v70
	v_exp_f32_e32 v71, v71
	v_rcp_f32_e32 v58, v58
	s_nop 0
	v_pk_mul_f32 v[58:59], v[60:61], v[58:59]
	v_pk_add_f32 v[60:61], v[70:71], 1.0 op_sel_hi:[1,0]
	v_lshlrev_b32_e32 v70, 16, v14
	v_and_b32_e32 v71, 0xffff0000, v14
	v_pk_mul_f32 v[62:63], v[70:71], v[62:63]
	v_rcp_f32_e32 v61, v61
	v_rcp_f32_e32 v60, v60
	v_lshlrev_b32_e32 v70, 16, v25
	v_and_b32_e32 v71, 0xffff0000, v25
	v_mul_f32_e32 v72, 0xbfb8aa3b, v70
	v_mul_f32_e32 v73, 0xbfb8aa3b, v71
	v_exp_f32_e32 v72, v72
	v_exp_f32_e32 v73, v73
	v_pk_mul_f32 v[60:61], v[62:63], v[60:61]
	v_mov_b32_e32 v62, v58
	v_mov_b32_e32 v63, v60
	v_pk_add_f32 v[72:73], v[72:73], 1.0 op_sel_hi:[1,0]
	v_pk_mul_f32 v[62:63], v[62:63], v[62:63]
	v_mov_b32_e32 v74, v59
	v_mov_b32_e32 v75, v61
	v_pk_fma_f32 v[62:63], v[74:75], v[74:75], v[62:63]
	v_lshlrev_b32_e32 v74, 16, v13
	v_and_b32_e32 v75, 0xffff0000, v13
	v_pk_mul_f32 v[70:71], v[74:75], v[70:71]
	v_rcp_f32_e32 v73, v73
	v_lshlrev_b32_e32 v74, 16, v24
	v_and_b32_e32 v75, 0xffff0000, v24
	v_mul_f32_e32 v84, 0xbfb8aa3b, v74
	v_mul_f32_e32 v85, 0xbfb8aa3b, v75
	v_exp_f32_e32 v84, v84
	v_exp_f32_e32 v85, v85
	v_rcp_f32_e32 v72, v72
	s_nop 0
	v_pk_mul_f32 v[70:71], v[70:71], v[72:73]
	v_pk_add_f32 v[72:73], v[84:85], 1.0 op_sel_hi:[1,0]
	v_lshlrev_b32_e32 v84, 16, v12
	v_and_b32_e32 v85, 0xffff0000, v12
	v_pk_mul_f32 v[74:75], v[84:85], v[74:75]
	v_div_scale_f32 v84, s[6:7], v72, v72, 1.0
	v_rcp_f32_e32 v87, v84
	v_rcp_f32_e32 v73, v73
	s_mov_b32 s6, 0x3b000000
	v_fma_f32 v83, -v84, v87, 1.0
	v_fmac_f32_e32 v87, v83, v87
	v_div_scale_f32 v83, vcc, 1.0, v72, 1.0
	v_mul_f32_e32 v85, v83, v87
	v_fma_f32 v86, -v84, v85, v83
	v_fmac_f32_e32 v85, v86, v87
	v_fma_f32 v83, -v84, v85, v83
	v_div_fmas_f32 v83, v83, v87, v85
	v_div_fixup_f32 v72, v83, v72, 1.0
	v_pk_mul_f32 v[72:73], v[74:75], v[72:73]
	v_mov_b32_e32 v75, v70
	v_mov_b32_e32 v74, v72
	v_pk_mul_f32 v[74:75], v[74:75], v[74:75]
	v_mov_b32_e32 v84, v73
	v_mov_b32_e32 v85, v71
	v_pk_fma_f32 v[74:75], v[84:85], v[84:85], v[74:75]
	v_mov_b32_e32 v85, v68
	v_mov_b32_e32 v84, v74
	v_mov_b32_e32 v68, v75
	v_pk_add_f32 v[68:69], v[84:85], v[68:69]
	v_mov_b32_e32 v74, v63
	v_mov_b32_e32 v75, v53
	v_pk_add_f32 v[68:69], v[74:75], v[68:69]
	v_mov_b32_e32 v63, v52
	v_pk_add_f32 v[52:53], v[62:63], v[68:69]
	ds_bpermute_b32 v63, v65, v53
	ds_bpermute_b32 v62, v65, v52
	s_waitcnt lgkmcnt(0)
; DI unsigned pk2(float lo, float hi) { const f32x2_t v = {lo, hi}; const bf16x2_t b = __builtin_convertvector(v, bf16x2_t); return __builtin_bit_cast(unsigned, b); }
; DI float lo16(unsigned w) { return __uint_as_float(w << 16); }
; DI float hi16(unsigned w) { return __uint_as_float(w & 0xffff0000u); }
; DI void gatenorm_pass(const Args& a, int G, const int tid) {
;     ...
;                 for (int e = 0; e < 4; ++e) { const float z0 = lo16(zw[q][g][e]), z1 = hi16(zw[q][g][e]); v[2 * e] = lo16(yw[q][g][e]) * z0 * __frcp_rn(1.0f + __expf(-z0)); v[2 * e + 1] = hi16(yw[q][g][e]) * z1 * __frcp_rn(1.0f + __expf(-z1)); s += v[2 * e] * v[2 * e] + v[2 * e + 1] * v[2 * e + 1]; }
;                 s = wave_sum(s); const float r = rsqrtf(s * (1.0f / 512.0f) + EPS);
;                 u32x4 w;
; #pragma unroll
;                 for (int e = 0; e < 4; ++e) w[e] = pk2(v[2 * e] * r, v[2 * e + 1] * r);
;                 *((u32x4*)(MIX + (size_t)m * LDMIX + 512 + g * 512) + lane) = w;
	v_pk_add_f32 v[52:53], v[52:53], v[62:63]
	ds_bpermute_b32 v63, v76, v53
	ds_bpermute_b32 v62, v76, v52
	s_waitcnt lgkmcnt(0)
	v_pk_add_f32 v[52:53], v[52:53], v[62:63]
	ds_bpermute_b32 v63, v77, v53
	ds_bpermute_b32 v62, v77, v52
	s_waitcnt lgkmcnt(0)
	v_pk_add_f32 v[52:53], v[52:53], v[62:63]
	ds_bpermute_b32 v63, v78, v53
	ds_bpermute_b32 v62, v78, v52
	s_waitcnt lgkmcnt(0)
	v_pk_add_f32 v[52:53], v[52:53], v[62:63]
	ds_bpermute_b32 v63, v79, v53
	ds_bpermute_b32 v62, v79, v52
	s_waitcnt lgkmcnt(0)
	v_pk_add_f32 v[52:53], v[52:53], v[62:63]
	ds_bpermute_b32 v63, v80, v53
	ds_bpermute_b32 v62, v80, v52
	s_waitcnt lgkmcnt(0)
	v_pk_add_f32 v[52:53], v[52:53], v[62:63]
	s_nop 0
	v_pk_fma_f32 v[62:63], v[52:53], s[6:7], v[176:177] op_sel_hi:[1,0,0]
	v_mad_i64_i32 v[68:69], s[6:7], v82, s27, v[66:67]
	v_mul_f32_e32 v52, 0x4b800000, v63
	v_cmp_gt_f32_e32 vcc, s39, v63
	s_nop 1
	v_cndmask_b32_e32 v52, v63, v52, vcc
	v_rsq_f32_e32 v52, v52
	s_nop 0
	v_mul_f32_e32 v53, 0x45800000, v52
	v_cndmask_b32_e32 v74, v52, v53, vcc
	v_pk_mul_f32 v[52:53], v[56:57], v[74:75] op_sel_hi:[1,0]
	v_pk_mul_f32 v[54:55], v[54:55], v[74:75] op_sel_hi:[1,0]
	v_pk_mul_f32 v[50:51], v[50:51], v[74:75] op_sel_hi:[1,0]
	v_cvt_pk_bf16_f32 v52, v52, v53
	v_cvt_pk_bf16_f32 v53, v54, v55
	v_cvt_pk_bf16_f32 v54, v50, v51
	v_mul_f32_e32 v50, 0x4b800000, v62
	v_cmp_gt_f32_e32 vcc, s39, v62
	v_pk_mul_f32 v[48:49], v[48:49], v[74:75] op_sel_hi:[1,0]
	s_nop 0
	v_cndmask_b32_e32 v50, v62, v50, vcc
	v_rsq_f32_e32 v50, v50
	v_cvt_pk_bf16_f32 v55, v48, v49
	global_store_dwordx4 v[68:69], v[52:55], off offset:1024
	v_mul_f32_e32 v48, 0x45800000, v50
	s_nop 0
	v_cndmask_b32_e32 v52, v50, v48, vcc
	v_pk_mul_f32 v[48:49], v[72:73], v[52:53] op_sel_hi:[1,0]
	v_pk_mul_f32 v[50:51], v[70:71], v[52:53] op_sel_hi:[1,0]
	v_cvt_pk_bf16_f32 v48, v48, v49
	v_cvt_pk_bf16_f32 v49, v50, v51
	v_pk_mul_f32 v[50:51], v[60:61], v[52:53] op_sel_hi:[1,0]
	v_pk_mul_f32 v[52:53], v[58:59], v[52:53] op_sel_hi:[1,0]
	v_cvt_pk_bf16_f32 v50, v50, v51
	v_cvt_pk_bf16_f32 v51, v52, v53
	global_store_dwordx4 v[68:69], v[48:51], off offset:2048
	s_branch .LBB0_96

; #define LAS __attribute__((address_space(3)))
; DI float lo16(unsigned w) { return __uint_as_float(w << 16); }
; DI float hi16(unsigned w) { return __uint_as_float(w & 0xffff0000u); }
; DI void ssd_unit(const Args& a, bool sample, int b, int hd, LAS unsigned char* lds, const int tid) {
;     ...
;         for (int it = tid; it < TC * 40; it += NTHR) {
;             const int tt = it / 40, cgp = it % 40, t = t0 + tt;
;             int ch; LAS float* dst;
;             if (cgp < 8) { ch = hd * 64 + cgp * 8; dst = Xs + tt * 64 + cgp * 8; }
;             else if (cgp < 24) { ch = 1024 + gr * 128 + (cgp - 8) * 8; dst = Bs + tt * 128 + (cgp - 8) * 8; }
;             else { ch = 1280 + gr * 128 + (cgp - 24) * 8; dst = Cs + tt * 128 + (cgp - 24) * 8; }
;             float acc[8];
;             { const f32x4 b0 = *(const f32x4*)(cb + ch), b1 = *(const f32x4*)(cb + ch + 4);
; #pragma unroll
;               for (int e = 0; e < 4; ++e) { acc[e] = b0[e]; acc[4 + e] = b1[e]; } }
; #pragma unroll
;             for (int jj = 0; jj < 4; ++jj) {
;                 const int ts = t - 3 + jj;
;                 float raw[8];
;                 if (ts >= 0) { const u32x4 w = *(const u32x4*)(HIN + (row0 + ts) * LDH + C_XBC + ch);
; #pragma unroll
;                     for (int e = 0; e < 4; ++e) { raw[2 * e] = lo16(w[e]); raw[2 * e + 1] = hi16(w[e]); } }
;                 else if (sample) { const float* cp = conv0 + ((size_t)b * 3 + (3 + ts)) * 1536 + ch; const f32x4 r0 = *(const f32x4*)cp, r1 = *(const f32x4*)(cp + 4);
; #pragma unroll
;                     for (int e = 0; e < 4; ++e) { raw[e] = r0[e]; raw[4 + e] = r1[e]; } }
;                 else {
; #pragma unroll
;                     for (int e = 0; e < 8; ++e) raw[e] = 0.f; }
;                 const f32x4 w0 = *(const f32x4*)(cw + jj * 1536 + ch), w1 = *(const f32x4*)(cw + jj * 1536 + ch + 4);
; #pragma unroll
;                 for (int e = 0; e < 4; ++e) { acc[e] += w0[e] * raw[e]; acc[4 + e] += w1[e] * raw[4 + e]; }
;             }
; #pragma unroll
;             for (int e = 0; e < 8; ++e) acc[e] = acc[e] * __frcp_rn(1.0f + __expf(-acc[e]));
;             *(LAS f32x4*)dst = (f32x4){acc[0], acc[1], acc[2], acc[3]}; *(LAS f32x4*)(dst + 4) = (f32x4){acc[4], acc[5], acc[6], acc[7]};
.LBB0_167:
	s_or_b64 exec, exec, s[8:9]
	s_waitcnt vmcnt(4)
	v_pk_fma_f32 v[24:25], v[28:29], v[40:41], v[24:25]
	v_pk_fma_f32 v[16:17], v[32:33], v[36:37], v[16:17]
	s_waitcnt vmcnt(3)
	v_pk_fma_f32 v[24:25], v[44:45], v[60:61], v[24:25]
	s_mov_b64 s[8:9], 0x4800
	s_waitcnt vmcnt(2)
	v_pk_fma_f32 v[16:17], v[48:49], v[56:57], v[16:17]
	s_waitcnt vmcnt(1)
	v_pk_fma_f32 v[32:33], v[64:65], v[76:77], v[24:25]
	v_lshl_add_u64 v[24:25], v[88:89], 0, s[8:9]
	s_movk_i32 s8, 0x4000
	v_pk_fma_f32 v[26:27], v[30:31], v[42:43], v[26:27]
	v_pk_fma_f32 v[18:19], v[34:35], v[38:39], v[18:19]
	s_waitcnt vmcnt(0)
	v_pk_fma_f32 v[30:31], v[68:69], v[72:73], v[16:17]
	v_add_co_u32_e32 v16, vcc, s8, v88
	v_pk_fma_f32 v[26:27], v[46:47], v[62:63], v[26:27]
	v_pk_fma_f32 v[18:19], v[50:51], v[58:59], v[18:19]
	v_addc_co_u32_e32 v17, vcc, 0, v89, vcc
	v_pk_fma_f32 v[34:35], v[66:67], v[78:79], v[26:27]
	v_pk_fma_f32 v[28:29], v[70:71], v[74:75], v[18:19]
	global_load_dwordx4 v[16:19], v[16:17], off offset:2048
	s_nop 0
	global_load_dwordx4 v[24:27], v[24:25], off offset:16
	v_add_u32_e32 v93, 0x4000, v93
	v_add_u32_e32 v82, 0x1000, v82
	s_waitcnt vmcnt(1)
	v_pk_fma_f32 v[18:19], v[54:55], v[18:19], v[34:35]
	s_nop 0
	v_mul_f32_e32 v34, 0xbfb8aa3b, v18
	v_mul_f32_e32 v35, 0xbfb8aa3b, v19
	v_exp_f32_e32 v34, v34
	v_exp_f32_e32 v35, v35
	v_pk_fma_f32 v[16:17], v[52:53], v[16:17], v[32:33]
	s_waitcnt vmcnt(0)
	v_pk_fma_f32 v[20:21], v[20:21], v[24:25], v[30:31]
	v_mul_f32_e32 v32, 0xbfb8aa3b, v16
	v_pk_add_f32 v[34:35], v[34:35], 1.0 op_sel_hi:[1,0]
	v_mul_f32_e32 v33, 0xbfb8aa3b, v17
	v_exp_f32_e32 v32, v32
	v_exp_f32_e32 v33, v33
	v_mul_f32_e32 v24, 0xbfb8aa3b, v20
	v_rcp_f32_e32 v35, v35
	v_pk_add_f32 v[32:33], v[32:33], 1.0 op_sel_hi:[1,0]
	v_exp_f32_e32 v30, v24
	v_mul_f32_e32 v24, 0xbfb8aa3b, v21
	v_rcp_f32_e32 v34, v34
	v_exp_f32_e32 v31, v24
	v_pk_fma_f32 v[22:23], v[22:23], v[26:27], v[28:29]
	v_pk_mul_f32 v[18:19], v[18:19], v[34:35]
	v_rcp_f32_e32 v33, v33
	v_pk_add_f32 v[26:27], v[30:31], 1.0 op_sel_hi:[1,0]
	v_mul_f32_e32 v24, 0xbfb8aa3b, v22
	v_rcp_f32_e32 v32, v32
	s_nop 0
	v_pk_mul_f32 v[16:17], v[16:17], v[32:33]
	v_rcp_f32_e32 v27, v27
	v_mul_f32_e32 v25, 0xbfb8aa3b, v23
	v_exp_f32_e32 v24, v24
	v_exp_f32_e32 v25, v25
	s_nop 0
	v_pk_add_f32 v[24:25], v[24:25], 1.0 op_sel_hi:[1,0]
	v_rcp_f32_e32 v26, v26
	s_nop 0
	v_pk_mul_f32 v[20:21], v[20:21], v[26:27]
	v_rcp_f32_e32 v25, v25
	s_movk_i32 s8, 0x7f
	v_rcp_f32_e32 v24, v24
	s_nop 0
	v_pk_mul_f32 v[22:23], v[22:23], v[24:25]
	ds_write_b128 v94, v[16:19]
	ds_write_b128 v94, v[20:23] offset:16
	v_add_u32_e32 v16, 0x200, v84
	v_cmp_lt_i32_e32 vcc, s8, v84
	s_or_b64 s[6:7], vcc, s[6:7]
	v_mov_b32_e32 v84, v16
	s_andn2_b64 exec, exec, s[6:7]
	s_cbranch_execz .LBB0_192

; #define LAS __attribute__((address_space(3)))
; DI void conv_row8(const u32x4 (&raw)[11], int i, const float (&w)[4][8], const float (&bias)[8], float (&v)[8]) {
; #pragma unroll
;     for (int e = 0; e < 8; ++e) v[e] = bias[e];
; #pragma unroll
;     for (int jj = 0; jj < 4; ++jj) {
; #pragma unroll
;         for (int e = 0; e < 4; ++e) { v[2 * e] += w[jj][2 * e] * lo16(raw[i + jj][e]); v[2 * e + 1] += w[jj][2 * e + 1] * hi16(raw[i + jj][e]); }
;     }
; #pragma unroll
;     for (int e = 0; e < 8; ++e) v[e] = v[e] * __frcp_rn(1.0f + __expf(-v[e]));
; }
; DI void ssd_prompt_unit(const Args& a, int b, int hd, LAS unsigned char* lds, const int tid) {
;     ...
;             const float cum63 = cumC[63];
;             float cwt[4][8], cbias[8];
; #pragma unroll
;             for (int jj = 0; jj < 4; ++jj) { const f32x4 w0 = *(const LAS f32x4*)(cwS + jj * 8), w1 = *(const LAS f32x4*)(cwS + jj * 8 + 4);
; #pragma unroll
;                 for (int e = 0; e < 4; ++e) { cwt[jj][e] = w0[e]; cwt[jj][4 + e] = w1[e]; } }
;             { const f32x4 b0 = *(const LAS f32x4*)(cwS + 32), b1 = *(const LAS f32x4*)(cwS + 36);
; #pragma unroll
;               for (int e = 0; e < 4; ++e) { cbias[e] = b0[e]; cbias[4 + e] = b1[e]; } }
;             const f32x4 cq0 = *(const LAS f32x4*)(cumC + seg * 8), cq1 = *(const LAS f32x4*)(cumC + seg * 8 + 4), dq0 = *(const LAS f32x4*)(dtC + seg * 8), dq1 = *(const LAS f32x4*)(dtC + seg * 8 + 4);
;             const float cqa[8] = {cq0[0], cq0[1], cq0[2], cq0[3], cq1[0], cq1[1], cq1[2], cq1[3]}, dqa[8] = {dq0[0], dq0[1], dq0[2], dq0[3], dq1[0], dq1[1], dq1[2], dq1[3]};
;             const int tn = (c + 1 < 32) ? t0 + 64 : t0;
;             const bf16_t* nsrc = HIN + (row0 + tn + seg * 8 - 3 + 2 * kq) * LDH + C_XBC + ch;
;     ...
; #pragma unroll
;             for (int k = 0; k < 4; ++k) {
;                 const bool act = stager || k == 0;
;                 float va[8], vb[8];
;                 if (act) { conv_row8(raw, 2 * k, cwt, cbias, va); conv_row8(raw, 2 * k + 1, cwt, cbias, vb); }
;                 raw[2 * k] = *(const u32x4*)(nsrc + SP_ROWOFF(2 * k)); raw[2 * k + 1] = *(const u32x4*)(nsrc + SP_ROWOFF(2 * k + 1));
;                 if (k == 3) { raw[8] = *(const u32x4*)(nsrc + SP_ROWOFF(8)); raw[9] = *(const u32x4*)(nsrc + SP_ROWOFF(9)); raw[10] = *(const u32x4*)(nsrc + SP_ROWOFF(10)); }
.LBB0_286:
	s_and_b32 s58, s1, 1
	s_lshl_b32 s5, s58, 8
	s_add_i32 s66, s5, 0
	s_add_i32 s57, s66, 0x1c000
	s_add_i32 s66, s66, 0x1c200
	s_cmp_lg_u32 s92, 0x5d0000
	s_cselect_b64 s[12:13], -1, 0
	v_mov_b32_e32 v32, s57
	s_and_b64 s[14:15], s[12:13], exec
	ds_read_b32 v160, v32 offset:252
	ds_read_b128 v[100:103], v215
	ds_read_b128 v[44:47], v215 offset:16
	ds_read_b128 v[104:107], v215 offset:32
	ds_read_b128 v[48:51], v215 offset:48
	ds_read_b128 v[108:111], v215 offset:64
	ds_read_b128 v[52:55], v215 offset:80
	ds_read_b128 v[60:63], v215 offset:96
	ds_read_b128 v[40:43], v215 offset:112
	ds_read_b128 v[112:115], v215 offset:128
	ds_read_b128 v[56:59], v215 offset:144
	s_cselect_b32 s14, s62, 0x7c0
	s_mov_b32 s15, s95
	v_lshl_add_u64 v[144:145], v[136:137], 0, s[14:15]
	v_mad_u64_u32 v[142:143], s[14:15], v144, s55, v[138:139]
	v_mad_i32_i24 v143, v145, s55, v143
	s_waitcnt vmcnt(0)
	v_lshlrev_b32_e32 v144, 16, v72
	v_and_b32_e32 v145, 0xffff0000, v72
	v_lshlrev_b32_e32 v148, 16, v73
	v_and_b32_e32 v149, 0xffff0000, v73
	v_lshlrev_b32_e32 v146, 16, v76
	v_and_b32_e32 v147, 0xffff0000, v76
	v_lshlrev_b32_e32 v150, 16, v77
	v_and_b32_e32 v151, 0xffff0000, v77
	v_lshlrev_b32_e32 v76, 16, v78
	v_and_b32_e32 v77, 0xffff0000, v78
	v_lshlrev_b32_e32 v72, 16, v79
	v_and_b32_e32 v73, 0xffff0000, v79
	s_waitcnt lgkmcnt(1)
	v_pk_fma_f32 v[78:79], v[100:101], v[144:145], v[112:113]
	v_lshlrev_b32_e32 v190, 16, v92
	v_and_b32_e32 v191, 0xffff0000, v92
	v_pk_fma_f32 v[78:79], v[104:105], v[146:147], v[78:79]
	v_lshlrev_b32_e32 v186, 16, v96
	v_and_b32_e32 v187, 0xffff0000, v96
	v_pk_fma_f32 v[78:79], v[108:109], v[190:191], v[78:79]
	v_lshlrev_b32_e32 v174, 16, v93
	v_pk_fma_f32 v[78:79], v[60:61], v[186:187], v[78:79]
	v_and_b32_e32 v175, 0xffff0000, v93
	v_lshlrev_b32_e32 v170, 16, v97
	v_and_b32_e32 v171, 0xffff0000, v97
	v_lshlrev_b32_e32 v96, 16, v98
	v_and_b32_e32 v97, 0xffff0000, v98
	v_lshlrev_b32_e32 v92, 16, v99
	v_and_b32_e32 v93, 0xffff0000, v99
	v_mul_f32_e32 v98, 0xbfb8aa3b, v78
	v_mul_f32_e32 v99, 0xbfb8aa3b, v79
	v_exp_f32_e32 v98, v98
	v_exp_f32_e32 v99, v99
	v_lshlrev_b32_e32 v152, 16, v122
	v_and_b32_e32 v153, 0xffff0000, v122
	v_lshlrev_b32_e32 v156, 16, v120
	v_pk_add_f32 v[98:99], v[98:99], 1.0 op_sel_hi:[1,0]
	v_and_b32_e32 v157, 0xffff0000, v120
	v_lshlrev_b32_e32 v154, 16, v121
	v_and_b32_e32 v155, 0xffff0000, v121
	v_lshlrev_b32_e32 v120, 16, v123
	v_and_b32_e32 v121, 0xffff0000, v123
	v_lshlrev_b32_e32 v158, 16, v74
	v_and_b32_e32 v159, 0xffff0000, v74
	v_lshlrev_b32_e32 v168, 16, v94
	v_rcp_f32_e32 v99, v99
	v_and_b32_e32 v169, 0xffff0000, v94
	v_lshlrev_b32_e32 v74, 16, v75
	v_and_b32_e32 v75, 0xffff0000, v75
	v_rcp_f32_e32 v98, v98
	s_nop 0
	v_pk_mul_f32 v[144:145], v[78:79], v[98:99]
	v_pk_fma_f32 v[78:79], v[100:101], v[146:147], v[112:113]
	s_waitcnt lgkmcnt(0)
; DI float lo16(unsigned w) { return __uint_as_float(w << 16); }
; DI float hi16(unsigned w) { return __uint_as_float(w & 0xffff0000u); }
; DI void conv_row8(const u32x4 (&raw)[11], int i, const float (&w)[4][8], const float (&bias)[8], float (&v)[8]) {
; #pragma unroll
;     for (int e = 0; e < 8; ++e) v[e] = bias[e];
; #pragma unroll
;     for (int jj = 0; jj < 4; ++jj) {
; #pragma unroll
;         for (int e = 0; e < 4; ++e) { v[2 * e] += w[jj][2 * e] * lo16(raw[i + jj][e]); v[2 * e + 1] += w[jj][2 * e + 1] * hi16(raw[i + jj][e]); }
;     }
; #pragma unroll
;     for (int e = 0; e < 8; ++e) v[e] = v[e] * __frcp_rn(1.0f + __expf(-v[e]));
; }
; DI void ssd_prompt_unit(const Args& a, int b, int hd, LAS unsigned char* lds, const int tid) {
;     ...
;             for (int k = 0; k < 4; ++k) {
;                 const bool act = stager || k == 0;
;                 float va[8], vb[8];
;                 if (act) { conv_row8(raw, 2 * k, cwt, cbias, va); conv_row8(raw, 2 * k + 1, cwt, cbias, vb); }
;                 raw[2 * k] = *(const u32x4*)(nsrc + SP_ROWOFF(2 * k)); raw[2 * k + 1] = *(const u32x4*)(nsrc + SP_ROWOFF(2 * k + 1));
;                 if (k == 3) { raw[8] = *(const u32x4*)(nsrc + SP_ROWOFF(8)); raw[9] = *(const u32x4*)(nsrc + SP_ROWOFF(9)); raw[10] = *(const u32x4*)(nsrc + SP_ROWOFF(10)); }
;                 const int ta = seg * 8 + 2 * (stager ? k : kq), tb = ta + 1;
;                 if (act) {
	v_pk_fma_f32 v[74:75], v[46:47], v[74:75], v[58:59]
	v_pk_fma_f32 v[78:79], v[104:105], v[190:191], v[78:79]
	v_lshlrev_b32_e32 v94, 16, v95
	v_pk_fma_f32 v[78:79], v[108:109], v[186:187], v[78:79]
	v_and_b32_e32 v95, 0xffff0000, v95
	v_pk_fma_f32 v[78:79], v[60:61], v[156:157], v[78:79]
	v_pk_fma_f32 v[74:75], v[50:51], v[72:73], v[74:75]
	v_mul_f32_e32 v98, 0xbfb8aa3b, v78
	v_mul_f32_e32 v99, 0xbfb8aa3b, v79
	v_exp_f32_e32 v98, v98
	v_exp_f32_e32 v99, v99
	v_pk_fma_f32 v[74:75], v[54:55], v[94:95], v[74:75]
	v_pk_fma_f32 v[72:73], v[46:47], v[72:73], v[58:59]
	v_pk_fma_f32 v[74:75], v[42:43], v[92:93], v[74:75]
	v_pk_add_f32 v[98:99], v[98:99], 1.0 op_sel_hi:[1,0]
	v_pk_fma_f32 v[72:73], v[50:51], v[94:95], v[72:73]
	v_pk_fma_f32 v[72:73], v[54:55], v[92:93], v[72:73]
	v_lshlrev_b32_e32 v32, 2, v134
	v_pk_fma_f32 v[72:73], v[42:43], v[120:121], v[72:73]
	v_rcp_f32_e32 v99, v99
	v_add_u32_e32 v162, s57, v32
	v_add_u32_e32 v32, s66, v32
	ds_read_b128 v[128:131], v162
	ds_read_b128 v[36:39], v162 offset:16
	v_rcp_f32_e32 v98, v98
	s_nop 0
	v_pk_mul_f32 v[146:147], v[78:79], v[98:99]
	v_pk_fma_f32 v[78:79], v[102:103], v[148:149], v[114:115]
	ds_read_b128 v[124:127], v32
	ds_read_b128 v[32:35], v32 offset:16
	v_pk_fma_f32 v[78:79], v[106:107], v[150:151], v[78:79]
	s_cmp_lt_i32 s67, 1
	v_pk_fma_f32 v[78:79], v[110:111], v[174:175], v[78:79]
	s_nop 0
	v_pk_fma_f32 v[78:79], v[62:63], v[170:171], v[78:79]
	s_nop 0
	v_mul_f32_e32 v98, 0xbfb8aa3b, v78
	v_mul_f32_e32 v99, 0xbfb8aa3b, v79
	v_exp_f32_e32 v98, v98
	v_exp_f32_e32 v99, v99
	s_nop 0
	v_pk_add_f32 v[98:99], v[98:99], 1.0 op_sel_hi:[1,0]
	s_nop 0
	s_nop 0
	v_rcp_f32_e32 v99, v99
	s_nop 0
	v_rcp_f32_e32 v98, v98
	s_nop 0
	v_pk_mul_f32 v[148:149], v[78:79], v[98:99]
	v_pk_fma_f32 v[78:79], v[102:103], v[150:151], v[114:115]
	s_nop 0
	v_pk_fma_f32 v[78:79], v[106:107], v[174:175], v[78:79]
	s_nop 0
	v_pk_fma_f32 v[78:79], v[110:111], v[170:171], v[78:79]
	s_nop 0
	v_pk_fma_f32 v[78:79], v[62:63], v[154:155], v[78:79]
	s_nop 0
	v_mul_f32_e32 v98, 0xbfb8aa3b, v78
	v_mul_f32_e32 v99, 0xbfb8aa3b, v79
	v_exp_f32_e32 v98, v98
	v_exp_f32_e32 v99, v99
	s_nop 0
	v_pk_add_f32 v[98:99], v[98:99], 1.0 op_sel_hi:[1,0]
	s_nop 0
	s_nop 0
	v_rcp_f32_e32 v99, v99
	s_nop 0
	v_rcp_f32_e32 v98, v98
	s_nop 0
	v_pk_mul_f32 v[150:151], v[78:79], v[98:99]
	v_pk_fma_f32 v[78:79], v[44:45], v[158:159], v[56:57]
	s_nop 0
	v_pk_fma_f32 v[78:79], v[48:49], v[76:77], v[78:79]
	v_pk_fma_f32 v[76:77], v[44:45], v[76:77], v[56:57]
	v_pk_fma_f32 v[78:79], v[52:53], v[168:169], v[78:79]
	v_pk_fma_f32 v[76:77], v[48:49], v[168:169], v[76:77]
	v_pk_fma_f32 v[78:79], v[40:41], v[96:97], v[78:79]
	v_pk_fma_f32 v[76:77], v[52:53], v[96:97], v[76:77]
	v_mul_f32_e32 v98, 0xbfb8aa3b, v78
	v_mul_f32_e32 v99, 0xbfb8aa3b, v79
	v_exp_f32_e32 v98, v98
	v_exp_f32_e32 v99, v99
	v_pk_fma_f32 v[76:77], v[40:41], v[152:153], v[76:77]
	v_pk_add_f32 v[98:99], v[98:99], 1.0 op_sel_hi:[1,0]
	s_nop 0
	s_nop 0
	v_rcp_f32_e32 v99, v99
	s_nop 0
	v_rcp_f32_e32 v98, v98
	s_nop 0
	v_pk_mul_f32 v[158:159], v[78:79], v[98:99]
	v_mul_f32_e32 v78, 0xbfb8aa3b, v76
	v_mul_f32_e32 v79, 0xbfb8aa3b, v77
	v_exp_f32_e32 v78, v78
	v_exp_f32_e32 v79, v79
	s_nop 0
	v_pk_add_f32 v[78:79], v[78:79], 1.0 op_sel_hi:[1,0]
	s_nop 0
	s_nop 0
	v_rcp_f32_e32 v79, v79
	s_nop 0
	v_rcp_f32_e32 v78, v78
	s_nop 0
	v_pk_mul_f32 v[166:167], v[76:77], v[78:79]
	v_mul_f32_e32 v76, 0xbfb8aa3b, v74
	v_mul_f32_e32 v77, 0xbfb8aa3b, v75
	v_exp_f32_e32 v76, v76
	v_exp_f32_e32 v77, v77
	s_nop 0
	v_pk_add_f32 v[76:77], v[76:77], 1.0 op_sel_hi:[1,0]
	s_nop 0
	s_nop 0
	v_rcp_f32_e32 v77, v77
	s_nop 0
	v_rcp_f32_e32 v76, v76
	s_nop 0
	v_pk_mul_f32 v[184:185], v[74:75], v[76:77]
	v_mul_f32_e32 v74, 0xbfb8aa3b, v72
	v_mul_f32_e32 v75, 0xbfb8aa3b, v73
	v_exp_f32_e32 v74, v74
	v_exp_f32_e32 v75, v75
	s_nop 0
	v_pk_add_f32 v[74:75], v[74:75], 1.0 op_sel_hi:[1,0]
	s_nop 0
	s_nop 0
	v_rcp_f32_e32 v75, v75
	s_mov_b64 s[14:15], -1
	v_rcp_f32_e32 v74, v74
	v_add_co_u32_e32 v76, vcc, 0x2000, v142
	v_pk_mul_f32 v[194:195], v[72:73], v[74:75]
	s_nop 0
	v_addc_co_u32_e32 v77, vcc, 0, v143, vcc
	global_load_dwordx4 v[72:75], v[142:143], off offset:3584
	s_nop 0
	global_load_dwordx4 v[76:79], v[76:77], off offset:2176
	s_cbranch_scc1 .LBB0_295
	s_cmp_lg_u32 s67, 1
	s_cbranch_scc0 .LBB0_292
	s_andn2_b64 vcc, exec, s[22:23]
	s_cbranch_vccnz .LBB0_290
	v_lshl_add_u32 v98, s64, 2, v162
	ds_read_b64 v[98:99], v98
	s_branch .LBB0_291

; DI float lo16(unsigned w) { return __uint_as_float(w << 16); }
; DI float hi16(unsigned w) { return __uint_as_float(w & 0xffff0000u); }
; DI void conv_row8(const u32x4 (&raw)[11], int i, const float (&w)[4][8], const float (&bias)[8], float (&v)[8]) {
; #pragma unroll
;     for (int e = 0; e < 8; ++e) v[e] = bias[e];
; #pragma unroll
;     for (int jj = 0; jj < 4; ++jj) {
; #pragma unroll
;         for (int e = 0; e < 4; ++e) { v[2 * e] += w[jj][2 * e] * lo16(raw[i + jj][e]); v[2 * e + 1] += w[jj][2 * e + 1] * hi16(raw[i + jj][e]); }
;     }
; #pragma unroll
;     for (int e = 0; e < 8; ++e) v[e] = v[e] * __frcp_rn(1.0f + __expf(-v[e]));
; }
; DI void ssd_prompt_unit(const Args& a, int b, int hd, LAS unsigned char* lds, const int tid) {
;     ...
;             for (int k = 0; k < 4; ++k) {
;                 const bool act = stager || k == 0;
;                 float va[8], vb[8];
;                 if (act) { conv_row8(raw, 2 * k, cwt, cbias, va); conv_row8(raw, 2 * k + 1, cwt, cbias, vb); }
.LBB0_297:
	v_cndmask_b32_e64 v98, 0, 1, s[26:27]
	v_cmp_ne_u32_e64 s[52:53], 1, v98
	s_andn2_b64 vcc, exec, s[26:27]
	v_lshlrev_b32_e32 v192, 16, v80
	v_and_b32_e32 v193, 0xffff0000, v80
	v_lshlrev_b32_e32 v164, 16, v116
	v_and_b32_e32 v165, 0xffff0000, v116
	v_lshlrev_b32_e32 v188, 16, v81
	v_and_b32_e32 v189, 0xffff0000, v81
	v_lshlrev_b32_e32 v162, 16, v117
	v_and_b32_e32 v163, 0xffff0000, v117
	v_lshlrev_b32_e32 v172, 16, v82
	v_and_b32_e32 v173, 0xffff0000, v82
	s_waitcnt lgkmcnt(3)
	v_lshlrev_b32_e32 v128, 16, v118
	v_and_b32_e32 v129, 0xffff0000, v118
	v_lshlrev_b32_e32 v122, 16, v83
	v_and_b32_e32 v123, 0xffff0000, v83
	s_waitcnt lgkmcnt(1)
	v_lshlrev_b32_e32 v124, 16, v119
	v_and_b32_e32 v125, 0xffff0000, v119
	s_cbranch_vccnz .LBB0_299
	v_pk_fma_f32 v[80:81], v[100:101], v[190:191], v[112:113]
	s_nop 0
	v_pk_fma_f32 v[80:81], v[104:105], v[186:187], v[80:81]
	s_nop 0
	v_pk_fma_f32 v[80:81], v[108:109], v[156:157], v[80:81]
	s_nop 0
	v_pk_fma_f32 v[80:81], v[60:61], v[192:193], v[80:81]
	s_nop 0
	v_mul_f32_e32 v82, 0xbfb8aa3b, v80
	v_mul_f32_e32 v83, 0xbfb8aa3b, v81
	v_exp_f32_e32 v82, v82
	v_exp_f32_e32 v83, v83
	s_nop 0
	v_pk_add_f32 v[82:83], v[82:83], 1.0 op_sel_hi:[1,0]
	s_nop 0
	s_nop 0
	v_rcp_f32_e32 v83, v83
	s_nop 0
	v_rcp_f32_e32 v82, v82
	s_nop 0
	v_pk_mul_f32 v[144:145], v[80:81], v[82:83]
	v_pk_fma_f32 v[80:81], v[100:101], v[186:187], v[112:113]
	s_nop 0
	v_pk_fma_f32 v[80:81], v[104:105], v[156:157], v[80:81]
	s_nop 0
	v_pk_fma_f32 v[80:81], v[108:109], v[192:193], v[80:81]
	s_nop 0
	v_pk_fma_f32 v[80:81], v[60:61], v[164:165], v[80:81]
	s_nop 0
	v_mul_f32_e32 v82, 0xbfb8aa3b, v80
	v_mul_f32_e32 v83, 0xbfb8aa3b, v81
	v_exp_f32_e32 v82, v82
	v_exp_f32_e32 v83, v83
	s_nop 0
	v_pk_add_f32 v[82:83], v[82:83], 1.0 op_sel_hi:[1,0]
	s_nop 0
	s_nop 0
	v_rcp_f32_e32 v83, v83
	s_nop 0
	v_rcp_f32_e32 v82, v82
	s_nop 0
	v_pk_mul_f32 v[146:147], v[80:81], v[82:83]
	v_pk_fma_f32 v[80:81], v[102:103], v[174:175], v[114:115]
	s_nop 0
	v_pk_fma_f32 v[80:81], v[106:107], v[170:171], v[80:81]
	s_nop 0
	v_pk_fma_f32 v[80:81], v[110:111], v[154:155], v[80:81]
	s_nop 0
	v_pk_fma_f32 v[80:81], v[62:63], v[188:189], v[80:81]
	s_nop 0
	v_mul_f32_e32 v82, 0xbfb8aa3b, v80
	v_mul_f32_e32 v83, 0xbfb8aa3b, v81
	v_exp_f32_e32 v82, v82
	v_exp_f32_e32 v83, v83
	s_nop 0
	v_pk_add_f32 v[82:83], v[82:83], 1.0 op_sel_hi:[1,0]
	s_nop 0
	s_nop 0
	v_rcp_f32_e32 v83, v83
	s_nop 0
	v_rcp_f32_e32 v82, v82
	s_nop 0
	v_pk_mul_f32 v[148:149], v[80:81], v[82:83]
	v_pk_fma_f32 v[80:81], v[102:103], v[170:171], v[114:115]
	s_nop 0
	v_pk_fma_f32 v[80:81], v[106:107], v[154:155], v[80:81]
	s_nop 0
	v_pk_fma_f32 v[80:81], v[110:111], v[188:189], v[80:81]
	s_nop 0
	v_pk_fma_f32 v[80:81], v[62:63], v[162:163], v[80:81]
	s_nop 0
	v_mul_f32_e32 v82, 0xbfb8aa3b, v80
	v_mul_f32_e32 v83, 0xbfb8aa3b, v81
	v_exp_f32_e32 v82, v82
	v_exp_f32_e32 v83, v83
	s_nop 0
	v_pk_add_f32 v[82:83], v[82:83], 1.0 op_sel_hi:[1,0]
	s_nop 0
	s_nop 0
	v_rcp_f32_e32 v83, v83
	s_nop 0
	v_rcp_f32_e32 v82, v82
	s_nop 0
	v_pk_mul_f32 v[150:151], v[80:81], v[82:83]
	v_pk_fma_f32 v[80:81], v[44:45], v[168:169], v[56:57]
	s_nop 0
	v_pk_fma_f32 v[80:81], v[48:49], v[96:97], v[80:81]
	s_nop 0
	v_pk_fma_f32 v[80:81], v[52:53], v[152:153], v[80:81]
	s_nop 0
	v_pk_fma_f32 v[80:81], v[40:41], v[172:173], v[80:81]
	s_nop 0
	v_mul_f32_e32 v82, 0xbfb8aa3b, v80
	v_mul_f32_e32 v83, 0xbfb8aa3b, v81
	v_exp_f32_e32 v82, v82
	v_exp_f32_e32 v83, v83
	s_nop 0
	v_pk_add_f32 v[82:83], v[82:83], 1.0 op_sel_hi:[1,0]
	s_nop 0
	s_nop 0
	v_rcp_f32_e32 v83, v83
	s_nop 0
	v_rcp_f32_e32 v82, v82
	s_nop 0
	v_pk_mul_f32 v[158:159], v[80:81], v[82:83]
	v_pk_fma_f32 v[80:81], v[44:45], v[96:97], v[56:57]
	s_nop 0
	v_pk_fma_f32 v[80:81], v[48:49], v[152:153], v[80:81]
	s_nop 0
	v_pk_fma_f32 v[80:81], v[52:53], v[172:173], v[80:81]
	s_nop 0
	v_pk_fma_f32 v[80:81], v[40:41], v[128:129], v[80:81]
	s_nop 0
	v_mul_f32_e32 v82, 0xbfb8aa3b, v80
	v_mul_f32_e32 v83, 0xbfb8aa3b, v81
	v_exp_f32_e32 v82, v82
	v_exp_f32_e32 v83, v83
	s_nop 0
	v_pk_add_f32 v[82:83], v[82:83], 1.0 op_sel_hi:[1,0]
	s_nop 0
	s_nop 0
	v_rcp_f32_e32 v83, v83
	s_nop 0
	v_rcp_f32_e32 v82, v82
	s_nop 0
	v_pk_mul_f32 v[166:167], v[80:81], v[82:83]
	v_pk_fma_f32 v[80:81], v[46:47], v[94:95], v[58:59]
	s_nop 0
	v_pk_fma_f32 v[80:81], v[50:51], v[92:93], v[80:81]
	s_nop 0
	v_pk_fma_f32 v[80:81], v[54:55], v[120:121], v[80:81]
	s_nop 0
	v_pk_fma_f32 v[80:81], v[42:43], v[122:123], v[80:81]
	s_nop 0
	v_mul_f32_e32 v82, 0xbfb8aa3b, v80
	v_mul_f32_e32 v83, 0xbfb8aa3b, v81
	v_exp_f32_e32 v82, v82
	v_exp_f32_e32 v83, v83
	s_nop 0
	v_pk_add_f32 v[82:83], v[82:83], 1.0 op_sel_hi:[1,0]
	s_nop 0
	s_nop 0
	v_rcp_f32_e32 v83, v83
	s_nop 0
	v_rcp_f32_e32 v82, v82
	s_nop 0
	v_pk_mul_f32 v[184:185], v[80:81], v[82:83]
	v_pk_fma_f32 v[80:81], v[46:47], v[92:93], v[58:59]
	s_nop 0
	v_pk_fma_f32 v[80:81], v[50:51], v[120:121], v[80:81]
	s_nop 0
	v_pk_fma_f32 v[80:81], v[54:55], v[122:123], v[80:81]
	s_nop 0
	v_pk_fma_f32 v[80:81], v[42:43], v[124:125], v[80:81]
	s_nop 0
	v_mul_f32_e32 v82, 0xbfb8aa3b, v80
	v_mul_f32_e32 v83, 0xbfb8aa3b, v81
	v_exp_f32_e32 v82, v82
	v_exp_f32_e32 v83, v83
	s_nop 0
	v_pk_add_f32 v[82:83], v[82:83], 1.0 op_sel_hi:[1,0]
	s_nop 0
	s_nop 0
	v_rcp_f32_e32 v83, v83
	s_nop 0
	v_rcp_f32_e32 v82, v82
	s_nop 0
	v_pk_mul_f32 v[194:195], v[80:81], v[82:83]

; DI float lo16(unsigned w) { return __uint_as_float(w << 16); }
; DI float hi16(unsigned w) { return __uint_as_float(w & 0xffff0000u); }
; DI void conv_row8(const u32x4 (&raw)[11], int i, const float (&w)[4][8], const float (&bias)[8], float (&v)[8]) {
; #pragma unroll
;     for (int e = 0; e < 8; ++e) v[e] = bias[e];
; #pragma unroll
;     for (int jj = 0; jj < 4; ++jj) {
; #pragma unroll
;         for (int e = 0; e < 4; ++e) { v[2 * e] += w[jj][2 * e] * lo16(raw[i + jj][e]); v[2 * e + 1] += w[jj][2 * e + 1] * hi16(raw[i + jj][e]); }
;     }
; #pragma unroll
;     for (int e = 0; e < 8; ++e) v[e] = v[e] * __frcp_rn(1.0f + __expf(-v[e]));
; }
.LBB0_308:
	s_and_b64 vcc, exec, s[52:53]
	v_lshlrev_b32_e32 v174, 16, v84
	v_and_b32_e32 v175, 0xffff0000, v84
	v_lshlrev_b32_e32 v186, 16, v88
	v_and_b32_e32 v187, 0xffff0000, v88
	v_lshlrev_b32_e32 v168, 16, v85
	v_and_b32_e32 v169, 0xffff0000, v85
	v_lshlrev_b32_e32 v170, 16, v89
	v_and_b32_e32 v171, 0xffff0000, v89
	v_lshlrev_b32_e32 v126, 16, v86
	v_and_b32_e32 v127, 0xffff0000, v86
	v_lshlrev_b32_e32 v130, 16, v90
	v_and_b32_e32 v131, 0xffff0000, v90
	v_lshlrev_b32_e32 v116, 16, v87
	v_and_b32_e32 v117, 0xffff0000, v87
	v_lshlrev_b32_e32 v118, 16, v91
	v_and_b32_e32 v119, 0xffff0000, v91
	s_cbranch_vccnz .LBB0_310
	v_pk_fma_f32 v[80:81], v[100:101], v[156:157], v[112:113]
	s_nop 0
	v_pk_fma_f32 v[80:81], v[104:105], v[192:193], v[80:81]
	s_nop 0
	v_pk_fma_f32 v[80:81], v[108:109], v[164:165], v[80:81]
	s_nop 0
	v_pk_fma_f32 v[80:81], v[60:61], v[174:175], v[80:81]
	s_nop 0
	v_mul_f32_e32 v82, 0xbfb8aa3b, v80
	v_mul_f32_e32 v83, 0xbfb8aa3b, v81
	v_exp_f32_e32 v82, v82
	v_exp_f32_e32 v83, v83
	s_nop 0
	v_pk_add_f32 v[82:83], v[82:83], 1.0 op_sel_hi:[1,0]
	s_nop 0
	s_nop 0
	v_rcp_f32_e32 v83, v83
	s_nop 0
	v_rcp_f32_e32 v82, v82
	s_nop 0
	v_pk_mul_f32 v[144:145], v[80:81], v[82:83]
	v_pk_fma_f32 v[80:81], v[100:101], v[192:193], v[112:113]
	s_nop 0
	v_pk_fma_f32 v[80:81], v[104:105], v[164:165], v[80:81]
	s_nop 0
	v_pk_fma_f32 v[80:81], v[108:109], v[174:175], v[80:81]
	s_nop 0
	v_pk_fma_f32 v[80:81], v[60:61], v[186:187], v[80:81]
	s_nop 0
	v_mul_f32_e32 v82, 0xbfb8aa3b, v80
	v_mul_f32_e32 v83, 0xbfb8aa3b, v81
	v_exp_f32_e32 v82, v82
	v_exp_f32_e32 v83, v83
	s_nop 0
	v_pk_add_f32 v[82:83], v[82:83], 1.0 op_sel_hi:[1,0]
	s_nop 0
	s_nop 0
	v_rcp_f32_e32 v83, v83
	s_nop 0
	v_rcp_f32_e32 v82, v82
	s_nop 0
	v_pk_mul_f32 v[146:147], v[80:81], v[82:83]
	v_pk_fma_f32 v[80:81], v[102:103], v[154:155], v[114:115]
	s_nop 0
	v_pk_fma_f32 v[80:81], v[106:107], v[188:189], v[80:81]
	s_nop 0
	v_pk_fma_f32 v[80:81], v[110:111], v[162:163], v[80:81]
	s_nop 0
	v_pk_fma_f32 v[80:81], v[62:63], v[168:169], v[80:81]
	s_nop 0
	v_mul_f32_e32 v82, 0xbfb8aa3b, v80
	v_mul_f32_e32 v83, 0xbfb8aa3b, v81
	v_exp_f32_e32 v82, v82
	v_exp_f32_e32 v83, v83
	s_nop 0
	v_pk_add_f32 v[82:83], v[82:83], 1.0 op_sel_hi:[1,0]
	s_nop 0
	s_nop 0
	v_rcp_f32_e32 v83, v83
	s_nop 0
	v_rcp_f32_e32 v82, v82
	s_nop 0
	v_pk_mul_f32 v[148:149], v[80:81], v[82:83]
	v_pk_fma_f32 v[80:81], v[102:103], v[188:189], v[114:115]
	s_nop 0
	v_pk_fma_f32 v[80:81], v[106:107], v[162:163], v[80:81]
	s_nop 0
	v_pk_fma_f32 v[80:81], v[110:111], v[168:169], v[80:81]
	s_nop 0
	v_pk_fma_f32 v[80:81], v[62:63], v[170:171], v[80:81]
	s_nop 0
	v_mul_f32_e32 v82, 0xbfb8aa3b, v80
	v_mul_f32_e32 v83, 0xbfb8aa3b, v81
	v_exp_f32_e32 v82, v82
	v_exp_f32_e32 v83, v83
	s_nop 0
	v_pk_add_f32 v[82:83], v[82:83], 1.0 op_sel_hi:[1,0]
	s_nop 0
	s_nop 0
	v_rcp_f32_e32 v83, v83
	s_nop 0
	v_rcp_f32_e32 v82, v82
	s_nop 0
	v_pk_mul_f32 v[150:151], v[80:81], v[82:83]
	v_pk_fma_f32 v[80:81], v[44:45], v[152:153], v[56:57]
	s_nop 0
	v_pk_fma_f32 v[80:81], v[48:49], v[172:173], v[80:81]
	s_nop 0
	v_pk_fma_f32 v[80:81], v[52:53], v[128:129], v[80:81]
	s_nop 0
	v_pk_fma_f32 v[80:81], v[40:41], v[126:127], v[80:81]
	s_nop 0
	v_mul_f32_e32 v82, 0xbfb8aa3b, v80
	v_mul_f32_e32 v83, 0xbfb8aa3b, v81
	v_exp_f32_e32 v82, v82
	v_exp_f32_e32 v83, v83
	s_nop 0
	v_pk_add_f32 v[82:83], v[82:83], 1.0 op_sel_hi:[1,0]
	s_nop 0
	s_nop 0
	v_rcp_f32_e32 v83, v83
	s_nop 0
	v_rcp_f32_e32 v82, v82
	s_nop 0
	v_pk_mul_f32 v[158:159], v[80:81], v[82:83]
	v_pk_fma_f32 v[80:81], v[44:45], v[172:173], v[56:57]
	s_nop 0
	v_pk_fma_f32 v[80:81], v[48:49], v[128:129], v[80:81]
	s_nop 0
	v_pk_fma_f32 v[80:81], v[52:53], v[126:127], v[80:81]
	s_nop 0
	v_pk_fma_f32 v[80:81], v[40:41], v[130:131], v[80:81]
	s_nop 0
	v_mul_f32_e32 v82, 0xbfb8aa3b, v80
	v_mul_f32_e32 v83, 0xbfb8aa3b, v81
	v_exp_f32_e32 v82, v82
	v_exp_f32_e32 v83, v83
	s_nop 0
	v_pk_add_f32 v[82:83], v[82:83], 1.0 op_sel_hi:[1,0]
	s_nop 0
	s_nop 0
	v_rcp_f32_e32 v83, v83
	s_nop 0
	v_rcp_f32_e32 v82, v82
	s_nop 0
	v_pk_mul_f32 v[166:167], v[80:81], v[82:83]
	v_pk_fma_f32 v[80:81], v[46:47], v[120:121], v[58:59]
	s_nop 0
	v_pk_fma_f32 v[80:81], v[50:51], v[122:123], v[80:81]
	s_nop 0
	v_pk_fma_f32 v[80:81], v[54:55], v[124:125], v[80:81]
	s_nop 0
	v_pk_fma_f32 v[80:81], v[42:43], v[116:117], v[80:81]
	s_nop 0
	v_mul_f32_e32 v82, 0xbfb8aa3b, v80
	v_mul_f32_e32 v83, 0xbfb8aa3b, v81
	v_exp_f32_e32 v82, v82
	v_exp_f32_e32 v83, v83
	s_nop 0
	v_pk_add_f32 v[82:83], v[82:83], 1.0 op_sel_hi:[1,0]
	s_nop 0
	s_nop 0
	v_rcp_f32_e32 v83, v83
	s_nop 0
	v_rcp_f32_e32 v82, v82
	s_nop 0
	v_pk_mul_f32 v[184:185], v[80:81], v[82:83]
	v_pk_fma_f32 v[80:81], v[46:47], v[122:123], v[58:59]
	s_nop 0
	v_pk_fma_f32 v[80:81], v[50:51], v[124:125], v[80:81]
	s_nop 0
	v_pk_fma_f32 v[80:81], v[54:55], v[116:117], v[80:81]
	s_nop 0
	v_pk_fma_f32 v[80:81], v[42:43], v[118:119], v[80:81]
	s_nop 0
	v_mul_f32_e32 v82, 0xbfb8aa3b, v80
	v_mul_f32_e32 v83, 0xbfb8aa3b, v81
	v_exp_f32_e32 v82, v82
	v_exp_f32_e32 v83, v83
	s_nop 0
	v_pk_add_f32 v[82:83], v[82:83], 1.0 op_sel_hi:[1,0]
	s_nop 0
	s_nop 0
	v_rcp_f32_e32 v83, v83
	s_nop 0
	v_rcp_f32_e32 v82, v82
	s_nop 0
	v_pk_mul_f32 v[194:195], v[80:81], v[82:83]

; DI float lo16(unsigned w) { return __uint_as_float(w << 16); }
; DI float hi16(unsigned w) { return __uint_as_float(w & 0xffff0000u); }
; DI void conv_row8(const u32x4 (&raw)[11], int i, const float (&w)[4][8], const float (&bias)[8], float (&v)[8]) {
; #pragma unroll
;     for (int e = 0; e < 8; ++e) v[e] = bias[e];
; #pragma unroll
;     for (int jj = 0; jj < 4; ++jj) {
; #pragma unroll
;         for (int e = 0; e < 4; ++e) { v[2 * e] += w[jj][2 * e] * lo16(raw[i + jj][e]); v[2 * e + 1] += w[jj][2 * e + 1] * hi16(raw[i + jj][e]); }
;     }
; #pragma unroll
;     for (int e = 0; e < 8; ++e) v[e] = v[e] * __frcp_rn(1.0f + __expf(-v[e]));
; }
.LBB0_319:
	s_and_b64 vcc, exec, s[52:53]
	s_cbranch_vccnz .LBB0_321
	v_pk_fma_f32 v[36:37], v[100:101], v[164:165], v[112:113]
	s_waitcnt lgkmcnt(0)
	v_lshlrev_b32_e32 v32, 16, v68
	v_pk_fma_f32 v[36:37], v[104:105], v[174:175], v[36:37]
	v_and_b32_e32 v33, 0xffff0000, v68
	v_pk_fma_f32 v[36:37], v[108:109], v[186:187], v[36:37]
	s_nop 0
	v_pk_fma_f32 v[36:37], v[60:61], v[32:33], v[36:37]
	s_nop 0
	v_mul_f32_e32 v68, 0xbfb8aa3b, v36
	v_exp_f32_e32 v84, v68
	v_mul_f32_e32 v68, 0xbfb8aa3b, v37
	v_exp_f32_e32 v85, v68
	s_nop 0
	v_pk_add_f32 v[84:85], v[84:85], 1.0 op_sel_hi:[1,0]
	s_nop 0
	s_nop 0
	v_rcp_f32_e32 v85, v85
	s_nop 0
	v_rcp_f32_e32 v84, v84
	s_nop 0
	v_pk_mul_f32 v[144:145], v[36:37], v[84:85]
	v_pk_fma_f32 v[36:37], v[100:101], v[174:175], v[112:113]
	s_nop 0
	v_pk_fma_f32 v[36:37], v[104:105], v[186:187], v[36:37]
	s_nop 0
	v_pk_fma_f32 v[32:33], v[108:109], v[32:33], v[36:37]
	v_lshlrev_b32_e32 v36, 16, v64
	v_and_b32_e32 v37, 0xffff0000, v64
	v_pk_fma_f32 v[32:33], v[60:61], v[36:37], v[32:33]
	s_nop 0
	v_mul_f32_e32 v36, 0xbfb8aa3b, v32
	v_mul_f32_e32 v37, 0xbfb8aa3b, v33
	v_exp_f32_e32 v36, v36
	v_exp_f32_e32 v37, v37
	s_nop 0
	v_pk_add_f32 v[36:37], v[36:37], 1.0 op_sel_hi:[1,0]
	s_nop 0
	s_nop 0
	v_rcp_f32_e32 v37, v37
	s_nop 0
	v_rcp_f32_e32 v36, v36
	s_nop 0
	v_pk_mul_f32 v[146:147], v[32:33], v[36:37]
	v_pk_fma_f32 v[36:37], v[102:103], v[162:163], v[114:115]
	v_lshlrev_b32_e32 v32, 16, v69
	v_pk_fma_f32 v[36:37], v[106:107], v[168:169], v[36:37]
	v_and_b32_e32 v33, 0xffff0000, v69
	v_pk_fma_f32 v[36:37], v[110:111], v[170:171], v[36:37]
	s_nop 0
	v_pk_fma_f32 v[36:37], v[62:63], v[32:33], v[36:37]
	s_nop 0
	v_mul_f32_e32 v60, 0xbfb8aa3b, v36
	v_mul_f32_e32 v61, 0xbfb8aa3b, v37
	v_exp_f32_e32 v60, v60
	v_exp_f32_e32 v61, v61
	s_nop 0
	v_pk_add_f32 v[60:61], v[60:61], 1.0 op_sel_hi:[1,0]
	s_nop 0
	s_nop 0
	v_rcp_f32_e32 v61, v61
	s_nop 0
	v_rcp_f32_e32 v60, v60
	s_nop 0
	v_pk_mul_f32 v[148:149], v[36:37], v[60:61]
	v_pk_fma_f32 v[36:37], v[102:103], v[168:169], v[114:115]
	s_nop 0
	v_pk_fma_f32 v[36:37], v[106:107], v[170:171], v[36:37]
	s_nop 0
	v_pk_fma_f32 v[32:33], v[110:111], v[32:33], v[36:37]
	v_lshlrev_b32_e32 v36, 16, v65
	v_and_b32_e32 v37, 0xffff0000, v65
	v_pk_fma_f32 v[32:33], v[62:63], v[36:37], v[32:33]
	s_nop 0
	v_mul_f32_e32 v36, 0xbfb8aa3b, v32
	v_mul_f32_e32 v37, 0xbfb8aa3b, v33
	v_exp_f32_e32 v36, v36
	v_exp_f32_e32 v37, v37
	s_nop 0
	v_pk_add_f32 v[36:37], v[36:37], 1.0 op_sel_hi:[1,0]
	s_nop 0
	s_nop 0
	v_rcp_f32_e32 v37, v37
	s_nop 0
	v_rcp_f32_e32 v36, v36
	s_nop 0
	v_pk_mul_f32 v[150:151], v[32:33], v[36:37]
	v_pk_fma_f32 v[36:37], v[44:45], v[128:129], v[56:57]
	v_lshlrev_b32_e32 v32, 16, v70
	v_pk_fma_f32 v[36:37], v[48:49], v[126:127], v[36:37]
	v_and_b32_e32 v33, 0xffff0000, v70
	v_pk_fma_f32 v[36:37], v[52:53], v[130:131], v[36:37]
	s_nop 0
	v_pk_fma_f32 v[36:37], v[40:41], v[32:33], v[36:37]
	s_nop 0
	v_mul_f32_e32 v60, 0xbfb8aa3b, v36
	v_mul_f32_e32 v61, 0xbfb8aa3b, v37
	v_exp_f32_e32 v60, v60
	v_exp_f32_e32 v61, v61
	s_nop 0
	v_pk_add_f32 v[60:61], v[60:61], 1.0 op_sel_hi:[1,0]
	s_nop 0
	s_nop 0
	v_rcp_f32_e32 v61, v61
	s_nop 0
	v_rcp_f32_e32 v60, v60
	s_nop 0
	v_pk_mul_f32 v[158:159], v[36:37], v[60:61]
	v_pk_fma_f32 v[36:37], v[44:45], v[126:127], v[56:57]
	s_nop 0
	v_pk_fma_f32 v[36:37], v[48:49], v[130:131], v[36:37]
	s_nop 0
	v_pk_fma_f32 v[32:33], v[52:53], v[32:33], v[36:37]
	v_lshlrev_b32_e32 v36, 16, v66
	v_and_b32_e32 v37, 0xffff0000, v66
	v_pk_fma_f32 v[32:33], v[40:41], v[36:37], v[32:33]
	s_nop 0
	v_mul_f32_e32 v36, 0xbfb8aa3b, v32
	v_mul_f32_e32 v37, 0xbfb8aa3b, v33
	v_exp_f32_e32 v36, v36
	v_exp_f32_e32 v37, v37
	s_nop 0
	v_pk_add_f32 v[36:37], v[36:37], 1.0 op_sel_hi:[1,0]
	s_nop 0
	s_nop 0
	v_rcp_f32_e32 v37, v37
	s_nop 0
	v_rcp_f32_e32 v36, v36
	s_nop 0
	v_pk_mul_f32 v[166:167], v[32:33], v[36:37]
	v_pk_fma_f32 v[36:37], v[46:47], v[124:125], v[58:59]
	v_lshlrev_b32_e32 v32, 16, v71
	v_pk_fma_f32 v[36:37], v[50:51], v[116:117], v[36:37]
	v_and_b32_e32 v33, 0xffff0000, v71
	v_pk_fma_f32 v[36:37], v[54:55], v[118:119], v[36:37]
	s_nop 0
	v_pk_fma_f32 v[36:37], v[42:43], v[32:33], v[36:37]
	s_nop 0
	v_mul_f32_e32 v40, 0xbfb8aa3b, v36
	v_mul_f32_e32 v41, 0xbfb8aa3b, v37
	v_exp_f32_e32 v40, v40
	v_exp_f32_e32 v41, v41
	s_nop 0
	v_pk_add_f32 v[40:41], v[40:41], 1.0 op_sel_hi:[1,0]
	s_nop 0
	s_nop 0
	v_rcp_f32_e32 v41, v41
	s_nop 0
	v_rcp_f32_e32 v40, v40
	s_nop 0
	v_pk_mul_f32 v[184:185], v[36:37], v[40:41]
	v_pk_fma_f32 v[36:37], v[46:47], v[116:117], v[58:59]
	s_nop 0
	v_pk_fma_f32 v[36:37], v[50:51], v[118:119], v[36:37]
	s_nop 0
	v_pk_fma_f32 v[32:33], v[54:55], v[32:33], v[36:37]
	v_lshlrev_b32_e32 v36, 16, v67
	v_and_b32_e32 v37, 0xffff0000, v67
	v_pk_fma_f32 v[32:33], v[42:43], v[36:37], v[32:33]
	s_nop 0
	v_mul_f32_e32 v36, 0xbfb8aa3b, v32
	v_mul_f32_e32 v37, 0xbfb8aa3b, v33
	v_exp_f32_e32 v36, v36
	v_exp_f32_e32 v37, v37
	s_nop 0
	v_pk_add_f32 v[36:37], v[36:37], 1.0 op_sel_hi:[1,0]
	s_nop 0
	s_nop 0
	v_rcp_f32_e32 v37, v37
	s_nop 0
	v_rcp_f32_e32 v36, v36
	s_nop 0
	v_pk_mul_f32 v[194:195], v[32:33], v[36:37]

; DI float lo16(unsigned w) { return __uint_as_float(w << 16); }
; DI float hi16(unsigned w) { return __uint_as_float(w & 0xffff0000u); }
; DI float rowscale(const float* ss, int row) {
;     const f32x4* p = (const f32x4*)(ss + (size_t)row * 16);
;     const f32x4 a = p[0], b = p[1], c = p[2], d = p[3];
;     const float s = (((a.x + a.y) + (a.z + a.w)) + ((b.x + b.y) + (b.z + b.w))) + (((c.x + c.y) + (c.z + c.w)) + ((d.x + d.y) + (d.z + d.w)));
;     return rsqrtf(s * (1.0f / 1024.0f) + EPS);
; }
; DI void rowscales8(const float* ss, int rowbase, int fr, int fq, float (&r)[2][4]) {
;     const int lane = fq * 16 + fr;
;     const float rA = rowscale(ss, rowbase + lane), rB = rowscale(ss, rowbase + 128 + lane);
; #pragma unroll
;     for (int m = 0; m < 4; ++m) { r[0][m] = __shfl(rA, m * 16 + fr); r[1][m] = __shfl(rB, m * 16 + fr); }
; }
;     DI void operator()(const pg8::f32x4 (&acc)[2][2][4][2], const pg8::Unit& u, int wr, int wc, int fr, int fq) const {
;     ...
;                 const int row = row0 + ai * 128 + m * 16; const float r = rs[ai][m];
;                 float part = 0.f;
; #pragma unroll
;                 for (int bj = 0; bj < 2; ++bj) { const size_t off = (size_t)row * 1024 + col0 + bj * 128;
;                     const u32x4 tw = *(const u32x4*)(T + off); const u32x4 xw = *(const u32x4*)(xr + off);
;                     const pg8::f32x4 a0 = acc[ai][bj][m][0] * r, a1 = acc[ai][bj][m][1] * r;
;                     const float o0 = lo16(xw.x) + lo16(tw.x) * __frcp_rn(1.0f + __expf(-a0[0])), o1 = hi16(xw.x) + hi16(tw.x) * __frcp_rn(1.0f + __expf(-a0[1]));
.LBB0_470:
	s_lshl_b32 s1, s2, 8
	s_add_i32 s1, s1, s80
	v_or_b32_e32 v154, s1, v139
	v_ashrrev_i32_e32 v155, 31, v154
	v_lshlrev_b64 v[154:155], 6, v[154:155]
	v_lshl_add_u64 v[158:159], s[8:9], 0, v[154:155]
	global_load_dwordx4 v[154:157], v[158:159], off offset:16
	global_load_dwordx4 v[162:165], v[158:159], off offset:48
	global_load_dwordx4 v[166:169], v[158:159], off
	global_load_dwordx4 v[170:173], v[158:159], off offset:32
	s_mov_b32 s2, 0x3a800000
	v_or_b32_e32 v142, s1, v145
	v_lshl_or_b32 v140, s0, 8, v149
	s_waitcnt vmcnt(0)
	v_mov_b32_e32 v158, v166
	v_mov_b32_e32 v159, v170
	v_mov_b32_e32 v170, v167
	v_mov_b32_e32 v166, v168
	v_mov_b32_e32 v167, v172
	v_mov_b32_e32 v172, v169
	v_pk_add_f32 v[158:159], v[158:159], v[170:171]
	v_pk_add_f32 v[166:167], v[166:167], v[172:173]
	s_nop 0
	v_pk_add_f32 v[158:159], v[158:159], v[166:167]
	v_mov_b32_e32 v166, v154
	v_mov_b32_e32 v167, v162
	v_mov_b32_e32 v162, v155
	v_pk_add_f32 v[154:155], v[166:167], v[162:163]
	v_mov_b32_e32 v162, v156
	v_mov_b32_e32 v163, v164
	v_mov_b32_e32 v164, v157
	v_pk_add_f32 v[156:157], v[162:163], v[164:165]
	s_nop 0
	v_pk_add_f32 v[154:155], v[154:155], v[156:157]
	s_nop 0
	v_pk_add_f32 v[158:159], v[158:159], v[154:155]
	v_add_u32_e32 v154, s1, v151
	v_ashrrev_i32_e32 v155, 31, v154
	v_lshlrev_b64 v[154:155], 6, v[154:155]
	v_lshl_add_u64 v[170:171], s[8:9], 0, v[154:155]
	global_load_dwordx4 v[154:157], v[170:171], off offset:16
	global_load_dwordx4 v[162:165], v[170:171], off offset:48
	global_load_dwordx4 v[166:169], v[170:171], off
	s_nop 0
	global_load_dwordx4 v[170:173], v[170:171], off offset:32
	s_waitcnt vmcnt(1)
	v_mov_b32_e32 v174, v166
	s_waitcnt vmcnt(0)
	v_mov_b32_e32 v175, v170
	v_mov_b32_e32 v170, v167
	v_pk_add_f32 v[166:167], v[174:175], v[170:171]
	v_mov_b32_e32 v170, v168
	v_mov_b32_e32 v171, v172
	v_mov_b32_e32 v172, v169
	v_pk_add_f32 v[168:169], v[170:171], v[172:173]
	s_nop 0
	v_pk_add_f32 v[166:167], v[166:167], v[168:169]
	v_mov_b32_e32 v168, v154
	v_mov_b32_e32 v169, v162
	v_mov_b32_e32 v162, v155
	v_pk_add_f32 v[154:155], v[168:169], v[162:163]
	v_mov_b32_e32 v162, v156
	v_mov_b32_e32 v163, v164
	v_mov_b32_e32 v164, v157
	v_pk_add_f32 v[156:157], v[162:163], v[164:165]
	s_nop 0
	v_pk_add_f32 v[154:155], v[154:155], v[156:157]
	v_mov_b32_e32 v157, v158
	v_pk_add_f32 v[154:155], v[166:167], v[154:155]
	s_nop 0
	v_mov_b32_e32 v156, v154
	v_mov_b32_e32 v158, v155
	v_pk_add_f32 v[154:155], v[156:157], v[158:159]
	s_nop 0
	v_pk_fma_f32 v[154:155], v[154:155], s[2:3], v[176:177] op_sel_hi:[1,0,0]
	s_nop 0
	v_mul_f32_e32 v138, 0x4b800000, v155
	v_cmp_gt_f32_e64 s[42:43], s39, v155
	v_cmp_gt_f32_e32 vcc, s39, v154
	s_nop 0
	v_cndmask_b32_e64 v138, v155, v138, s[42:43]
	v_rsq_f32_e32 v138, v138
	s_nop 0
	v_mul_f32_e32 v141, 0x45800000, v138
	v_cndmask_b32_e64 v138, v138, v141, s[42:43]
	v_mul_f32_e32 v141, 0x4b800000, v154
	v_cndmask_b32_e32 v141, v154, v141, vcc
	v_rsq_f32_e32 v141, v141
	s_lshl_b32 s42, s0, 2
	s_ashr_i32 s43, s42, 31
	v_mul_f32_e32 v143, 0x45800000, v141
	v_cndmask_b32_e32 v141, v141, v143, vcc
	v_and_b32_e32 v143, 64, v177
	v_or_b32_e32 v144, v143, v145
	v_lshlrev_b32_e32 v155, 2, v144
	ds_bpermute_b32 v168, v155, v138
	ds_bpermute_b32 v148, v155, v141
	ds_bpermute_b32 v154, v155, v138 offset:64
	ds_bpermute_b32 v146, v155, v141 offset:64
	ds_bpermute_b32 v152, v155, v138 offset:128
	ds_bpermute_b32 v144, v155, v141 offset:128
	ds_bpermute_b32 v150, v155, v138 offset:192
	ds_bpermute_b32 v138, v155, v141 offset:192
	v_xor_b32_e32 v155, 16, v177
	v_add_u32_e32 v143, 64, v143
	v_cmp_lt_i32_e32 vcc, v155, v143
	v_ashrrev_i32_e32 v141, 31, v140
	s_nop 0
	v_cndmask_b32_e32 v155, v177, v155, vcc
	v_lshlrev_b32_e32 v169, 2, v155
	v_xor_b32_e32 v155, 32, v177
	v_cmp_lt_i32_e32 vcc, v155, v143
	s_waitcnt lgkmcnt(7)
	v_pk_mul_f32 v[124:125], v[124:125], v[168:169] op_sel_hi:[1,0]
	v_pk_mul_f32 v[126:127], v[126:127], v[168:169] op_sel_hi:[1,0]
	v_cndmask_b32_e32 v143, v177, v155, vcc
	v_lshlrev_b32_e32 v155, 2, v143
	v_ashrrev_i32_e32 v143, 31, v142
	v_lshlrev_b64 v[156:157], 10, v[142:143]
	v_lshl_add_u64 v[156:157], v[156:157], 0, v[140:141]
	v_lshlrev_b64 v[158:159], 1, v[156:157]
	v_lshl_add_u64 v[156:157], s[18:19], 0, v[158:159]
	global_load_dwordx4 v[162:165], v[156:157], off
	v_lshl_add_u64 v[170:171], s[12:13], 0, v[158:159]
	global_load_dwordx4 v[172:175], v[170:171], off
	v_mul_f32_e32 v124, 0xbfb8aa3b, v124
	v_mul_f32_e32 v125, 0xbfb8aa3b, v125
	v_exp_f32_e32 v124, v124
	v_exp_f32_e32 v125, v125
	v_mul_f32_e32 v126, 0xbfb8aa3b, v126
	v_mul_f32_e32 v127, 0xbfb8aa3b, v127
	v_exp_f32_e32 v126, v126
	v_pk_add_f32 v[124:125], v[124:125], 1.0 op_sel_hi:[1,0]
	v_exp_f32_e32 v127, v127
	v_pk_mul_f32 v[120:121], v[120:121], v[168:169] op_sel_hi:[1,0]
	v_pk_mul_f32 v[122:123], v[122:123], v[168:169] op_sel_hi:[1,0]
	v_mul_f32_e32 v120, 0xbfb8aa3b, v120
	v_pk_add_f32 v[126:127], v[126:127], 1.0 op_sel_hi:[1,0]
	v_mul_f32_e32 v121, 0xbfb8aa3b, v121
	v_exp_f32_e32 v120, v120
	v_exp_f32_e32 v121, v121
	v_pk_mul_f32 v[116:117], v[116:117], v[168:169] op_sel_hi:[1,0]
	v_pk_mul_f32 v[118:119], v[118:119], v[168:169] op_sel_hi:[1,0]
	v_pk_mul_f32 v[114:115], v[114:115], v[168:169] op_sel_hi:[1,0]
	v_pk_add_f32 v[120:121], v[120:121], 1.0 op_sel_hi:[1,0]
	v_mul_f32_e32 v114, 0xbfb8aa3b, v114
	v_mul_f32_e32 v115, 0xbfb8aa3b, v115
	v_exp_f32_e32 v114, v114
	v_exp_f32_e32 v115, v115
	s_waitcnt vmcnt(1)
	v_lshlrev_b32_e32 v166, 16, v162
	v_and_b32_e32 v167, 0xffff0000, v162
	s_waitcnt vmcnt(0)
; DI unsigned pk2(float lo, float hi) { const f32x2_t v = {lo, hi}; const bf16x2_t b = __builtin_convertvector(v, bf16x2_t); return __builtin_bit_cast(unsigned, b); }
; DI float lo16(unsigned w) { return __uint_as_float(w << 16); }
; DI float hi16(unsigned w) { return __uint_as_float(w & 0xffff0000u); }
;     DI void operator()(const pg8::f32x4 (&acc)[2][2][4][2], const pg8::Unit& u, int wr, int wc, int fr, int fq) const {
;     ...
;                 for (int bj = 0; bj < 2; ++bj) { const size_t off = (size_t)row * 1024 + col0 + bj * 128;
;                     const u32x4 tw = *(const u32x4*)(T + off); const u32x4 xw = *(const u32x4*)(xr + off);
;                     const pg8::f32x4 a0 = acc[ai][bj][m][0] * r, a1 = acc[ai][bj][m][1] * r;
;                     const float o0 = lo16(xw.x) + lo16(tw.x) * __frcp_rn(1.0f + __expf(-a0[0])), o1 = hi16(xw.x) + hi16(tw.x) * __frcp_rn(1.0f + __expf(-a0[1]));
;                     const float o2 = lo16(xw.y) + lo16(tw.y) * __frcp_rn(1.0f + __expf(-a0[2])), o3 = hi16(xw.y) + hi16(tw.y) * __frcp_rn(1.0f + __expf(-a0[3]));
;                     const float o4 = lo16(xw.z) + lo16(tw.z) * __frcp_rn(1.0f + __expf(-a1[0])), o5 = hi16(xw.z) + hi16(tw.z) * __frcp_rn(1.0f + __expf(-a1[1]));
;                     const float o6 = lo16(xw.w) + lo16(tw.w) * __frcp_rn(1.0f + __expf(-a1[2])), o7 = hi16(xw.w) + hi16(tw.w) * __frcp_rn(1.0f + __expf(-a1[3]));
;                     u32x4 w; w.x = pk2(o0, o1); w.y = pk2(o2, o3); w.z = pk2(o4, o5); w.w = pk2(o6, o7); *(u32x4*)(xbo + off) = w;
;                     part += ((o0 * o0 + o1 * o1) + (o2 * o2 + o3 * o3)) + ((o4 * o4 + o5 * o5) + (o6 * o6 + o7 * o7)); }
;                 part += __shfl_xor(part, 16); part += __shfl_xor(part, 32);
;                 if (ssout && fq == 0) ssout[(size_t)row * 16 + u.pn * 4 + wc] = part;
	v_lshlrev_b32_e32 v158, 16, v172
	v_and_b32_e32 v159, 0xffff0000, v172
	v_pk_add_f32 v[114:115], v[114:115], 1.0 op_sel_hi:[1,0]
	v_rcp_f32_e32 v125, v125
	s_nop 0
	v_rcp_f32_e32 v124, v124
	s_nop 0
	v_pk_fma_f32 v[124:125], v[124:125], v[166:167], v[158:159]
	v_lshlrev_b32_e32 v158, 16, v173
	v_and_b32_e32 v159, 0xffff0000, v173
	v_lshlrev_b32_e32 v162, 16, v163
	v_rcp_f32_e32 v127, v127
	v_and_b32_e32 v163, 0xffff0000, v163
	v_rcp_f32_e32 v126, v126
	s_nop 0
	v_pk_fma_f32 v[126:127], v[126:127], v[162:163], v[158:159]
	v_lshlrev_b32_e32 v162, 16, v164
	v_and_b32_e32 v163, 0xffff0000, v164
	v_lshlrev_b32_e32 v158, 16, v174
	v_and_b32_e32 v159, 0xffff0000, v174
	v_rcp_f32_e32 v121, v121
	s_nop 0
	v_rcp_f32_e32 v120, v120
	s_nop 0
	v_pk_fma_f32 v[166:167], v[120:121], v[162:163], v[158:159]
	v_mul_f32_e32 v120, 0xbfb8aa3b, v122
	v_mul_f32_e32 v121, 0xbfb8aa3b, v123
	v_exp_f32_e32 v120, v120
	v_exp_f32_e32 v121, v121
	v_lshlrev_b32_e32 v158, 16, v165
	v_and_b32_e32 v159, 0xffff0000, v165
	v_lshlrev_b32_e32 v122, 16, v175
	v_pk_add_f32 v[120:121], v[120:121], 1.0 op_sel_hi:[1,0]
	v_and_b32_e32 v123, 0xffff0000, v175
	s_nop 0
	v_rcp_f32_e32 v121, v121
	s_nop 0
	v_rcp_f32_e32 v120, v120
	s_nop 0
	v_pk_fma_f32 v[172:173], v[120:121], v[158:159], v[122:123]
	v_cvt_pk_bf16_f32 v120, v124, v125
	v_cvt_pk_bf16_f32 v121, v126, v127
	v_cvt_pk_bf16_f32 v122, v166, v167
	v_cvt_pk_bf16_f32 v123, v172, v173
	global_store_dwordx4 v[156:157], v[120:123], off
	v_pk_mul_f32 v[158:159], v[124:125], v[124:125]
	v_pk_mul_f32 v[162:163], v[126:127], v[126:127]
	global_load_dwordx4 v[120:123], v[156:157], off offset:256
	global_load_dwordx4 v[124:127], v[170:171], off offset:256
	v_pk_mul_f32 v[170:171], v[112:113], v[168:169] op_sel_hi:[1,0]
	v_mul_f32_e32 v112, 0xbfb8aa3b, v116
	v_mul_f32_e32 v113, 0xbfb8aa3b, v117
	v_exp_f32_e32 v112, v112
	v_exp_f32_e32 v113, v113
	v_pk_mul_f32 v[164:165], v[166:167], v[166:167]
	v_pk_mul_f32 v[166:167], v[172:173], v[172:173]
	v_pk_add_f32 v[112:113], v[112:113], 1.0 op_sel_hi:[1,0]
	s_waitcnt vmcnt(1)
	v_lshlrev_b32_e32 v172, 16, v120
	v_and_b32_e32 v173, 0xffff0000, v120
	s_waitcnt vmcnt(0)
	v_lshlrev_b32_e32 v116, 16, v124
	v_and_b32_e32 v117, 0xffff0000, v124
	s_nop 0
	v_rcp_f32_e32 v113, v113
	s_nop 0
	v_rcp_f32_e32 v112, v112
	s_nop 0
	v_pk_fma_f32 v[112:113], v[112:113], v[172:173], v[116:117]
	v_mul_f32_e32 v116, 0xbfb8aa3b, v118
	v_mul_f32_e32 v117, 0xbfb8aa3b, v119
	v_exp_f32_e32 v116, v116
	v_exp_f32_e32 v117, v117
	v_lshlrev_b32_e32 v118, 16, v125
	v_and_b32_e32 v119, 0xffff0000, v125
	v_lshlrev_b32_e32 v120, 16, v121
	v_pk_add_f32 v[116:117], v[116:117], 1.0 op_sel_hi:[1,0]
	v_and_b32_e32 v121, 0xffff0000, v121
	s_nop 0
	v_rcp_f32_e32 v117, v117
	s_nop 0
	v_rcp_f32_e32 v116, v116
	s_nop 0
	v_pk_fma_f32 v[116:117], v[116:117], v[120:121], v[118:119]
	v_mul_f32_e32 v118, 0xbfb8aa3b, v170
	v_mul_f32_e32 v119, 0xbfb8aa3b, v171
	v_exp_f32_e32 v118, v118
	v_exp_f32_e32 v119, v119
	v_lshlrev_b32_e32 v124, 16, v122
	v_and_b32_e32 v125, 0xffff0000, v122
	v_lshlrev_b32_e32 v120, 16, v126
	v_pk_add_f32 v[118:119], v[118:119], 1.0 op_sel_hi:[1,0]
	v_and_b32_e32 v121, 0xffff0000, v126
	s_nop 0
	v_rcp_f32_e32 v119, v119
	s_nop 0
	v_rcp_f32_e32 v118, v118
	s_nop 0
	v_pk_fma_f32 v[124:125], v[118:119], v[124:125], v[120:121]
	v_lshlrev_b32_e32 v120, 16, v123
	v_and_b32_e32 v121, 0xffff0000, v123
	v_lshlrev_b32_e32 v118, 16, v127
	v_and_b32_e32 v119, 0xffff0000, v127
	v_rcp_f32_e32 v115, v115
	s_nop 0
	v_rcp_f32_e32 v114, v114
	s_nop 0
	v_pk_fma_f32 v[114:115], v[114:115], v[120:121], v[118:119]
	v_cvt_pk_bf16_f32 v118, v112, v113
	v_cvt_pk_bf16_f32 v119, v116, v117
	v_cvt_pk_bf16_f32 v120, v124, v125
	v_cvt_pk_bf16_f32 v121, v114, v115
	global_store_dwordx4 v[156:157], v[118:121], off offset:256
	v_pk_mul_f32 v[114:115], v[114:115], v[114:115]
	v_pk_mul_f32 v[112:113], v[112:113], v[112:113]
	v_pk_mul_f32 v[118:119], v[124:125], v[124:125]
	v_pk_mul_f32 v[116:117], v[116:117], v[116:117]
	v_add_f32_e32 v120, v166, v167
	v_add_f32_e32 v121, v164, v165
	v_add_f32_e32 v114, v114, v115
	v_add_f32_e32 v115, v118, v119
	v_add_f32_e32 v120, v121, v120
	v_add_f32_e32 v121, v162, v163
	v_add_f32_e32 v122, v158, v159
	v_add_f32_e32 v114, v115, v114
	v_add_f32_e32 v115, v116, v117
	v_add_f32_e32 v112, v112, v113
	v_add_f32_e32 v121, v122, v121
	v_add_f32_e32 v112, v112, v115
	v_add_f32_e32 v120, v121, v120
	v_add_f32_e32 v112, v112, v114
	v_add_f32_e32 v112, v120, v112
	ds_bpermute_b32 v113, v169, v112
	s_waitcnt lgkmcnt(0)
	v_add_f32_e32 v112, v112, v113
	ds_bpermute_b32 v113, v155, v112
	s_and_saveexec_b64 s[0:1], s[46:47]
	s_cbranch_execz .LBB0_472
	s_waitcnt lgkmcnt(0)
	v_add_f32_e32 v114, v112, v113
	v_lshlrev_b64 v[112:113], 6, v[142:143]
	v_lshl_add_u64 v[112:113], s[6:7], 0, v[112:113]
	v_lshl_add_u64 v[112:113], s[42:43], 2, v[112:113]
	s_lshl_b32 s94, s35, 2
	v_lshl_add_u64 v[112:113], v[112:113], 0, s[94:95]
	global_store_dword v[112:113], v114, off
; DI unsigned pk2(float lo, float hi) { const f32x2_t v = {lo, hi}; const bf16x2_t b = __builtin_convertvector(v, bf16x2_t); return __builtin_bit_cast(unsigned, b); }
; DI float lo16(unsigned w) { return __uint_as_float(w << 16); }
; DI float hi16(unsigned w) { return __uint_as_float(w & 0xffff0000u); }
;     DI void operator()(const pg8::f32x4 (&acc)[2][2][4][2], const pg8::Unit& u, int wr, int wc, int fr, int fq) const {
;     ...
;             for (int m = 0; m < 4; ++m) {
;                 const int row = row0 + ai * 128 + m * 16; const float r = rs[ai][m];
;                 float part = 0.f;
; #pragma unroll
;                 for (int bj = 0; bj < 2; ++bj) { const size_t off = (size_t)row * 1024 + col0 + bj * 128;
;                     const u32x4 tw = *(const u32x4*)(T + off); const u32x4 xw = *(const u32x4*)(xr + off);
;                     const pg8::f32x4 a0 = acc[ai][bj][m][0] * r, a1 = acc[ai][bj][m][1] * r;
;                     const float o0 = lo16(xw.x) + lo16(tw.x) * __frcp_rn(1.0f + __expf(-a0[0])), o1 = hi16(xw.x) + hi16(tw.x) * __frcp_rn(1.0f + __expf(-a0[1]));
;                     const float o2 = lo16(xw.y) + lo16(tw.y) * __frcp_rn(1.0f + __expf(-a0[2])), o3 = hi16(xw.y) + hi16(tw.y) * __frcp_rn(1.0f + __expf(-a0[3]));
;                     const float o4 = lo16(xw.z) + lo16(tw.z) * __frcp_rn(1.0f + __expf(-a1[0])), o5 = hi16(xw.z) + hi16(tw.z) * __frcp_rn(1.0f + __expf(-a1[1]));
;                     const float o6 = lo16(xw.w) + lo16(tw.w) * __frcp_rn(1.0f + __expf(-a1[2])), o7 = hi16(xw.w) + hi16(tw.w) * __frcp_rn(1.0f + __expf(-a1[3]));
;                     u32x4 w; w.x = pk2(o0, o1); w.y = pk2(o2, o3); w.z = pk2(o4, o5); w.w = pk2(o6, o7); *(u32x4*)(xbo + off) = w;
;                     part += ((o0 * o0 + o1 * o1) + (o2 * o2 + o3 * o3)) + ((o4 * o4 + o5 * o5) + (o6 * o6 + o7 * o7)); }
;                 part += __shfl_xor(part, 16); part += __shfl_xor(part, 32);
;                 if (ssout && fq == 0) ssout[(size_t)row * 16 + u.pn * 4 + wc] = part;
.LBB0_472:
	s_or_b64 exec, exec, s[0:1]
	v_or_b32_e32 v120, 16, v142
	v_ashrrev_i32_e32 v121, 31, v120
	s_waitcnt lgkmcnt(0)
	v_lshlrev_b64 v[112:113], 10, v[120:121]
	v_lshl_add_u64 v[112:113], v[112:113], 0, v[140:141]
	v_lshlrev_b64 v[116:117], 1, v[112:113]
	v_lshl_add_u64 v[122:123], s[18:19], 0, v[116:117]
	global_load_dwordx4 v[112:115], v[122:123], off
	v_lshl_add_u64 v[124:125], s[12:13], 0, v[116:117]
	global_load_dwordx4 v[116:119], v[124:125], off
	v_pk_mul_f32 v[108:109], v[108:109], v[154:155] op_sel_hi:[1,0]
	v_pk_mul_f32 v[126:127], v[104:105], v[154:155] op_sel_hi:[1,0]
	v_mul_f32_e32 v104, 0xbfb8aa3b, v108
	v_mul_f32_e32 v105, 0xbfb8aa3b, v109
	v_exp_f32_e32 v104, v104
	v_exp_f32_e32 v105, v105
	v_pk_mul_f32 v[110:111], v[110:111], v[154:155] op_sel_hi:[1,0]
	v_pk_mul_f32 v[106:107], v[106:107], v[154:155] op_sel_hi:[1,0]
	v_pk_mul_f32 v[100:101], v[100:101], v[154:155] op_sel_hi:[1,0]
	v_pk_add_f32 v[104:105], v[104:105], 1.0 op_sel_hi:[1,0]
	v_mul_f32_e32 v106, 0xbfb8aa3b, v106
	v_mul_f32_e32 v107, 0xbfb8aa3b, v107
	v_exp_f32_e32 v106, v106
	v_exp_f32_e32 v107, v107
	v_pk_mul_f32 v[102:103], v[102:103], v[154:155] op_sel_hi:[1,0]
	v_pk_mul_f32 v[98:99], v[98:99], v[154:155] op_sel_hi:[1,0]
	v_pk_add_f32 v[106:107], v[106:107], 1.0 op_sel_hi:[1,0]
	v_mul_f32_e32 v98, 0xbfb8aa3b, v98
	v_mul_f32_e32 v99, 0xbfb8aa3b, v99
	v_exp_f32_e32 v98, v98
	v_exp_f32_e32 v99, v99
	s_waitcnt vmcnt(1)
	v_lshlrev_b32_e32 v156, 16, v112
	v_and_b32_e32 v157, 0xffff0000, v112
	s_waitcnt vmcnt(0)
	v_lshlrev_b32_e32 v108, 16, v116
	v_and_b32_e32 v109, 0xffff0000, v116
	v_pk_add_f32 v[98:99], v[98:99], 1.0 op_sel_hi:[1,0]
	v_rcp_f32_e32 v105, v105
	s_nop 0
	v_rcp_f32_e32 v104, v104
	s_nop 0
	v_pk_fma_f32 v[104:105], v[104:105], v[156:157], v[108:109]
	v_mul_f32_e32 v108, 0xbfb8aa3b, v110
	v_mul_f32_e32 v109, 0xbfb8aa3b, v111
	v_exp_f32_e32 v108, v108
	v_exp_f32_e32 v109, v109
	v_lshlrev_b32_e32 v110, 16, v117
	v_and_b32_e32 v111, 0xffff0000, v117
	v_lshlrev_b32_e32 v112, 16, v113
	v_pk_add_f32 v[108:109], v[108:109], 1.0 op_sel_hi:[1,0]
	v_and_b32_e32 v113, 0xffff0000, v113
	s_nop 0
	v_rcp_f32_e32 v109, v109
	s_nop 0
	v_rcp_f32_e32 v108, v108
	s_nop 0
	v_pk_fma_f32 v[110:111], v[108:109], v[112:113], v[110:111]
	v_mul_f32_e32 v108, 0xbfb8aa3b, v126
	v_mul_f32_e32 v109, 0xbfb8aa3b, v127
	v_exp_f32_e32 v108, v108
	v_exp_f32_e32 v109, v109
	v_lshlrev_b32_e32 v116, 16, v114
	v_and_b32_e32 v117, 0xffff0000, v114
	v_lshlrev_b32_e32 v112, 16, v118
	v_pk_add_f32 v[108:109], v[108:109], 1.0 op_sel_hi:[1,0]
	v_and_b32_e32 v113, 0xffff0000, v118
	s_nop 0
	v_rcp_f32_e32 v109, v109
	s_nop 0
	v_rcp_f32_e32 v108, v108
	s_nop 0
	v_pk_fma_f32 v[116:117], v[108:109], v[116:117], v[112:113]
	v_lshlrev_b32_e32 v112, 16, v115
	v_and_b32_e32 v113, 0xffff0000, v115
	v_lshlrev_b32_e32 v108, 16, v119
	v_and_b32_e32 v109, 0xffff0000, v119
	v_rcp_f32_e32 v107, v107
	s_nop 0
	v_rcp_f32_e32 v106, v106
	s_nop 0
	v_pk_fma_f32 v[118:119], v[106:107], v[112:113], v[108:109]
	v_cvt_pk_bf16_f32 v106, v104, v105
	v_cvt_pk_bf16_f32 v107, v110, v111
	v_cvt_pk_bf16_f32 v108, v116, v117
	v_cvt_pk_bf16_f32 v109, v118, v119
	global_store_dwordx4 v[122:123], v[106:109], off
	v_pk_mul_f32 v[112:113], v[104:105], v[104:105]
	v_pk_mul_f32 v[114:115], v[110:111], v[110:111]
	global_load_dwordx4 v[104:107], v[122:123], off offset:256
	global_load_dwordx4 v[108:111], v[124:125], off offset:256
	v_pk_mul_f32 v[124:125], v[96:97], v[154:155] op_sel_hi:[1,0]
	v_mul_f32_e32 v96, 0xbfb8aa3b, v100
	v_mul_f32_e32 v97, 0xbfb8aa3b, v101
	v_exp_f32_e32 v96, v96
	v_exp_f32_e32 v97, v97
	v_pk_mul_f32 v[116:117], v[116:117], v[116:117]
	v_pk_mul_f32 v[118:119], v[118:119], v[118:119]
	v_pk_add_f32 v[96:97], v[96:97], 1.0 op_sel_hi:[1,0]
	s_waitcnt vmcnt(1)
	v_lshlrev_b32_e32 v126, 16, v104
	v_and_b32_e32 v127, 0xffff0000, v104
	s_waitcnt vmcnt(0)
	v_lshlrev_b32_e32 v100, 16, v108
	v_and_b32_e32 v101, 0xffff0000, v108
	s_nop 0
	v_rcp_f32_e32 v97, v97
	s_nop 0
	v_rcp_f32_e32 v96, v96
	s_nop 0
	v_pk_fma_f32 v[96:97], v[96:97], v[126:127], v[100:101]
	v_mul_f32_e32 v100, 0xbfb8aa3b, v102
	v_mul_f32_e32 v101, 0xbfb8aa3b, v103
	v_exp_f32_e32 v100, v100
	v_exp_f32_e32 v101, v101
	v_lshlrev_b32_e32 v102, 16, v109
	v_and_b32_e32 v103, 0xffff0000, v109
	v_lshlrev_b32_e32 v104, 16, v105
	v_pk_add_f32 v[100:101], v[100:101], 1.0 op_sel_hi:[1,0]
	v_and_b32_e32 v105, 0xffff0000, v105
	s_nop 0
	v_rcp_f32_e32 v101, v101
	s_nop 0
	v_rcp_f32_e32 v100, v100
	s_nop 0
	v_pk_fma_f32 v[100:101], v[100:101], v[104:105], v[102:103]
	v_mul_f32_e32 v102, 0xbfb8aa3b, v124
	v_mul_f32_e32 v103, 0xbfb8aa3b, v125
	v_exp_f32_e32 v102, v102
	v_exp_f32_e32 v103, v103
	v_lshlrev_b32_e32 v108, 16, v106
	v_and_b32_e32 v109, 0xffff0000, v106
	v_lshlrev_b32_e32 v104, 16, v110
	v_pk_add_f32 v[102:103], v[102:103], 1.0 op_sel_hi:[1,0]
	v_and_b32_e32 v105, 0xffff0000, v110
	s_nop 0
	v_rcp_f32_e32 v103, v103
	s_nop 0
	v_rcp_f32_e32 v102, v102
	s_nop 0
	v_pk_fma_f32 v[108:109], v[102:103], v[108:109], v[104:105]
	v_lshlrev_b32_e32 v104, 16, v107
	v_and_b32_e32 v105, 0xffff0000, v107
	v_lshlrev_b32_e32 v102, 16, v111
	v_and_b32_e32 v103, 0xffff0000, v111
	v_rcp_f32_e32 v99, v99
	s_nop 0
	v_rcp_f32_e32 v98, v98
	s_nop 0
	v_pk_fma_f32 v[98:99], v[98:99], v[104:105], v[102:103]
	v_cvt_pk_bf16_f32 v102, v96, v97
	v_cvt_pk_bf16_f32 v103, v100, v101
	v_cvt_pk_bf16_f32 v104, v108, v109
	v_cvt_pk_bf16_f32 v105, v98, v99
	global_store_dwordx4 v[122:123], v[102:105], off offset:256
	v_pk_mul_f32 v[98:99], v[98:99], v[98:99]
	v_pk_mul_f32 v[96:97], v[96:97], v[96:97]
	v_pk_mul_f32 v[102:103], v[108:109], v[108:109]
	v_pk_mul_f32 v[100:101], v[100:101], v[100:101]
	v_add_f32_e32 v104, v118, v119
	v_add_f32_e32 v105, v116, v117
	v_add_f32_e32 v98, v98, v99
	v_add_f32_e32 v99, v102, v103
	v_add_f32_e32 v104, v105, v104
	v_add_f32_e32 v105, v114, v115
	v_add_f32_e32 v106, v112, v113
	v_add_f32_e32 v98, v99, v98
	v_add_f32_e32 v99, v100, v101
	v_add_f32_e32 v96, v96, v97
	v_add_f32_e32 v105, v106, v105
	v_add_f32_e32 v96, v96, v99
	v_add_f32_e32 v104, v105, v104
	v_add_f32_e32 v96, v96, v98
	v_add_f32_e32 v96, v104, v96
	ds_bpermute_b32 v97, v169, v96
	s_waitcnt lgkmcnt(0)
	v_add_f32_e32 v96, v96, v97
	ds_bpermute_b32 v97, v155, v96
	s_and_saveexec_b64 s[0:1], s[46:47]
	s_cbranch_execz .LBB0_474
	s_waitcnt lgkmcnt(0)
	v_add_f32_e32 v98, v96, v97
	v_lshlrev_b64 v[96:97], 6, v[120:121]
	v_lshl_add_u64 v[96:97], s[6:7], 0, v[96:97]
	v_lshl_add_u64 v[96:97], s[42:43], 2, v[96:97]
	s_lshl_b32 s94, s35, 2
	v_lshl_add_u64 v[96:97], v[96:97], 0, s[94:95]
	global_store_dword v[96:97], v98, off
; DI unsigned pk2(float lo, float hi) { const f32x2_t v = {lo, hi}; const bf16x2_t b = __builtin_convertvector(v, bf16x2_t); return __builtin_bit_cast(unsigned, b); }
; DI float lo16(unsigned w) { return __uint_as_float(w << 16); }
; DI float hi16(unsigned w) { return __uint_as_float(w & 0xffff0000u); }
;     DI void operator()(const pg8::f32x4 (&acc)[2][2][4][2], const pg8::Unit& u, int wr, int wc, int fr, int fq) const {
;     ...
;             for (int m = 0; m < 4; ++m) {
;                 const int row = row0 + ai * 128 + m * 16; const float r = rs[ai][m];
;                 float part = 0.f;
; #pragma unroll
;                 for (int bj = 0; bj < 2; ++bj) { const size_t off = (size_t)row * 1024 + col0 + bj * 128;
;                     const u32x4 tw = *(const u32x4*)(T + off); const u32x4 xw = *(const u32x4*)(xr + off);
;                     const pg8::f32x4 a0 = acc[ai][bj][m][0] * r, a1 = acc[ai][bj][m][1] * r;
;                     const float o0 = lo16(xw.x) + lo16(tw.x) * __frcp_rn(1.0f + __expf(-a0[0])), o1 = hi16(xw.x) + hi16(tw.x) * __frcp_rn(1.0f + __expf(-a0[1]));
;                     const float o2 = lo16(xw.y) + lo16(tw.y) * __frcp_rn(1.0f + __expf(-a0[2])), o3 = hi16(xw.y) + hi16(tw.y) * __frcp_rn(1.0f + __expf(-a0[3]));
;                     const float o4 = lo16(xw.z) + lo16(tw.z) * __frcp_rn(1.0f + __expf(-a1[0])), o5 = hi16(xw.z) + hi16(tw.z) * __frcp_rn(1.0f + __expf(-a1[1]));
;                     const float o6 = lo16(xw.w) + lo16(tw.w) * __frcp_rn(1.0f + __expf(-a1[2])), o7 = hi16(xw.w) + hi16(tw.w) * __frcp_rn(1.0f + __expf(-a1[3]));
;                     u32x4 w; w.x = pk2(o0, o1); w.y = pk2(o2, o3); w.z = pk2(o4, o5); w.w = pk2(o6, o7); *(u32x4*)(xbo + off) = w;
;                     part += ((o0 * o0 + o1 * o1) + (o2 * o2 + o3 * o3)) + ((o4 * o4 + o5 * o5) + (o6 * o6 + o7 * o7)); }
;                 part += __shfl_xor(part, 16); part += __shfl_xor(part, 32);
;                 if (ssout && fq == 0) ssout[(size_t)row * 16 + u.pn * 4 + wc] = part;
.LBB0_474:
	s_or_b64 exec, exec, s[0:1]
	v_or_b32_e32 v104, 32, v142
	v_ashrrev_i32_e32 v105, 31, v104
	s_waitcnt lgkmcnt(0)
	v_lshlrev_b64 v[96:97], 10, v[104:105]
	v_lshl_add_u64 v[96:97], v[96:97], 0, v[140:141]
	v_lshlrev_b64 v[100:101], 1, v[96:97]
	v_lshl_add_u64 v[106:107], s[18:19], 0, v[100:101]
	global_load_dwordx4 v[96:99], v[106:107], off
	v_lshl_add_u64 v[108:109], s[12:13], 0, v[100:101]
	global_load_dwordx4 v[100:103], v[108:109], off
	v_pk_mul_f32 v[92:93], v[92:93], v[152:153] op_sel_hi:[1,0]
	v_pk_mul_f32 v[110:111], v[88:89], v[152:153] op_sel_hi:[1,0]
	v_mul_f32_e32 v88, 0xbfb8aa3b, v92
	v_mul_f32_e32 v89, 0xbfb8aa3b, v93
	v_exp_f32_e32 v88, v88
	v_exp_f32_e32 v89, v89
	v_pk_mul_f32 v[94:95], v[94:95], v[152:153] op_sel_hi:[1,0]
	v_pk_mul_f32 v[90:91], v[90:91], v[152:153] op_sel_hi:[1,0]
	v_pk_mul_f32 v[84:85], v[84:85], v[152:153] op_sel_hi:[1,0]
	v_pk_add_f32 v[88:89], v[88:89], 1.0 op_sel_hi:[1,0]
	v_mul_f32_e32 v90, 0xbfb8aa3b, v90
	v_mul_f32_e32 v91, 0xbfb8aa3b, v91
	v_exp_f32_e32 v90, v90
	v_exp_f32_e32 v91, v91
	v_pk_mul_f32 v[86:87], v[86:87], v[152:153] op_sel_hi:[1,0]
	v_pk_mul_f32 v[82:83], v[82:83], v[152:153] op_sel_hi:[1,0]
	v_pk_add_f32 v[90:91], v[90:91], 1.0 op_sel_hi:[1,0]
	v_mul_f32_e32 v82, 0xbfb8aa3b, v82
	v_mul_f32_e32 v83, 0xbfb8aa3b, v83
	v_exp_f32_e32 v82, v82
	v_exp_f32_e32 v83, v83
	s_waitcnt vmcnt(1)
	v_lshlrev_b32_e32 v112, 16, v96
	v_and_b32_e32 v113, 0xffff0000, v96
	s_waitcnt vmcnt(0)
	v_lshlrev_b32_e32 v92, 16, v100
	v_and_b32_e32 v93, 0xffff0000, v100
	v_pk_add_f32 v[82:83], v[82:83], 1.0 op_sel_hi:[1,0]
	v_rcp_f32_e32 v89, v89
	s_nop 0
	v_rcp_f32_e32 v88, v88
	s_nop 0
	v_pk_fma_f32 v[88:89], v[88:89], v[112:113], v[92:93]
	v_mul_f32_e32 v92, 0xbfb8aa3b, v94
	v_mul_f32_e32 v93, 0xbfb8aa3b, v95
	v_exp_f32_e32 v92, v92
	v_exp_f32_e32 v93, v93
	v_lshlrev_b32_e32 v94, 16, v101
	v_and_b32_e32 v95, 0xffff0000, v101
	v_lshlrev_b32_e32 v96, 16, v97
	v_pk_add_f32 v[92:93], v[92:93], 1.0 op_sel_hi:[1,0]
	v_and_b32_e32 v97, 0xffff0000, v97
	s_nop 0
	v_rcp_f32_e32 v93, v93
	s_nop 0
	v_rcp_f32_e32 v92, v92
	s_nop 0
	v_pk_fma_f32 v[94:95], v[92:93], v[96:97], v[94:95]
	v_mul_f32_e32 v92, 0xbfb8aa3b, v110
	v_mul_f32_e32 v93, 0xbfb8aa3b, v111
	v_exp_f32_e32 v92, v92
	v_exp_f32_e32 v93, v93
	v_lshlrev_b32_e32 v100, 16, v98
	v_and_b32_e32 v101, 0xffff0000, v98
	v_lshlrev_b32_e32 v96, 16, v102
	v_pk_add_f32 v[92:93], v[92:93], 1.0 op_sel_hi:[1,0]
	v_and_b32_e32 v97, 0xffff0000, v102
	s_nop 0
	v_rcp_f32_e32 v93, v93
	s_nop 0
	v_rcp_f32_e32 v92, v92
	s_nop 0
	v_pk_fma_f32 v[100:101], v[92:93], v[100:101], v[96:97]
	v_lshlrev_b32_e32 v96, 16, v99
	v_and_b32_e32 v97, 0xffff0000, v99
	v_lshlrev_b32_e32 v92, 16, v103
	v_and_b32_e32 v93, 0xffff0000, v103
	v_rcp_f32_e32 v91, v91
	s_nop 0
	v_rcp_f32_e32 v90, v90
	s_nop 0
	v_pk_fma_f32 v[102:103], v[90:91], v[96:97], v[92:93]
	v_cvt_pk_bf16_f32 v90, v88, v89
	v_cvt_pk_bf16_f32 v91, v94, v95
	v_cvt_pk_bf16_f32 v92, v100, v101
	v_cvt_pk_bf16_f32 v93, v102, v103
	global_store_dwordx4 v[106:107], v[90:93], off
	v_pk_mul_f32 v[96:97], v[88:89], v[88:89]
	v_pk_mul_f32 v[98:99], v[94:95], v[94:95]
	global_load_dwordx4 v[88:91], v[106:107], off offset:256
	global_load_dwordx4 v[92:95], v[108:109], off offset:256
	v_pk_mul_f32 v[108:109], v[80:81], v[152:153] op_sel_hi:[1,0]
	v_mul_f32_e32 v80, 0xbfb8aa3b, v84
	v_mul_f32_e32 v81, 0xbfb8aa3b, v85
	v_exp_f32_e32 v80, v80
	v_exp_f32_e32 v81, v81
	v_pk_mul_f32 v[100:101], v[100:101], v[100:101]
	v_pk_mul_f32 v[102:103], v[102:103], v[102:103]
	v_pk_add_f32 v[80:81], v[80:81], 1.0 op_sel_hi:[1,0]
	s_waitcnt vmcnt(1)
	v_lshlrev_b32_e32 v110, 16, v88
	v_and_b32_e32 v111, 0xffff0000, v88
	s_waitcnt vmcnt(0)
	v_lshlrev_b32_e32 v84, 16, v92
	v_and_b32_e32 v85, 0xffff0000, v92
	s_nop 0
	v_rcp_f32_e32 v81, v81
	s_nop 0
	v_rcp_f32_e32 v80, v80
	s_nop 0
	v_pk_fma_f32 v[80:81], v[80:81], v[110:111], v[84:85]
	v_mul_f32_e32 v84, 0xbfb8aa3b, v86
	v_mul_f32_e32 v85, 0xbfb8aa3b, v87
	v_exp_f32_e32 v84, v84
	v_exp_f32_e32 v85, v85
	v_lshlrev_b32_e32 v86, 16, v93
	v_and_b32_e32 v87, 0xffff0000, v93
	v_lshlrev_b32_e32 v88, 16, v89
	v_pk_add_f32 v[84:85], v[84:85], 1.0 op_sel_hi:[1,0]
	v_and_b32_e32 v89, 0xffff0000, v89
	s_nop 0
	v_rcp_f32_e32 v85, v85
	s_nop 0
	v_rcp_f32_e32 v84, v84
	s_nop 0
	v_pk_fma_f32 v[84:85], v[84:85], v[88:89], v[86:87]
	v_mul_f32_e32 v86, 0xbfb8aa3b, v108
	v_mul_f32_e32 v87, 0xbfb8aa3b, v109
	v_exp_f32_e32 v86, v86
	v_exp_f32_e32 v87, v87
	v_lshlrev_b32_e32 v92, 16, v90
	v_and_b32_e32 v93, 0xffff0000, v90
	v_lshlrev_b32_e32 v88, 16, v94
	v_pk_add_f32 v[86:87], v[86:87], 1.0 op_sel_hi:[1,0]
	v_and_b32_e32 v89, 0xffff0000, v94
	s_nop 0
	v_rcp_f32_e32 v87, v87
	s_nop 0
	v_rcp_f32_e32 v86, v86
	s_nop 0
	v_pk_fma_f32 v[92:93], v[86:87], v[92:93], v[88:89]
	v_lshlrev_b32_e32 v88, 16, v91
	v_and_b32_e32 v89, 0xffff0000, v91
	v_lshlrev_b32_e32 v86, 16, v95
	v_and_b32_e32 v87, 0xffff0000, v95
	v_rcp_f32_e32 v83, v83
	s_nop 0
	v_rcp_f32_e32 v82, v82
	s_nop 0
	v_pk_fma_f32 v[82:83], v[82:83], v[88:89], v[86:87]
	v_cvt_pk_bf16_f32 v86, v80, v81
	v_cvt_pk_bf16_f32 v87, v84, v85
	v_cvt_pk_bf16_f32 v88, v92, v93
	v_cvt_pk_bf16_f32 v89, v82, v83
	global_store_dwordx4 v[106:107], v[86:89], off offset:256
	v_pk_mul_f32 v[82:83], v[82:83], v[82:83]
	v_pk_mul_f32 v[80:81], v[80:81], v[80:81]
	v_pk_mul_f32 v[86:87], v[92:93], v[92:93]
	v_pk_mul_f32 v[84:85], v[84:85], v[84:85]
	v_add_f32_e32 v88, v102, v103
	v_add_f32_e32 v89, v100, v101
	v_add_f32_e32 v82, v82, v83
	v_add_f32_e32 v83, v86, v87
	v_add_f32_e32 v88, v89, v88
	v_add_f32_e32 v89, v98, v99
	v_add_f32_e32 v90, v96, v97
	v_add_f32_e32 v82, v83, v82
	v_add_f32_e32 v83, v84, v85
	v_add_f32_e32 v80, v80, v81
	v_add_f32_e32 v89, v90, v89
	v_add_f32_e32 v80, v80, v83
	v_add_f32_e32 v88, v89, v88
	v_add_f32_e32 v80, v80, v82
	v_add_f32_e32 v80, v88, v80
	ds_bpermute_b32 v81, v169, v80
	s_waitcnt lgkmcnt(0)
	v_add_f32_e32 v80, v80, v81
	ds_bpermute_b32 v81, v155, v80
	s_and_saveexec_b64 s[0:1], s[46:47]
	s_cbranch_execz .LBB0_476
	s_waitcnt lgkmcnt(0)
	v_add_f32_e32 v82, v80, v81
	v_lshlrev_b64 v[80:81], 6, v[104:105]
	v_lshl_add_u64 v[80:81], s[6:7], 0, v[80:81]
	v_lshl_add_u64 v[80:81], s[42:43], 2, v[80:81]
	s_lshl_b32 s94, s35, 2
	v_lshl_add_u64 v[80:81], v[80:81], 0, s[94:95]
	global_store_dword v[80:81], v82, off
; DI unsigned pk2(float lo, float hi) { const f32x2_t v = {lo, hi}; const bf16x2_t b = __builtin_convertvector(v, bf16x2_t); return __builtin_bit_cast(unsigned, b); }
; DI float lo16(unsigned w) { return __uint_as_float(w << 16); }
; DI float hi16(unsigned w) { return __uint_as_float(w & 0xffff0000u); }
;     DI void operator()(const pg8::f32x4 (&acc)[2][2][4][2], const pg8::Unit& u, int wr, int wc, int fr, int fq) const {
;     ...
;             for (int m = 0; m < 4; ++m) {
;                 const int row = row0 + ai * 128 + m * 16; const float r = rs[ai][m];
;                 float part = 0.f;
; #pragma unroll
;                 for (int bj = 0; bj < 2; ++bj) { const size_t off = (size_t)row * 1024 + col0 + bj * 128;
;                     const u32x4 tw = *(const u32x4*)(T + off); const u32x4 xw = *(const u32x4*)(xr + off);
;                     const pg8::f32x4 a0 = acc[ai][bj][m][0] * r, a1 = acc[ai][bj][m][1] * r;
;                     const float o0 = lo16(xw.x) + lo16(tw.x) * __frcp_rn(1.0f + __expf(-a0[0])), o1 = hi16(xw.x) + hi16(tw.x) * __frcp_rn(1.0f + __expf(-a0[1]));
;                     const float o2 = lo16(xw.y) + lo16(tw.y) * __frcp_rn(1.0f + __expf(-a0[2])), o3 = hi16(xw.y) + hi16(tw.y) * __frcp_rn(1.0f + __expf(-a0[3]));
;                     const float o4 = lo16(xw.z) + lo16(tw.z) * __frcp_rn(1.0f + __expf(-a1[0])), o5 = hi16(xw.z) + hi16(tw.z) * __frcp_rn(1.0f + __expf(-a1[1]));
;                     const float o6 = lo16(xw.w) + lo16(tw.w) * __frcp_rn(1.0f + __expf(-a1[2])), o7 = hi16(xw.w) + hi16(tw.w) * __frcp_rn(1.0f + __expf(-a1[3]));
;                     u32x4 w; w.x = pk2(o0, o1); w.y = pk2(o2, o3); w.z = pk2(o4, o5); w.w = pk2(o6, o7); *(u32x4*)(xbo + off) = w;
;                     part += ((o0 * o0 + o1 * o1) + (o2 * o2 + o3 * o3)) + ((o4 * o4 + o5 * o5) + (o6 * o6 + o7 * o7)); }
;                 part += __shfl_xor(part, 16); part += __shfl_xor(part, 32);
;                 if (ssout && fq == 0) ssout[(size_t)row * 16 + u.pn * 4 + wc] = part;
.LBB0_476:
	s_or_b64 exec, exec, s[0:1]
	v_or_b32_e32 v88, 48, v142
	v_ashrrev_i32_e32 v89, 31, v88
	s_waitcnt lgkmcnt(0)
	v_lshlrev_b64 v[80:81], 10, v[88:89]
	v_lshl_add_u64 v[80:81], v[80:81], 0, v[140:141]
	v_lshlrev_b64 v[84:85], 1, v[80:81]
	v_lshl_add_u64 v[90:91], s[18:19], 0, v[84:85]
	global_load_dwordx4 v[80:83], v[90:91], off
	v_lshl_add_u64 v[92:93], s[12:13], 0, v[84:85]
	global_load_dwordx4 v[84:87], v[92:93], off
	v_pk_mul_f32 v[76:77], v[76:77], v[150:151] op_sel_hi:[1,0]
	v_pk_mul_f32 v[94:95], v[72:73], v[150:151] op_sel_hi:[1,0]
	v_mul_f32_e32 v72, 0xbfb8aa3b, v76
	v_mul_f32_e32 v73, 0xbfb8aa3b, v77
	v_exp_f32_e32 v72, v72
	v_exp_f32_e32 v73, v73
	v_pk_mul_f32 v[78:79], v[78:79], v[150:151] op_sel_hi:[1,0]
	v_pk_mul_f32 v[74:75], v[74:75], v[150:151] op_sel_hi:[1,0]
	v_pk_mul_f32 v[68:69], v[68:69], v[150:151] op_sel_hi:[1,0]
	v_pk_add_f32 v[72:73], v[72:73], 1.0 op_sel_hi:[1,0]
	v_mul_f32_e32 v74, 0xbfb8aa3b, v74
	v_mul_f32_e32 v75, 0xbfb8aa3b, v75
	v_exp_f32_e32 v74, v74
	v_exp_f32_e32 v75, v75
	v_pk_mul_f32 v[70:71], v[70:71], v[150:151] op_sel_hi:[1,0]
	v_pk_mul_f32 v[66:67], v[66:67], v[150:151] op_sel_hi:[1,0]
	v_pk_add_f32 v[74:75], v[74:75], 1.0 op_sel_hi:[1,0]
	v_mul_f32_e32 v66, 0xbfb8aa3b, v66
	v_mul_f32_e32 v67, 0xbfb8aa3b, v67
	v_exp_f32_e32 v66, v66
	v_exp_f32_e32 v67, v67
	s_waitcnt vmcnt(1)
	v_lshlrev_b32_e32 v96, 16, v80
	v_and_b32_e32 v97, 0xffff0000, v80
	s_waitcnt vmcnt(0)
	v_lshlrev_b32_e32 v76, 16, v84
	v_and_b32_e32 v77, 0xffff0000, v84
	v_pk_add_f32 v[66:67], v[66:67], 1.0 op_sel_hi:[1,0]
	v_rcp_f32_e32 v73, v73
	s_nop 0
	v_rcp_f32_e32 v72, v72
	s_nop 0
	v_pk_fma_f32 v[72:73], v[72:73], v[96:97], v[76:77]
	v_mul_f32_e32 v76, 0xbfb8aa3b, v78
	v_mul_f32_e32 v77, 0xbfb8aa3b, v79
	v_exp_f32_e32 v76, v76
	v_exp_f32_e32 v77, v77
	v_lshlrev_b32_e32 v78, 16, v85
	v_and_b32_e32 v79, 0xffff0000, v85
	v_lshlrev_b32_e32 v80, 16, v81
	v_pk_add_f32 v[76:77], v[76:77], 1.0 op_sel_hi:[1,0]
	v_and_b32_e32 v81, 0xffff0000, v81
	s_nop 0
	v_rcp_f32_e32 v77, v77
	s_nop 0
	v_rcp_f32_e32 v76, v76
	s_nop 0
	v_pk_fma_f32 v[78:79], v[76:77], v[80:81], v[78:79]
	v_mul_f32_e32 v76, 0xbfb8aa3b, v94
	v_mul_f32_e32 v77, 0xbfb8aa3b, v95
	v_exp_f32_e32 v76, v76
	v_exp_f32_e32 v77, v77
	v_lshlrev_b32_e32 v84, 16, v82
	v_and_b32_e32 v85, 0xffff0000, v82
	v_lshlrev_b32_e32 v80, 16, v86
	v_pk_add_f32 v[76:77], v[76:77], 1.0 op_sel_hi:[1,0]
	v_and_b32_e32 v81, 0xffff0000, v86
	s_nop 0
	v_rcp_f32_e32 v77, v77
	s_nop 0
	v_rcp_f32_e32 v76, v76
	s_nop 0
	v_pk_fma_f32 v[84:85], v[76:77], v[84:85], v[80:81]
	v_lshlrev_b32_e32 v80, 16, v83
	v_and_b32_e32 v81, 0xffff0000, v83
	v_lshlrev_b32_e32 v76, 16, v87
	v_and_b32_e32 v77, 0xffff0000, v87
	v_rcp_f32_e32 v75, v75
	s_nop 0
	v_rcp_f32_e32 v74, v74
	s_nop 0
	v_pk_fma_f32 v[86:87], v[74:75], v[80:81], v[76:77]
	v_cvt_pk_bf16_f32 v74, v72, v73
	v_cvt_pk_bf16_f32 v75, v78, v79
	v_cvt_pk_bf16_f32 v76, v84, v85
	v_cvt_pk_bf16_f32 v77, v86, v87
	global_store_dwordx4 v[90:91], v[74:77], off
	v_pk_mul_f32 v[80:81], v[72:73], v[72:73]
	v_pk_mul_f32 v[82:83], v[78:79], v[78:79]
	global_load_dwordx4 v[72:75], v[90:91], off offset:256
	global_load_dwordx4 v[76:79], v[92:93], off offset:256
	v_pk_mul_f32 v[92:93], v[64:65], v[150:151] op_sel_hi:[1,0]
	v_mul_f32_e32 v64, 0xbfb8aa3b, v68
	v_mul_f32_e32 v65, 0xbfb8aa3b, v69
	v_exp_f32_e32 v64, v64
	v_exp_f32_e32 v65, v65
	v_pk_mul_f32 v[84:85], v[84:85], v[84:85]
	v_pk_mul_f32 v[86:87], v[86:87], v[86:87]
	v_pk_add_f32 v[64:65], v[64:65], 1.0 op_sel_hi:[1,0]
	s_waitcnt vmcnt(1)
	v_lshlrev_b32_e32 v94, 16, v72
	v_and_b32_e32 v95, 0xffff0000, v72
	s_waitcnt vmcnt(0)
	v_lshlrev_b32_e32 v68, 16, v76
	v_and_b32_e32 v69, 0xffff0000, v76
	s_nop 0
	v_rcp_f32_e32 v65, v65
	s_nop 0
	v_rcp_f32_e32 v64, v64
	s_nop 0
	v_pk_fma_f32 v[64:65], v[64:65], v[94:95], v[68:69]
	v_mul_f32_e32 v68, 0xbfb8aa3b, v70
	v_mul_f32_e32 v69, 0xbfb8aa3b, v71
	v_exp_f32_e32 v68, v68
	v_exp_f32_e32 v69, v69
	v_lshlrev_b32_e32 v70, 16, v77
	v_and_b32_e32 v71, 0xffff0000, v77
	v_lshlrev_b32_e32 v72, 16, v73
	v_pk_add_f32 v[68:69], v[68:69], 1.0 op_sel_hi:[1,0]
	v_and_b32_e32 v73, 0xffff0000, v73
	s_nop 0
	v_rcp_f32_e32 v69, v69
	s_nop 0
	v_rcp_f32_e32 v68, v68
	s_nop 0
	v_pk_fma_f32 v[68:69], v[68:69], v[72:73], v[70:71]
	v_mul_f32_e32 v70, 0xbfb8aa3b, v92
	v_mul_f32_e32 v71, 0xbfb8aa3b, v93
	v_exp_f32_e32 v70, v70
	v_exp_f32_e32 v71, v71
	v_lshlrev_b32_e32 v76, 16, v74
	v_and_b32_e32 v77, 0xffff0000, v74
	v_lshlrev_b32_e32 v72, 16, v78
	v_pk_add_f32 v[70:71], v[70:71], 1.0 op_sel_hi:[1,0]
	v_and_b32_e32 v73, 0xffff0000, v78
	s_nop 0
	v_rcp_f32_e32 v71, v71
	s_nop 0
	v_rcp_f32_e32 v70, v70
	s_nop 0
	v_pk_fma_f32 v[76:77], v[70:71], v[76:77], v[72:73]
	v_lshlrev_b32_e32 v72, 16, v75
	v_and_b32_e32 v73, 0xffff0000, v75
	v_lshlrev_b32_e32 v70, 16, v79
	v_and_b32_e32 v71, 0xffff0000, v79
	v_rcp_f32_e32 v67, v67
	s_nop 0
	v_rcp_f32_e32 v66, v66
	s_nop 0
	v_pk_fma_f32 v[66:67], v[66:67], v[72:73], v[70:71]
	v_cvt_pk_bf16_f32 v70, v64, v65
	v_cvt_pk_bf16_f32 v71, v68, v69
	v_cvt_pk_bf16_f32 v72, v76, v77
	v_cvt_pk_bf16_f32 v73, v66, v67
	global_store_dwordx4 v[90:91], v[70:73], off offset:256
	v_pk_mul_f32 v[66:67], v[66:67], v[66:67]
	v_pk_mul_f32 v[64:65], v[64:65], v[64:65]
	v_pk_mul_f32 v[70:71], v[76:77], v[76:77]
	v_pk_mul_f32 v[68:69], v[68:69], v[68:69]
	v_add_f32_e32 v72, v86, v87
	v_add_f32_e32 v73, v84, v85
	v_add_f32_e32 v66, v66, v67
	v_add_f32_e32 v67, v70, v71
	v_add_f32_e32 v72, v73, v72
	v_add_f32_e32 v73, v82, v83
	v_add_f32_e32 v74, v80, v81
	v_add_f32_e32 v66, v67, v66
	v_add_f32_e32 v67, v68, v69
	v_add_f32_e32 v64, v64, v65
	v_add_f32_e32 v73, v74, v73
	v_add_f32_e32 v64, v64, v67
	v_add_f32_e32 v72, v73, v72
	v_add_f32_e32 v64, v64, v66
	v_add_f32_e32 v64, v72, v64
	ds_bpermute_b32 v65, v169, v64
	s_waitcnt lgkmcnt(0)
	v_add_f32_e32 v64, v64, v65
	ds_bpermute_b32 v65, v155, v64
	s_and_saveexec_b64 s[0:1], s[46:47]
	s_cbranch_execz .LBB0_478
	s_waitcnt lgkmcnt(0)
	v_add_f32_e32 v66, v64, v65
	v_lshlrev_b64 v[64:65], 6, v[88:89]
	v_lshl_add_u64 v[64:65], s[6:7], 0, v[64:65]
	v_lshl_add_u64 v[64:65], s[42:43], 2, v[64:65]
	s_lshl_b32 s94, s35, 2
	v_lshl_add_u64 v[64:65], v[64:65], 0, s[94:95]
	global_store_dword v[64:65], v66, off
; DI unsigned pk2(float lo, float hi) { const f32x2_t v = {lo, hi}; const bf16x2_t b = __builtin_convertvector(v, bf16x2_t); return __builtin_bit_cast(unsigned, b); }
; DI float lo16(unsigned w) { return __uint_as_float(w << 16); }
; DI float hi16(unsigned w) { return __uint_as_float(w & 0xffff0000u); }
;     DI void operator()(const pg8::f32x4 (&acc)[2][2][4][2], const pg8::Unit& u, int wr, int wc, int fr, int fq) const {
;     ...
;             for (int m = 0; m < 4; ++m) {
;                 const int row = row0 + ai * 128 + m * 16; const float r = rs[ai][m];
;                 float part = 0.f;
; #pragma unroll
;                 for (int bj = 0; bj < 2; ++bj) { const size_t off = (size_t)row * 1024 + col0 + bj * 128;
;                     const u32x4 tw = *(const u32x4*)(T + off); const u32x4 xw = *(const u32x4*)(xr + off);
;                     const pg8::f32x4 a0 = acc[ai][bj][m][0] * r, a1 = acc[ai][bj][m][1] * r;
;                     const float o0 = lo16(xw.x) + lo16(tw.x) * __frcp_rn(1.0f + __expf(-a0[0])), o1 = hi16(xw.x) + hi16(tw.x) * __frcp_rn(1.0f + __expf(-a0[1]));
;                     const float o2 = lo16(xw.y) + lo16(tw.y) * __frcp_rn(1.0f + __expf(-a0[2])), o3 = hi16(xw.y) + hi16(tw.y) * __frcp_rn(1.0f + __expf(-a0[3]));
;                     const float o4 = lo16(xw.z) + lo16(tw.z) * __frcp_rn(1.0f + __expf(-a1[0])), o5 = hi16(xw.z) + hi16(tw.z) * __frcp_rn(1.0f + __expf(-a1[1]));
;                     const float o6 = lo16(xw.w) + lo16(tw.w) * __frcp_rn(1.0f + __expf(-a1[2])), o7 = hi16(xw.w) + hi16(tw.w) * __frcp_rn(1.0f + __expf(-a1[3]));
;                     u32x4 w; w.x = pk2(o0, o1); w.y = pk2(o2, o3); w.z = pk2(o4, o5); w.w = pk2(o6, o7); *(u32x4*)(xbo + off) = w;
;                     part += ((o0 * o0 + o1 * o1) + (o2 * o2 + o3 * o3)) + ((o4 * o4 + o5 * o5) + (o6 * o6 + o7 * o7)); }
;                 part += __shfl_xor(part, 16); part += __shfl_xor(part, 32);
;                 if (ssout && fq == 0) ssout[(size_t)row * 16 + u.pn * 4 + wc] = part;
.LBB0_478:
	s_or_b64 exec, exec, s[0:1]
	v_add_u32_e32 v72, 0x80, v142
	v_ashrrev_i32_e32 v73, 31, v72
	s_waitcnt lgkmcnt(0)
	v_lshlrev_b64 v[64:65], 10, v[72:73]
	v_lshl_add_u64 v[64:65], v[64:65], 0, v[140:141]
	v_lshlrev_b64 v[68:69], 1, v[64:65]
	v_lshl_add_u64 v[74:75], s[18:19], 0, v[68:69]
	global_load_dwordx4 v[64:67], v[74:75], off
	v_lshl_add_u64 v[76:77], s[12:13], 0, v[68:69]
	global_load_dwordx4 v[68:71], v[76:77], off
	v_pk_mul_f32 v[60:61], v[60:61], v[148:149] op_sel_hi:[1,0]
	v_pk_mul_f32 v[78:79], v[56:57], v[148:149] op_sel_hi:[1,0]
	v_mul_f32_e32 v56, 0xbfb8aa3b, v60
	v_mul_f32_e32 v57, 0xbfb8aa3b, v61
	v_exp_f32_e32 v56, v56
	v_exp_f32_e32 v57, v57
	v_pk_mul_f32 v[62:63], v[62:63], v[148:149] op_sel_hi:[1,0]
	v_pk_mul_f32 v[58:59], v[58:59], v[148:149] op_sel_hi:[1,0]
	v_pk_mul_f32 v[52:53], v[52:53], v[148:149] op_sel_hi:[1,0]
	v_pk_add_f32 v[56:57], v[56:57], 1.0 op_sel_hi:[1,0]
	v_mul_f32_e32 v58, 0xbfb8aa3b, v58
	v_mul_f32_e32 v59, 0xbfb8aa3b, v59
	v_exp_f32_e32 v58, v58
	v_exp_f32_e32 v59, v59
	v_pk_mul_f32 v[54:55], v[54:55], v[148:149] op_sel_hi:[1,0]
	v_pk_mul_f32 v[50:51], v[50:51], v[148:149] op_sel_hi:[1,0]
	v_pk_add_f32 v[58:59], v[58:59], 1.0 op_sel_hi:[1,0]
	v_mul_f32_e32 v50, 0xbfb8aa3b, v50
	v_mul_f32_e32 v51, 0xbfb8aa3b, v51
	v_exp_f32_e32 v50, v50
	v_exp_f32_e32 v51, v51
	s_waitcnt vmcnt(1)
	v_lshlrev_b32_e32 v80, 16, v64
	v_and_b32_e32 v81, 0xffff0000, v64
	s_waitcnt vmcnt(0)
	v_lshlrev_b32_e32 v60, 16, v68
	v_and_b32_e32 v61, 0xffff0000, v68
	v_pk_add_f32 v[50:51], v[50:51], 1.0 op_sel_hi:[1,0]
	v_rcp_f32_e32 v57, v57
	s_nop 0
	v_rcp_f32_e32 v56, v56
	s_nop 0
	v_pk_fma_f32 v[56:57], v[56:57], v[80:81], v[60:61]
	v_mul_f32_e32 v60, 0xbfb8aa3b, v62
	v_mul_f32_e32 v61, 0xbfb8aa3b, v63
	v_exp_f32_e32 v60, v60
	v_exp_f32_e32 v61, v61
	v_lshlrev_b32_e32 v62, 16, v69
	v_and_b32_e32 v63, 0xffff0000, v69
	v_lshlrev_b32_e32 v64, 16, v65
	v_pk_add_f32 v[60:61], v[60:61], 1.0 op_sel_hi:[1,0]
	v_and_b32_e32 v65, 0xffff0000, v65
	s_nop 0
	v_rcp_f32_e32 v61, v61
	s_nop 0
	v_rcp_f32_e32 v60, v60
	s_nop 0
	v_pk_fma_f32 v[62:63], v[60:61], v[64:65], v[62:63]
	v_mul_f32_e32 v60, 0xbfb8aa3b, v78
	v_mul_f32_e32 v61, 0xbfb8aa3b, v79
	v_exp_f32_e32 v60, v60
	v_exp_f32_e32 v61, v61
	v_lshlrev_b32_e32 v68, 16, v66
	v_and_b32_e32 v69, 0xffff0000, v66
	v_lshlrev_b32_e32 v64, 16, v70
	v_pk_add_f32 v[60:61], v[60:61], 1.0 op_sel_hi:[1,0]
	v_and_b32_e32 v65, 0xffff0000, v70
	s_nop 0
	v_rcp_f32_e32 v61, v61
	s_nop 0
	v_rcp_f32_e32 v60, v60
	s_nop 0
	v_pk_fma_f32 v[68:69], v[60:61], v[68:69], v[64:65]
	v_lshlrev_b32_e32 v64, 16, v67
	v_and_b32_e32 v65, 0xffff0000, v67
	v_lshlrev_b32_e32 v60, 16, v71
	v_and_b32_e32 v61, 0xffff0000, v71
	v_rcp_f32_e32 v59, v59
	s_nop 0
	v_rcp_f32_e32 v58, v58
	s_nop 0
	v_pk_fma_f32 v[70:71], v[58:59], v[64:65], v[60:61]
	v_cvt_pk_bf16_f32 v58, v56, v57
	v_cvt_pk_bf16_f32 v59, v62, v63
	v_cvt_pk_bf16_f32 v60, v68, v69
	v_cvt_pk_bf16_f32 v61, v70, v71
	global_store_dwordx4 v[74:75], v[58:61], off
	v_pk_mul_f32 v[64:65], v[56:57], v[56:57]
	v_pk_mul_f32 v[66:67], v[62:63], v[62:63]
	global_load_dwordx4 v[56:59], v[74:75], off offset:256
	global_load_dwordx4 v[60:63], v[76:77], off offset:256
	v_pk_mul_f32 v[76:77], v[48:49], v[148:149] op_sel_hi:[1,0]
	v_mul_f32_e32 v48, 0xbfb8aa3b, v52
	v_mul_f32_e32 v49, 0xbfb8aa3b, v53
	v_exp_f32_e32 v48, v48
	v_exp_f32_e32 v49, v49
	v_pk_mul_f32 v[68:69], v[68:69], v[68:69]
	v_pk_mul_f32 v[70:71], v[70:71], v[70:71]
	v_pk_add_f32 v[48:49], v[48:49], 1.0 op_sel_hi:[1,0]
	s_waitcnt vmcnt(1)
	v_lshlrev_b32_e32 v78, 16, v56
	v_and_b32_e32 v79, 0xffff0000, v56
	s_waitcnt vmcnt(0)
	v_lshlrev_b32_e32 v52, 16, v60
	v_and_b32_e32 v53, 0xffff0000, v60
	s_nop 0
	v_rcp_f32_e32 v49, v49
	s_nop 0
	v_rcp_f32_e32 v48, v48
	s_nop 0
	v_pk_fma_f32 v[48:49], v[48:49], v[78:79], v[52:53]
	v_mul_f32_e32 v52, 0xbfb8aa3b, v54
	v_mul_f32_e32 v53, 0xbfb8aa3b, v55
	v_exp_f32_e32 v52, v52
	v_exp_f32_e32 v53, v53
	v_lshlrev_b32_e32 v54, 16, v61
	v_and_b32_e32 v55, 0xffff0000, v61
	v_lshlrev_b32_e32 v56, 16, v57
	v_pk_add_f32 v[52:53], v[52:53], 1.0 op_sel_hi:[1,0]
	v_and_b32_e32 v57, 0xffff0000, v57
	s_nop 0
	v_rcp_f32_e32 v53, v53
	s_nop 0
	v_rcp_f32_e32 v52, v52
	s_nop 0
	v_pk_fma_f32 v[52:53], v[52:53], v[56:57], v[54:55]
	v_mul_f32_e32 v54, 0xbfb8aa3b, v76
	v_mul_f32_e32 v55, 0xbfb8aa3b, v77
	v_exp_f32_e32 v54, v54
	v_exp_f32_e32 v55, v55
	v_lshlrev_b32_e32 v60, 16, v58
	v_and_b32_e32 v61, 0xffff0000, v58
	v_lshlrev_b32_e32 v56, 16, v62
	v_pk_add_f32 v[54:55], v[54:55], 1.0 op_sel_hi:[1,0]
	v_and_b32_e32 v57, 0xffff0000, v62
	s_nop 0
	v_rcp_f32_e32 v55, v55
	s_nop 0
	v_rcp_f32_e32 v54, v54
	s_nop 0
	v_pk_fma_f32 v[60:61], v[54:55], v[60:61], v[56:57]
	v_lshlrev_b32_e32 v56, 16, v59
	v_and_b32_e32 v57, 0xffff0000, v59
	v_lshlrev_b32_e32 v54, 16, v63
	v_and_b32_e32 v55, 0xffff0000, v63
	v_rcp_f32_e32 v51, v51
	s_nop 0
	v_rcp_f32_e32 v50, v50
	s_nop 0
	v_pk_fma_f32 v[50:51], v[50:51], v[56:57], v[54:55]
	v_cvt_pk_bf16_f32 v54, v48, v49
	v_cvt_pk_bf16_f32 v55, v52, v53
	v_cvt_pk_bf16_f32 v56, v60, v61
	v_cvt_pk_bf16_f32 v57, v50, v51
	global_store_dwordx4 v[74:75], v[54:57], off offset:256
	v_pk_mul_f32 v[50:51], v[50:51], v[50:51]
	v_pk_mul_f32 v[48:49], v[48:49], v[48:49]
	v_pk_mul_f32 v[54:55], v[60:61], v[60:61]
	v_pk_mul_f32 v[52:53], v[52:53], v[52:53]
	v_add_f32_e32 v56, v70, v71
	v_add_f32_e32 v57, v68, v69
	v_add_f32_e32 v50, v50, v51
	v_add_f32_e32 v51, v54, v55
	v_add_f32_e32 v56, v57, v56
	v_add_f32_e32 v57, v66, v67
	v_add_f32_e32 v58, v64, v65
	v_add_f32_e32 v50, v51, v50
	v_add_f32_e32 v51, v52, v53
	v_add_f32_e32 v48, v48, v49
	v_add_f32_e32 v57, v58, v57
	v_add_f32_e32 v48, v48, v51
	v_add_f32_e32 v56, v57, v56
	v_add_f32_e32 v48, v48, v50
	v_add_f32_e32 v48, v56, v48
	ds_bpermute_b32 v49, v169, v48
	s_waitcnt lgkmcnt(0)
	v_add_f32_e32 v48, v48, v49
	ds_bpermute_b32 v49, v155, v48
	s_and_saveexec_b64 s[0:1], s[46:47]
	s_cbranch_execz .LBB0_480
	s_waitcnt lgkmcnt(0)
	v_add_f32_e32 v50, v48, v49
	v_lshlrev_b64 v[48:49], 6, v[72:73]
	v_lshl_add_u64 v[48:49], s[6:7], 0, v[48:49]
	v_lshl_add_u64 v[48:49], s[42:43], 2, v[48:49]
	s_lshl_b32 s94, s35, 2
	v_lshl_add_u64 v[48:49], v[48:49], 0, s[94:95]
	global_store_dword v[48:49], v50, off
; DI unsigned pk2(float lo, float hi) { const f32x2_t v = {lo, hi}; const bf16x2_t b = __builtin_convertvector(v, bf16x2_t); return __builtin_bit_cast(unsigned, b); }
; DI float lo16(unsigned w) { return __uint_as_float(w << 16); }
; DI float hi16(unsigned w) { return __uint_as_float(w & 0xffff0000u); }
;     DI void operator()(const pg8::f32x4 (&acc)[2][2][4][2], const pg8::Unit& u, int wr, int wc, int fr, int fq) const {
;     ...
;             for (int m = 0; m < 4; ++m) {
;                 const int row = row0 + ai * 128 + m * 16; const float r = rs[ai][m];
;                 float part = 0.f;
; #pragma unroll
;                 for (int bj = 0; bj < 2; ++bj) { const size_t off = (size_t)row * 1024 + col0 + bj * 128;
;                     const u32x4 tw = *(const u32x4*)(T + off); const u32x4 xw = *(const u32x4*)(xr + off);
;                     const pg8::f32x4 a0 = acc[ai][bj][m][0] * r, a1 = acc[ai][bj][m][1] * r;
;                     const float o0 = lo16(xw.x) + lo16(tw.x) * __frcp_rn(1.0f + __expf(-a0[0])), o1 = hi16(xw.x) + hi16(tw.x) * __frcp_rn(1.0f + __expf(-a0[1]));
;                     const float o2 = lo16(xw.y) + lo16(tw.y) * __frcp_rn(1.0f + __expf(-a0[2])), o3 = hi16(xw.y) + hi16(tw.y) * __frcp_rn(1.0f + __expf(-a0[3]));
;                     const float o4 = lo16(xw.z) + lo16(tw.z) * __frcp_rn(1.0f + __expf(-a1[0])), o5 = hi16(xw.z) + hi16(tw.z) * __frcp_rn(1.0f + __expf(-a1[1]));
;                     const float o6 = lo16(xw.w) + lo16(tw.w) * __frcp_rn(1.0f + __expf(-a1[2])), o7 = hi16(xw.w) + hi16(tw.w) * __frcp_rn(1.0f + __expf(-a1[3]));
;                     u32x4 w; w.x = pk2(o0, o1); w.y = pk2(o2, o3); w.z = pk2(o4, o5); w.w = pk2(o6, o7); *(u32x4*)(xbo + off) = w;
;                     part += ((o0 * o0 + o1 * o1) + (o2 * o2 + o3 * o3)) + ((o4 * o4 + o5 * o5) + (o6 * o6 + o7 * o7)); }
;                 part += __shfl_xor(part, 16); part += __shfl_xor(part, 32);
;                 if (ssout && fq == 0) ssout[(size_t)row * 16 + u.pn * 4 + wc] = part;
.LBB0_480:
	s_or_b64 exec, exec, s[0:1]
	v_add_u32_e32 v56, 0x90, v142
	v_ashrrev_i32_e32 v57, 31, v56
	s_waitcnt lgkmcnt(0)
	v_lshlrev_b64 v[48:49], 10, v[56:57]
	v_lshl_add_u64 v[48:49], v[48:49], 0, v[140:141]
	v_lshlrev_b64 v[52:53], 1, v[48:49]
	v_lshl_add_u64 v[58:59], s[18:19], 0, v[52:53]
	global_load_dwordx4 v[48:51], v[58:59], off
	v_lshl_add_u64 v[60:61], s[12:13], 0, v[52:53]
	global_load_dwordx4 v[52:55], v[60:61], off
	v_pk_mul_f32 v[44:45], v[44:45], v[146:147] op_sel_hi:[1,0]
	v_pk_mul_f32 v[62:63], v[40:41], v[146:147] op_sel_hi:[1,0]
	v_mul_f32_e32 v40, 0xbfb8aa3b, v44
	v_mul_f32_e32 v41, 0xbfb8aa3b, v45
	v_exp_f32_e32 v40, v40
	v_exp_f32_e32 v41, v41
	v_pk_mul_f32 v[46:47], v[46:47], v[146:147] op_sel_hi:[1,0]
	v_pk_mul_f32 v[42:43], v[42:43], v[146:147] op_sel_hi:[1,0]
	v_pk_mul_f32 v[36:37], v[36:37], v[146:147] op_sel_hi:[1,0]
	v_pk_add_f32 v[40:41], v[40:41], 1.0 op_sel_hi:[1,0]
	v_mul_f32_e32 v42, 0xbfb8aa3b, v42
	v_mul_f32_e32 v43, 0xbfb8aa3b, v43
	v_exp_f32_e32 v42, v42
	v_exp_f32_e32 v43, v43
	v_pk_mul_f32 v[38:39], v[38:39], v[146:147] op_sel_hi:[1,0]
	v_pk_mul_f32 v[34:35], v[34:35], v[146:147] op_sel_hi:[1,0]
	v_pk_add_f32 v[42:43], v[42:43], 1.0 op_sel_hi:[1,0]
	v_mul_f32_e32 v34, 0xbfb8aa3b, v34
	v_mul_f32_e32 v35, 0xbfb8aa3b, v35
	v_exp_f32_e32 v34, v34
	v_exp_f32_e32 v35, v35
	s_waitcnt vmcnt(1)
	v_lshlrev_b32_e32 v64, 16, v48
	v_and_b32_e32 v65, 0xffff0000, v48
	s_waitcnt vmcnt(0)
	v_lshlrev_b32_e32 v44, 16, v52
	v_and_b32_e32 v45, 0xffff0000, v52
	v_pk_add_f32 v[34:35], v[34:35], 1.0 op_sel_hi:[1,0]
	v_rcp_f32_e32 v41, v41
	s_nop 0
	v_rcp_f32_e32 v40, v40
	s_nop 0
	v_pk_fma_f32 v[40:41], v[40:41], v[64:65], v[44:45]
	v_mul_f32_e32 v44, 0xbfb8aa3b, v46
	v_mul_f32_e32 v45, 0xbfb8aa3b, v47
	v_exp_f32_e32 v44, v44
	v_exp_f32_e32 v45, v45
	v_lshlrev_b32_e32 v46, 16, v53
	v_and_b32_e32 v47, 0xffff0000, v53
	v_lshlrev_b32_e32 v48, 16, v49
	v_pk_add_f32 v[44:45], v[44:45], 1.0 op_sel_hi:[1,0]
	v_and_b32_e32 v49, 0xffff0000, v49
	s_nop 0
	v_rcp_f32_e32 v45, v45
	s_nop 0
	v_rcp_f32_e32 v44, v44
	s_nop 0
	v_pk_fma_f32 v[46:47], v[44:45], v[48:49], v[46:47]
	v_mul_f32_e32 v44, 0xbfb8aa3b, v62
	v_mul_f32_e32 v45, 0xbfb8aa3b, v63
	v_exp_f32_e32 v44, v44
	v_exp_f32_e32 v45, v45
	v_lshlrev_b32_e32 v52, 16, v50
	v_and_b32_e32 v53, 0xffff0000, v50
	v_lshlrev_b32_e32 v48, 16, v54
	v_pk_add_f32 v[44:45], v[44:45], 1.0 op_sel_hi:[1,0]
	v_and_b32_e32 v49, 0xffff0000, v54
	s_nop 0
	v_rcp_f32_e32 v45, v45
	s_nop 0
	v_rcp_f32_e32 v44, v44
	s_nop 0
	v_pk_fma_f32 v[52:53], v[44:45], v[52:53], v[48:49]
	v_lshlrev_b32_e32 v48, 16, v51
	v_and_b32_e32 v49, 0xffff0000, v51
	v_lshlrev_b32_e32 v44, 16, v55
	v_and_b32_e32 v45, 0xffff0000, v55
	v_rcp_f32_e32 v43, v43
	s_nop 0
	v_rcp_f32_e32 v42, v42
	s_nop 0
	v_pk_fma_f32 v[54:55], v[42:43], v[48:49], v[44:45]
	v_cvt_pk_bf16_f32 v42, v40, v41
	v_cvt_pk_bf16_f32 v43, v46, v47
	v_cvt_pk_bf16_f32 v44, v52, v53
	v_cvt_pk_bf16_f32 v45, v54, v55
	global_store_dwordx4 v[58:59], v[42:45], off
	v_pk_mul_f32 v[48:49], v[40:41], v[40:41]
	v_pk_mul_f32 v[50:51], v[46:47], v[46:47]
	global_load_dwordx4 v[40:43], v[58:59], off offset:256
	global_load_dwordx4 v[44:47], v[60:61], off offset:256
	v_pk_mul_f32 v[60:61], v[32:33], v[146:147] op_sel_hi:[1,0]
	v_mul_f32_e32 v32, 0xbfb8aa3b, v36
	v_mul_f32_e32 v33, 0xbfb8aa3b, v37
	v_exp_f32_e32 v32, v32
	v_exp_f32_e32 v33, v33
	v_pk_mul_f32 v[52:53], v[52:53], v[52:53]
	v_pk_mul_f32 v[54:55], v[54:55], v[54:55]
	v_pk_add_f32 v[32:33], v[32:33], 1.0 op_sel_hi:[1,0]
	s_waitcnt vmcnt(1)
	v_lshlrev_b32_e32 v62, 16, v40
	v_and_b32_e32 v63, 0xffff0000, v40
	s_waitcnt vmcnt(0)
	v_lshlrev_b32_e32 v36, 16, v44
	v_and_b32_e32 v37, 0xffff0000, v44
	s_nop 0
	v_rcp_f32_e32 v33, v33
	s_nop 0
	v_rcp_f32_e32 v32, v32
	s_nop 0
	v_pk_fma_f32 v[32:33], v[32:33], v[62:63], v[36:37]
	v_mul_f32_e32 v36, 0xbfb8aa3b, v38
	v_mul_f32_e32 v37, 0xbfb8aa3b, v39
	v_exp_f32_e32 v36, v36
	v_exp_f32_e32 v37, v37
	v_lshlrev_b32_e32 v38, 16, v45
	v_and_b32_e32 v39, 0xffff0000, v45
	v_lshlrev_b32_e32 v40, 16, v41
	v_pk_add_f32 v[36:37], v[36:37], 1.0 op_sel_hi:[1,0]
	v_and_b32_e32 v41, 0xffff0000, v41
	s_nop 0
	v_rcp_f32_e32 v37, v37
	s_nop 0
	v_rcp_f32_e32 v36, v36
	s_nop 0
	v_pk_fma_f32 v[36:37], v[36:37], v[40:41], v[38:39]
	v_mul_f32_e32 v38, 0xbfb8aa3b, v60
	v_mul_f32_e32 v39, 0xbfb8aa3b, v61
	v_exp_f32_e32 v38, v38
	v_exp_f32_e32 v39, v39
	v_lshlrev_b32_e32 v44, 16, v42
	v_and_b32_e32 v45, 0xffff0000, v42
	v_lshlrev_b32_e32 v40, 16, v46
	v_pk_add_f32 v[38:39], v[38:39], 1.0 op_sel_hi:[1,0]
	v_and_b32_e32 v41, 0xffff0000, v46
	s_nop 0
	v_rcp_f32_e32 v39, v39
	s_nop 0
	v_rcp_f32_e32 v38, v38
	s_nop 0
	v_pk_fma_f32 v[44:45], v[38:39], v[44:45], v[40:41]
	v_lshlrev_b32_e32 v40, 16, v43
	v_and_b32_e32 v41, 0xffff0000, v43
	v_lshlrev_b32_e32 v38, 16, v47
	v_and_b32_e32 v39, 0xffff0000, v47
	v_rcp_f32_e32 v35, v35
	s_nop 0
	v_rcp_f32_e32 v34, v34
	s_nop 0
	v_pk_fma_f32 v[34:35], v[34:35], v[40:41], v[38:39]
	v_cvt_pk_bf16_f32 v38, v32, v33
	v_cvt_pk_bf16_f32 v39, v36, v37
	v_cvt_pk_bf16_f32 v40, v44, v45
	v_cvt_pk_bf16_f32 v41, v34, v35
	global_store_dwordx4 v[58:59], v[38:41], off offset:256
	v_pk_mul_f32 v[34:35], v[34:35], v[34:35]
	v_pk_mul_f32 v[32:33], v[32:33], v[32:33]
	v_pk_mul_f32 v[38:39], v[44:45], v[44:45]
	v_pk_mul_f32 v[36:37], v[36:37], v[36:37]
	v_add_f32_e32 v40, v54, v55
	v_add_f32_e32 v41, v52, v53
	v_add_f32_e32 v34, v34, v35
	v_add_f32_e32 v35, v38, v39
	v_add_f32_e32 v40, v41, v40
	v_add_f32_e32 v41, v50, v51
	v_add_f32_e32 v42, v48, v49
	v_add_f32_e32 v34, v35, v34
	v_add_f32_e32 v35, v36, v37
	v_add_f32_e32 v32, v32, v33
	v_add_f32_e32 v41, v42, v41
	v_add_f32_e32 v32, v32, v35
	v_add_f32_e32 v40, v41, v40
	v_add_f32_e32 v32, v32, v34
	v_add_f32_e32 v32, v40, v32
	ds_bpermute_b32 v33, v169, v32
	s_waitcnt lgkmcnt(0)
	v_add_f32_e32 v32, v32, v33
	ds_bpermute_b32 v33, v155, v32
	s_and_saveexec_b64 s[0:1], s[46:47]
	s_cbranch_execz .LBB0_482
	s_waitcnt lgkmcnt(0)
	v_add_f32_e32 v34, v32, v33
	v_lshlrev_b64 v[32:33], 6, v[56:57]
	v_lshl_add_u64 v[32:33], s[6:7], 0, v[32:33]
	v_lshl_add_u64 v[32:33], s[42:43], 2, v[32:33]
	s_lshl_b32 s94, s35, 2
	v_lshl_add_u64 v[32:33], v[32:33], 0, s[94:95]
	global_store_dword v[32:33], v34, off
; DI unsigned pk2(float lo, float hi) { const f32x2_t v = {lo, hi}; const bf16x2_t b = __builtin_convertvector(v, bf16x2_t); return __builtin_bit_cast(unsigned, b); }
; DI float lo16(unsigned w) { return __uint_as_float(w << 16); }
; DI float hi16(unsigned w) { return __uint_as_float(w & 0xffff0000u); }
;     DI void operator()(const pg8::f32x4 (&acc)[2][2][4][2], const pg8::Unit& u, int wr, int wc, int fr, int fq) const {
;     ...
;             for (int m = 0; m < 4; ++m) {
;                 const int row = row0 + ai * 128 + m * 16; const float r = rs[ai][m];
;                 float part = 0.f;
; #pragma unroll
;                 for (int bj = 0; bj < 2; ++bj) { const size_t off = (size_t)row * 1024 + col0 + bj * 128;
;                     const u32x4 tw = *(const u32x4*)(T + off); const u32x4 xw = *(const u32x4*)(xr + off);
;                     const pg8::f32x4 a0 = acc[ai][bj][m][0] * r, a1 = acc[ai][bj][m][1] * r;
;                     const float o0 = lo16(xw.x) + lo16(tw.x) * __frcp_rn(1.0f + __expf(-a0[0])), o1 = hi16(xw.x) + hi16(tw.x) * __frcp_rn(1.0f + __expf(-a0[1]));
;                     const float o2 = lo16(xw.y) + lo16(tw.y) * __frcp_rn(1.0f + __expf(-a0[2])), o3 = hi16(xw.y) + hi16(tw.y) * __frcp_rn(1.0f + __expf(-a0[3]));
;                     const float o4 = lo16(xw.z) + lo16(tw.z) * __frcp_rn(1.0f + __expf(-a1[0])), o5 = hi16(xw.z) + hi16(tw.z) * __frcp_rn(1.0f + __expf(-a1[1]));
;                     const float o6 = lo16(xw.w) + lo16(tw.w) * __frcp_rn(1.0f + __expf(-a1[2])), o7 = hi16(xw.w) + hi16(tw.w) * __frcp_rn(1.0f + __expf(-a1[3]));
;                     u32x4 w; w.x = pk2(o0, o1); w.y = pk2(o2, o3); w.z = pk2(o4, o5); w.w = pk2(o6, o7); *(u32x4*)(xbo + off) = w;
;                     part += ((o0 * o0 + o1 * o1) + (o2 * o2 + o3 * o3)) + ((o4 * o4 + o5 * o5) + (o6 * o6 + o7 * o7)); }
;                 part += __shfl_xor(part, 16); part += __shfl_xor(part, 32);
;                 if (ssout && fq == 0) ssout[(size_t)row * 16 + u.pn * 4 + wc] = part;
.LBB0_482:
	s_or_b64 exec, exec, s[0:1]
	v_add_u32_e32 v40, 0xa0, v142
	v_ashrrev_i32_e32 v41, 31, v40
	s_waitcnt lgkmcnt(0)
	v_lshlrev_b64 v[32:33], 10, v[40:41]
	v_lshl_add_u64 v[32:33], v[32:33], 0, v[140:141]
	v_lshlrev_b64 v[36:37], 1, v[32:33]
	v_lshl_add_u64 v[42:43], s[18:19], 0, v[36:37]
	global_load_dwordx4 v[32:35], v[42:43], off
	v_lshl_add_u64 v[44:45], s[12:13], 0, v[36:37]
	global_load_dwordx4 v[36:39], v[44:45], off
	v_pk_mul_f32 v[28:29], v[28:29], v[144:145] op_sel_hi:[1,0]
	v_pk_mul_f32 v[46:47], v[24:25], v[144:145] op_sel_hi:[1,0]
	v_mul_f32_e32 v24, 0xbfb8aa3b, v28
	v_mul_f32_e32 v25, 0xbfb8aa3b, v29
	v_exp_f32_e32 v24, v24
	v_exp_f32_e32 v25, v25
	v_pk_mul_f32 v[30:31], v[30:31], v[144:145] op_sel_hi:[1,0]
	v_pk_mul_f32 v[26:27], v[26:27], v[144:145] op_sel_hi:[1,0]
	v_pk_mul_f32 v[20:21], v[20:21], v[144:145] op_sel_hi:[1,0]
	v_pk_add_f32 v[24:25], v[24:25], 1.0 op_sel_hi:[1,0]
	v_mul_f32_e32 v26, 0xbfb8aa3b, v26
	v_mul_f32_e32 v27, 0xbfb8aa3b, v27
	v_exp_f32_e32 v26, v26
	v_exp_f32_e32 v27, v27
	v_pk_mul_f32 v[22:23], v[22:23], v[144:145] op_sel_hi:[1,0]
	v_pk_mul_f32 v[18:19], v[18:19], v[144:145] op_sel_hi:[1,0]
	v_pk_add_f32 v[26:27], v[26:27], 1.0 op_sel_hi:[1,0]
	v_mul_f32_e32 v18, 0xbfb8aa3b, v18
	v_mul_f32_e32 v19, 0xbfb8aa3b, v19
	v_exp_f32_e32 v18, v18
	v_exp_f32_e32 v19, v19
	s_waitcnt vmcnt(1)
	v_lshlrev_b32_e32 v48, 16, v32
	v_and_b32_e32 v49, 0xffff0000, v32
	s_waitcnt vmcnt(0)
	v_lshlrev_b32_e32 v28, 16, v36
	v_and_b32_e32 v29, 0xffff0000, v36
	v_pk_add_f32 v[18:19], v[18:19], 1.0 op_sel_hi:[1,0]
	v_rcp_f32_e32 v25, v25
	s_nop 0
	v_rcp_f32_e32 v24, v24
	s_nop 0
	v_pk_fma_f32 v[24:25], v[24:25], v[48:49], v[28:29]
	v_mul_f32_e32 v28, 0xbfb8aa3b, v30
	v_mul_f32_e32 v29, 0xbfb8aa3b, v31
	v_exp_f32_e32 v28, v28
	v_exp_f32_e32 v29, v29
	v_lshlrev_b32_e32 v30, 16, v37
	v_and_b32_e32 v31, 0xffff0000, v37
	v_lshlrev_b32_e32 v32, 16, v33
	v_pk_add_f32 v[28:29], v[28:29], 1.0 op_sel_hi:[1,0]
	v_and_b32_e32 v33, 0xffff0000, v33
	s_nop 0
	v_rcp_f32_e32 v29, v29
	s_nop 0
	v_rcp_f32_e32 v28, v28
	s_nop 0
	v_pk_fma_f32 v[30:31], v[28:29], v[32:33], v[30:31]
	v_mul_f32_e32 v28, 0xbfb8aa3b, v46
	v_mul_f32_e32 v29, 0xbfb8aa3b, v47
	v_exp_f32_e32 v28, v28
	v_exp_f32_e32 v29, v29
	v_lshlrev_b32_e32 v36, 16, v34
	v_and_b32_e32 v37, 0xffff0000, v34
	v_lshlrev_b32_e32 v32, 16, v38
	v_pk_add_f32 v[28:29], v[28:29], 1.0 op_sel_hi:[1,0]
	v_and_b32_e32 v33, 0xffff0000, v38
	s_nop 0
	v_rcp_f32_e32 v29, v29
	s_nop 0
	v_rcp_f32_e32 v28, v28
	s_nop 0
	v_pk_fma_f32 v[36:37], v[28:29], v[36:37], v[32:33]
	v_lshlrev_b32_e32 v32, 16, v35
	v_and_b32_e32 v33, 0xffff0000, v35
	v_lshlrev_b32_e32 v28, 16, v39
	v_and_b32_e32 v29, 0xffff0000, v39
	v_rcp_f32_e32 v27, v27
	s_nop 0
	v_rcp_f32_e32 v26, v26
	s_nop 0
	v_pk_fma_f32 v[38:39], v[26:27], v[32:33], v[28:29]
	v_cvt_pk_bf16_f32 v26, v24, v25
	v_cvt_pk_bf16_f32 v27, v30, v31
	v_cvt_pk_bf16_f32 v28, v36, v37
	v_cvt_pk_bf16_f32 v29, v38, v39
	global_store_dwordx4 v[42:43], v[26:29], off
	v_pk_mul_f32 v[32:33], v[24:25], v[24:25]
	v_pk_mul_f32 v[34:35], v[30:31], v[30:31]
	global_load_dwordx4 v[24:27], v[42:43], off offset:256
	global_load_dwordx4 v[28:31], v[44:45], off offset:256
	v_pk_mul_f32 v[44:45], v[16:17], v[144:145] op_sel_hi:[1,0]
	v_mul_f32_e32 v16, 0xbfb8aa3b, v20
	v_mul_f32_e32 v17, 0xbfb8aa3b, v21
	v_exp_f32_e32 v16, v16
	v_exp_f32_e32 v17, v17
	v_pk_mul_f32 v[36:37], v[36:37], v[36:37]
	v_pk_mul_f32 v[38:39], v[38:39], v[38:39]
	v_pk_add_f32 v[16:17], v[16:17], 1.0 op_sel_hi:[1,0]
	s_waitcnt vmcnt(1)
	v_lshlrev_b32_e32 v46, 16, v24
	v_and_b32_e32 v47, 0xffff0000, v24
	s_waitcnt vmcnt(0)
	v_lshlrev_b32_e32 v20, 16, v28
	v_and_b32_e32 v21, 0xffff0000, v28
	s_nop 0
	v_rcp_f32_e32 v17, v17
	s_nop 0
	v_rcp_f32_e32 v16, v16
	s_nop 0
	v_pk_fma_f32 v[16:17], v[16:17], v[46:47], v[20:21]
	v_mul_f32_e32 v20, 0xbfb8aa3b, v22
	v_mul_f32_e32 v21, 0xbfb8aa3b, v23
	v_exp_f32_e32 v20, v20
	v_exp_f32_e32 v21, v21
	v_lshlrev_b32_e32 v22, 16, v29
	v_and_b32_e32 v23, 0xffff0000, v29
	v_lshlrev_b32_e32 v24, 16, v25
	v_pk_add_f32 v[20:21], v[20:21], 1.0 op_sel_hi:[1,0]
	v_and_b32_e32 v25, 0xffff0000, v25
	s_nop 0
	v_rcp_f32_e32 v21, v21
	s_nop 0
	v_rcp_f32_e32 v20, v20
	s_nop 0
	v_pk_fma_f32 v[20:21], v[20:21], v[24:25], v[22:23]
	v_mul_f32_e32 v22, 0xbfb8aa3b, v44
	v_mul_f32_e32 v23, 0xbfb8aa3b, v45
	v_exp_f32_e32 v22, v22
	v_exp_f32_e32 v23, v23
	v_lshlrev_b32_e32 v28, 16, v26
	v_and_b32_e32 v29, 0xffff0000, v26
	v_lshlrev_b32_e32 v24, 16, v30
	v_pk_add_f32 v[22:23], v[22:23], 1.0 op_sel_hi:[1,0]
	v_and_b32_e32 v25, 0xffff0000, v30
	s_nop 0
	v_rcp_f32_e32 v23, v23
	s_nop 0
	v_rcp_f32_e32 v22, v22
	s_nop 0
	v_pk_fma_f32 v[28:29], v[22:23], v[28:29], v[24:25]
	v_lshlrev_b32_e32 v24, 16, v27
	v_and_b32_e32 v25, 0xffff0000, v27
	v_lshlrev_b32_e32 v22, 16, v31
	v_and_b32_e32 v23, 0xffff0000, v31
	v_rcp_f32_e32 v19, v19
	s_nop 0
	v_rcp_f32_e32 v18, v18
	s_nop 0
	v_pk_fma_f32 v[18:19], v[18:19], v[24:25], v[22:23]
	v_cvt_pk_bf16_f32 v22, v16, v17
	v_cvt_pk_bf16_f32 v23, v20, v21
	v_cvt_pk_bf16_f32 v24, v28, v29
	v_cvt_pk_bf16_f32 v25, v18, v19
	global_store_dwordx4 v[42:43], v[22:25], off offset:256
	v_pk_mul_f32 v[18:19], v[18:19], v[18:19]
	v_pk_mul_f32 v[16:17], v[16:17], v[16:17]
	v_pk_mul_f32 v[22:23], v[28:29], v[28:29]
	v_pk_mul_f32 v[20:21], v[20:21], v[20:21]
	v_add_f32_e32 v24, v38, v39
	v_add_f32_e32 v25, v36, v37
	v_add_f32_e32 v18, v18, v19
	v_add_f32_e32 v19, v22, v23
	v_add_f32_e32 v24, v25, v24
	v_add_f32_e32 v25, v34, v35
	v_add_f32_e32 v26, v32, v33
	v_add_f32_e32 v18, v19, v18
	v_add_f32_e32 v19, v20, v21
	v_add_f32_e32 v16, v16, v17
	v_add_f32_e32 v25, v26, v25
	v_add_f32_e32 v16, v16, v19
	v_add_f32_e32 v24, v25, v24
	v_add_f32_e32 v16, v16, v18
	v_add_f32_e32 v16, v24, v16
	ds_bpermute_b32 v17, v169, v16
	s_waitcnt lgkmcnt(0)
	v_add_f32_e32 v16, v16, v17
	ds_bpermute_b32 v17, v155, v16
	s_and_saveexec_b64 s[0:1], s[46:47]
	s_cbranch_execz .LBB0_484
	s_waitcnt lgkmcnt(0)
	v_add_f32_e32 v18, v16, v17
	v_lshlrev_b64 v[16:17], 6, v[40:41]
	v_lshl_add_u64 v[16:17], s[6:7], 0, v[16:17]
	v_lshl_add_u64 v[16:17], s[42:43], 2, v[16:17]
	s_lshl_b32 s94, s35, 2
	v_lshl_add_u64 v[16:17], v[16:17], 0, s[94:95]
	global_store_dword v[16:17], v18, off
; DI unsigned pk2(float lo, float hi) { const f32x2_t v = {lo, hi}; const bf16x2_t b = __builtin_convertvector(v, bf16x2_t); return __builtin_bit_cast(unsigned, b); }
; DI float lo16(unsigned w) { return __uint_as_float(w << 16); }
; DI float hi16(unsigned w) { return __uint_as_float(w & 0xffff0000u); }
;     DI void operator()(const pg8::f32x4 (&acc)[2][2][4][2], const pg8::Unit& u, int wr, int wc, int fr, int fq) const {
;     ...
;                 const int row = row0 + ai * 128 + m * 16; const float r = rs[ai][m];
;                 float part = 0.f;
; #pragma unroll
;                 for (int bj = 0; bj < 2; ++bj) { const size_t off = (size_t)row * 1024 + col0 + bj * 128;
;                     const u32x4 tw = *(const u32x4*)(T + off); const u32x4 xw = *(const u32x4*)(xr + off);
;                     const pg8::f32x4 a0 = acc[ai][bj][m][0] * r, a1 = acc[ai][bj][m][1] * r;
;                     const float o0 = lo16(xw.x) + lo16(tw.x) * __frcp_rn(1.0f + __expf(-a0[0])), o1 = hi16(xw.x) + hi16(tw.x) * __frcp_rn(1.0f + __expf(-a0[1]));
;                     const float o2 = lo16(xw.y) + lo16(tw.y) * __frcp_rn(1.0f + __expf(-a0[2])), o3 = hi16(xw.y) + hi16(tw.y) * __frcp_rn(1.0f + __expf(-a0[3]));
;                     const float o4 = lo16(xw.z) + lo16(tw.z) * __frcp_rn(1.0f + __expf(-a1[0])), o5 = hi16(xw.z) + hi16(tw.z) * __frcp_rn(1.0f + __expf(-a1[1]));
;                     const float o6 = lo16(xw.w) + lo16(tw.w) * __frcp_rn(1.0f + __expf(-a1[2])), o7 = hi16(xw.w) + hi16(tw.w) * __frcp_rn(1.0f + __expf(-a1[3]));
;                     u32x4 w; w.x = pk2(o0, o1); w.y = pk2(o2, o3); w.z = pk2(o4, o5); w.w = pk2(o6, o7); *(u32x4*)(xbo + off) = w;
;                     part += ((o0 * o0 + o1 * o1) + (o2 * o2 + o3 * o3)) + ((o4 * o4 + o5 * o5) + (o6 * o6 + o7 * o7)); }
;                 part += __shfl_xor(part, 16); part += __shfl_xor(part, 32);
;                 if (ssout && fq == 0) ssout[(size_t)row * 16 + u.pn * 4 + wc] = part;
.LBB0_484:
	s_or_b64 exec, exec, s[0:1]
	v_add_u32_e32 v24, 0xb0, v142
	v_ashrrev_i32_e32 v25, 31, v24
	s_waitcnt lgkmcnt(0)
	v_lshlrev_b64 v[16:17], 10, v[24:25]
	v_lshl_add_u64 v[16:17], v[16:17], 0, v[140:141]
	v_lshlrev_b64 v[20:21], 1, v[16:17]
	v_lshl_add_u64 v[26:27], s[18:19], 0, v[20:21]
	global_load_dwordx4 v[16:19], v[26:27], off
	v_lshl_add_u64 v[28:29], s[12:13], 0, v[20:21]
	global_load_dwordx4 v[20:23], v[28:29], off
	v_pk_mul_f32 v[12:13], v[12:13], v[138:139] op_sel_hi:[1,0]
	v_pk_mul_f32 v[30:31], v[8:9], v[138:139] op_sel_hi:[1,0]
	v_mul_f32_e32 v8, 0xbfb8aa3b, v12
	v_mul_f32_e32 v9, 0xbfb8aa3b, v13
	v_exp_f32_e32 v8, v8
	v_exp_f32_e32 v9, v9
	v_pk_mul_f32 v[14:15], v[14:15], v[138:139] op_sel_hi:[1,0]
	v_pk_mul_f32 v[10:11], v[10:11], v[138:139] op_sel_hi:[1,0]
	v_pk_mul_f32 v[4:5], v[4:5], v[138:139] op_sel_hi:[1,0]
	v_pk_add_f32 v[8:9], v[8:9], 1.0 op_sel_hi:[1,0]
	v_mul_f32_e32 v10, 0xbfb8aa3b, v10
	v_mul_f32_e32 v11, 0xbfb8aa3b, v11
	v_exp_f32_e32 v10, v10
	v_exp_f32_e32 v11, v11
	v_pk_mul_f32 v[6:7], v[6:7], v[138:139] op_sel_hi:[1,0]
	v_pk_mul_f32 v[2:3], v[2:3], v[138:139] op_sel_hi:[1,0]
	v_pk_add_f32 v[10:11], v[10:11], 1.0 op_sel_hi:[1,0]
	v_mul_f32_e32 v2, 0xbfb8aa3b, v2
	v_mul_f32_e32 v3, 0xbfb8aa3b, v3
	v_exp_f32_e32 v2, v2
	v_exp_f32_e32 v3, v3
	s_waitcnt vmcnt(1)
	v_lshlrev_b32_e32 v32, 16, v16
	v_and_b32_e32 v33, 0xffff0000, v16
	s_waitcnt vmcnt(0)
	v_lshlrev_b32_e32 v12, 16, v20
	v_and_b32_e32 v13, 0xffff0000, v20
	v_pk_add_f32 v[2:3], v[2:3], 1.0 op_sel_hi:[1,0]
	v_rcp_f32_e32 v9, v9
	s_nop 0
	v_rcp_f32_e32 v8, v8
	s_nop 0
	v_pk_fma_f32 v[8:9], v[8:9], v[32:33], v[12:13]
	v_mul_f32_e32 v12, 0xbfb8aa3b, v14
	v_mul_f32_e32 v13, 0xbfb8aa3b, v15
	v_exp_f32_e32 v12, v12
	v_exp_f32_e32 v13, v13
	v_lshlrev_b32_e32 v14, 16, v21
	v_and_b32_e32 v15, 0xffff0000, v21
	v_lshlrev_b32_e32 v16, 16, v17
	v_pk_add_f32 v[12:13], v[12:13], 1.0 op_sel_hi:[1,0]
	v_and_b32_e32 v17, 0xffff0000, v17
	s_nop 0
	v_rcp_f32_e32 v13, v13
	s_nop 0
	v_rcp_f32_e32 v12, v12
	s_nop 0
	v_pk_fma_f32 v[14:15], v[12:13], v[16:17], v[14:15]
	v_mul_f32_e32 v12, 0xbfb8aa3b, v30
	v_mul_f32_e32 v13, 0xbfb8aa3b, v31
	v_exp_f32_e32 v12, v12
	v_exp_f32_e32 v13, v13
	v_lshlrev_b32_e32 v20, 16, v18
	v_and_b32_e32 v21, 0xffff0000, v18
	v_lshlrev_b32_e32 v16, 16, v22
	v_pk_add_f32 v[12:13], v[12:13], 1.0 op_sel_hi:[1,0]
	v_and_b32_e32 v17, 0xffff0000, v22
	s_nop 0
	v_rcp_f32_e32 v13, v13
	s_nop 0
	v_rcp_f32_e32 v12, v12
	s_nop 0
	v_pk_fma_f32 v[20:21], v[12:13], v[20:21], v[16:17]
	v_lshlrev_b32_e32 v16, 16, v19
	v_and_b32_e32 v17, 0xffff0000, v19
	v_lshlrev_b32_e32 v12, 16, v23
	v_and_b32_e32 v13, 0xffff0000, v23
	v_rcp_f32_e32 v11, v11
	s_nop 0
	v_rcp_f32_e32 v10, v10
	s_nop 0
	v_pk_fma_f32 v[22:23], v[10:11], v[16:17], v[12:13]
	v_cvt_pk_bf16_f32 v10, v8, v9
	v_cvt_pk_bf16_f32 v11, v14, v15
	v_cvt_pk_bf16_f32 v12, v20, v21
	v_cvt_pk_bf16_f32 v13, v22, v23
	global_store_dwordx4 v[26:27], v[10:13], off
	v_pk_mul_f32 v[16:17], v[8:9], v[8:9]
	v_pk_mul_f32 v[18:19], v[14:15], v[14:15]
	global_load_dwordx4 v[8:11], v[26:27], off offset:256
	global_load_dwordx4 v[12:15], v[28:29], off offset:256
	v_pk_mul_f32 v[28:29], v[0:1], v[138:139] op_sel_hi:[1,0]
	v_mul_f32_e32 v0, 0xbfb8aa3b, v4
	v_mul_f32_e32 v1, 0xbfb8aa3b, v5
	v_exp_f32_e32 v0, v0
	v_exp_f32_e32 v1, v1
	v_pk_mul_f32 v[20:21], v[20:21], v[20:21]
	v_pk_mul_f32 v[22:23], v[22:23], v[22:23]
	v_pk_add_f32 v[0:1], v[0:1], 1.0 op_sel_hi:[1,0]
	s_waitcnt vmcnt(1)
	v_lshlrev_b32_e32 v30, 16, v8
	v_and_b32_e32 v31, 0xffff0000, v8
	s_waitcnt vmcnt(0)
	v_lshlrev_b32_e32 v4, 16, v12
	v_and_b32_e32 v5, 0xffff0000, v12
	s_nop 0
	v_rcp_f32_e32 v1, v1
	s_nop 0
	v_rcp_f32_e32 v0, v0
	s_nop 0
	v_pk_fma_f32 v[0:1], v[0:1], v[30:31], v[4:5]
	v_mul_f32_e32 v4, 0xbfb8aa3b, v6
	v_mul_f32_e32 v5, 0xbfb8aa3b, v7
	v_exp_f32_e32 v4, v4
	v_exp_f32_e32 v5, v5
	v_lshlrev_b32_e32 v6, 16, v13
	v_and_b32_e32 v7, 0xffff0000, v13
	v_lshlrev_b32_e32 v8, 16, v9
	v_pk_add_f32 v[4:5], v[4:5], 1.0 op_sel_hi:[1,0]
	v_and_b32_e32 v9, 0xffff0000, v9
	s_nop 0
	v_rcp_f32_e32 v5, v5
	s_nop 0
	v_rcp_f32_e32 v4, v4
	s_nop 0
	v_pk_fma_f32 v[4:5], v[4:5], v[8:9], v[6:7]
	v_mul_f32_e32 v6, 0xbfb8aa3b, v28
	v_mul_f32_e32 v7, 0xbfb8aa3b, v29
	v_exp_f32_e32 v6, v6
	v_exp_f32_e32 v7, v7
	v_lshlrev_b32_e32 v12, 16, v10
	v_and_b32_e32 v13, 0xffff0000, v10
	v_lshlrev_b32_e32 v8, 16, v14
	v_pk_add_f32 v[6:7], v[6:7], 1.0 op_sel_hi:[1,0]
	v_and_b32_e32 v9, 0xffff0000, v14
	s_nop 0
	v_rcp_f32_e32 v7, v7
	s_nop 0
	v_rcp_f32_e32 v6, v6
	s_nop 0
	v_pk_fma_f32 v[12:13], v[6:7], v[12:13], v[8:9]
	v_lshlrev_b32_e32 v8, 16, v11
	v_and_b32_e32 v9, 0xffff0000, v11
	v_lshlrev_b32_e32 v6, 16, v15
	v_and_b32_e32 v7, 0xffff0000, v15
	v_rcp_f32_e32 v3, v3
	s_nop 0
	v_rcp_f32_e32 v2, v2
	s_nop 0
	v_pk_fma_f32 v[2:3], v[2:3], v[8:9], v[6:7]
	v_cvt_pk_bf16_f32 v6, v0, v1
	v_cvt_pk_bf16_f32 v7, v4, v5
	v_cvt_pk_bf16_f32 v8, v12, v13
	v_cvt_pk_bf16_f32 v9, v2, v3
	global_store_dwordx4 v[26:27], v[6:9], off offset:256
	v_pk_mul_f32 v[2:3], v[2:3], v[2:3]
	v_pk_mul_f32 v[0:1], v[0:1], v[0:1]
	v_pk_mul_f32 v[6:7], v[12:13], v[12:13]
	v_pk_mul_f32 v[4:5], v[4:5], v[4:5]
	v_add_f32_e32 v8, v22, v23
	v_add_f32_e32 v9, v20, v21
	v_add_f32_e32 v2, v2, v3
	v_add_f32_e32 v3, v6, v7
	v_add_f32_e32 v8, v9, v8
	v_add_f32_e32 v9, v18, v19
	v_add_f32_e32 v10, v16, v17
	v_add_f32_e32 v2, v3, v2
	v_add_f32_e32 v3, v4, v5
	v_add_f32_e32 v0, v0, v1
	v_add_f32_e32 v9, v10, v9
	v_add_f32_e32 v0, v0, v3
	v_add_f32_e32 v8, v9, v8
	v_add_f32_e32 v0, v0, v2
	v_add_f32_e32 v0, v8, v0
	ds_bpermute_b32 v1, v169, v0
	s_waitcnt lgkmcnt(0)
	v_add_f32_e32 v0, v0, v1
	ds_bpermute_b32 v1, v155, v0
	s_and_saveexec_b64 s[0:1], s[46:47]
	s_cbranch_execz .LBB0_486
	s_waitcnt lgkmcnt(0)
	v_add_f32_e32 v2, v0, v1
	v_lshlrev_b64 v[0:1], 6, v[24:25]
	v_lshl_add_u64 v[0:1], s[6:7], 0, v[0:1]
	v_lshl_add_u64 v[0:1], s[42:43], 2, v[0:1]
	s_lshl_b32 s94, s35, 2
	v_lshl_add_u64 v[0:1], v[0:1], 0, s[94:95]
	global_store_dword v[0:1], v2, off

; #define LAS __attribute__((address_space(3)))
; #define BX mk_bx()
; DI void lds_barrier() { asm volatile("s_waitcnt lgkmcnt(0)\n\ts_barrier" ::: "memory"); }
; template <class Epi> DI void small_gemm(LAS unsigned char* lds, const bf16_t* A, const bf16_t* Bt, int K, const Epi& E, int G, const int tid) {
;     ...
;     for (int u = BX; u < 256; u += G) {
;         const int rg = u & 15, slot = u >> 4, cA = (slot >> 2) * 256 + (slot & 3) * 32;
;         const bf16_t* ap = A + (size_t)(RP + 32 * rg + r) * K + w * kw + 8 * h;
;         const bf16_t* b0 = Bt + (size_t)(cA + r) * K + w * kw + 8 * h;
;         const bf16_t* b1 = b0 + (size_t)128 * K;
;         f32x16 acc0, acc1;
; #pragma unroll
;         for (int i = 0; i < 16; ++i) { acc0[i] = 0.f; acc1[i] = 0.f; }
;         for (int ks = 0; ks < nks; ks += 2) {
;             const bf16x8 a0 = *(const bf16x8*)(ap + 16 * ks), a1 = *(const bf16x8*)(ap + 16 * ks + 16);
;             const bf16x8 w00 = *(const bf16x8*)(b0 + 16 * ks), w01 = *(const bf16x8*)(b0 + 16 * ks + 16);
;             const bf16x8 w10 = *(const bf16x8*)(b1 + 16 * ks), w11 = *(const bf16x8*)(b1 + 16 * ks + 16);
;             acc0 = __builtin_amdgcn_mfma_f32_32x32x16_bf16(w00, a0, acc0, 0, 0, 0); acc1 = __builtin_amdgcn_mfma_f32_32x32x16_bf16(w10, a0, acc1, 0, 0, 0);
;             acc0 = __builtin_amdgcn_mfma_f32_32x32x16_bf16(w01, a1, acc0, 0, 0, 0); acc1 = __builtin_amdgcn_mfma_f32_32x32x16_bf16(w11, a1, acc1, 0, 0, 0);
;         }
; #pragma unroll
;         for (int g = 0; g < 4; ++g) {
;             *(LAS f32x4*)(red + (((w * 2 + 0) * 4 + g) * 64 + lane) * 4) = (f32x4){acc0[4 * g], acc0[4 * g + 1], acc0[4 * g + 2], acc0[4 * g + 3]};
;             *(LAS f32x4*)(red + (((w * 2 + 1) * 4 + g) * 64 + lane) * 4) = (f32x4){acc1[4 * g], acc1[4 * g + 1], acc1[4 * g + 2], acc1[4 * g + 3]};
;         }
;         lds_barrier();
.LBB0_493:
	s_ashr_i32 s2, s16, 4
	s_lshl_b32 s14, s2, 5
	s_and_b32 s3, s21, 0xffffff00
	s_and_b32 s14, s14, 0x60
	s_or_b32 s14, s14, s3
	v_or_b32_e32 v0, s14, v36
	s_and_b32 s3, s20, 0x1e0
	s_waitcnt lgkmcnt(0)
	v_ashrrev_i32_e32 v1, 31, v0
	s_bitset1_b32 s3, 16
	v_lshlrev_b64 v[0:1], 11, v[0:1]
	v_or_b32_e32 v42, s3, v36
	s_waitcnt vmcnt(0)
	v_lshl_add_u64 v[68:69], v[34:35], 0, v[0:1]
	s_mov_b32 s15, 0x40000
	v_lshlrev_b32_e32 v0, 11, v42
	v_mov_b32_e32 v1, v161
	v_add_co_u32_e32 v72, vcc, s15, v68
	v_lshl_add_u64 v[70:71], v[32:33], 0, v[0:1]
	s_nop 0
	v_addc_co_u32_e32 v73, vcc, 0, v69, vcc
	global_load_dwordx4 v[16:19], v[70:71], off
	global_load_dwordx4 v[44:47], v[70:71], off offset:32
	global_load_dwordx4 v[0:3], v[68:69], off
	global_load_dwordx4 v[48:51], v[68:69], off offset:32
	global_load_dwordx4 v[20:23], v[72:73], off
	global_load_dwordx4 v[52:55], v[72:73], off offset:32
	v_add_u32_e32 v43, s17, v37
	v_lshlrev_b32_e32 v160, 10, v42
	s_waitcnt vmcnt(3)
	v_mfma_f32_32x32x16_bf16 v[0:15], v[0:3], v[16:19], 0
	s_waitcnt vmcnt(1)
	v_mfma_f32_32x32x16_bf16 v[16:31], v[20:23], v[16:19], 0
	v_mfma_f32_32x32x16_bf16 v[0:15], v[48:51], v[44:47], v[0:15]
	s_waitcnt vmcnt(0)
	v_mfma_f32_32x32x16_bf16 v[16:31], v[52:55], v[44:47], v[16:31]
	global_load_dwordx4 v[44:47], v[70:71], off offset:64
	global_load_dwordx4 v[48:51], v[70:71], off offset:96
	global_load_dwordx4 v[52:55], v[68:69], off offset:64
	global_load_dwordx4 v[56:59], v[68:69], off offset:96
	global_load_dwordx4 v[60:63], v[72:73], off offset:64
	global_load_dwordx4 v[64:67], v[72:73], off offset:96
	s_waitcnt vmcnt(3)
	v_mfma_f32_32x32x16_bf16 v[0:15], v[52:55], v[44:47], v[0:15]
	s_waitcnt vmcnt(1)
	v_mfma_f32_32x32x16_bf16 v[16:31], v[60:63], v[44:47], v[16:31]
	v_mfma_f32_32x32x16_bf16 v[0:15], v[56:59], v[48:51], v[0:15]
	s_waitcnt vmcnt(0)
	v_mfma_f32_32x32x16_bf16 v[16:31], v[64:67], v[48:51], v[16:31]
	global_load_dwordx4 v[44:47], v[70:71], off offset:128
	global_load_dwordx4 v[48:51], v[70:71], off offset:160
	global_load_dwordx4 v[52:55], v[68:69], off offset:128
	global_load_dwordx4 v[56:59], v[68:69], off offset:160
	global_load_dwordx4 v[60:63], v[72:73], off offset:128
	global_load_dwordx4 v[64:67], v[72:73], off offset:160
	s_waitcnt vmcnt(3)
	v_mfma_f32_32x32x16_bf16 v[0:15], v[52:55], v[44:47], v[0:15]
	s_waitcnt vmcnt(1)
	v_mfma_f32_32x32x16_bf16 v[16:31], v[60:63], v[44:47], v[16:31]
	v_mfma_f32_32x32x16_bf16 v[0:15], v[56:59], v[48:51], v[0:15]
	s_waitcnt vmcnt(0)
	v_mfma_f32_32x32x16_bf16 v[16:31], v[64:67], v[48:51], v[16:31]
	global_load_dwordx4 v[44:47], v[70:71], off offset:192
	global_load_dwordx4 v[48:51], v[70:71], off offset:224
	global_load_dwordx4 v[52:55], v[68:69], off offset:192
	global_load_dwordx4 v[56:59], v[68:69], off offset:224
	global_load_dwordx4 v[60:63], v[72:73], off offset:192
	global_load_dwordx4 v[64:67], v[72:73], off offset:224
	s_waitcnt vmcnt(3)
	v_mfma_f32_32x32x16_bf16 v[0:15], v[52:55], v[44:47], v[0:15]
	s_waitcnt vmcnt(1)
	v_mfma_f32_32x32x16_bf16 v[16:31], v[60:63], v[44:47], v[16:31]
	v_mfma_f32_32x32x16_bf16 v[0:15], v[56:59], v[48:51], v[0:15]
	s_waitcnt vmcnt(0)
	v_mfma_f32_32x32x16_bf16 v[16:31], v[64:67], v[48:51], v[16:31]
	s_nop 9
	ds_write_b128 v43, v[0:3]
	s_nop 0
	ds_write_b128 v43, v[16:19] offset:4096
	ds_write_b128 v43, v[4:7] offset:1024
	ds_write_b128 v43, v[20:23] offset:5120
	ds_write_b128 v43, v[8:11] offset:2048
	ds_write_b128 v43, v[24:27] offset:6144
	ds_write_b128 v43, v[12:15] offset:3072
	ds_write_b128 v43, v[28:31] offset:7168
	s_waitcnt lgkmcnt(0)
	s_barrier
; #define LAS __attribute__((address_space(3)))
; DI unsigned pk2(float lo, float hi) { const f32x2_t v = {lo, hi}; const bf16x2_t b = __builtin_convertvector(v, bf16x2_t); return __builtin_bit_cast(unsigned, b); }
; DI float lo16(unsigned w) { return __uint_as_float(w << 16); }
; DI float hi16(unsigned w) { return __uint_as_float(w & 0xffff0000u); }
;     DI float small(int row, int col, const pg8::f32x4& v) const {
;         const float r = rowscale(ss, row); const size_t off = (size_t)row * 1024 + col;
;         const u32x2 tw = *(const u32x2*)(T + off); const u32x2 xw = *(const u32x2*)(xr + off);
;         const float o0 = lo16(xw.x) + lo16(tw.x) * __frcp_rn(1.0f + __expf(-v[0] * r)), o1 = hi16(xw.x) + hi16(tw.x) * __frcp_rn(1.0f + __expf(-v[1] * r));
;         const float o2 = lo16(xw.y) + lo16(tw.y) * __frcp_rn(1.0f + __expf(-v[2] * r)), o3 = hi16(xw.y) + hi16(tw.y) * __frcp_rn(1.0f + __expf(-v[3] * r));
;         u32x2 w; w.x = pk2(o0, o1); w.y = pk2(o2, o3); *(u32x2*)(xbo + off) = w;
;         return (o0 * o0 + o1 * o1) + (o2 * o2 + o3 * o3);
;     }
; template <class Epi> DI void small_gemm(LAS unsigned char* lds, const bf16_t* A, const bf16_t* Bt, int K, const Epi& E, int G, const int tid) {
;     ...
;         const int tile = w >> 2, g = w & 3;
;         f32x4 v = (f32x4){0.f, 0.f, 0.f, 0.f};
; #pragma unroll
;         for (int ww = 0; ww < 8; ++ww) v += *(const LAS f32x4*)(red + (((ww * 2 + tile) * 4 + g) * 64 + lane) * 4);
;         const int row = RP + 32 * rg + r, col = cA + tile * 128 + 8 * g + 4 * h;
;         float part = E.small(row, col, pg8::f32x4{v[0], v[1], v[2], v[3]});
;         part += __shfl_xor(part, 32);
;         if (h == 0) ssred[w * 32 + r] = part;
	ds_read_b128 v[0:3], v40
	s_waitcnt lgkmcnt(0)
	v_pk_add_f32 v[4:5], v[2:3], 0 op_sel_hi:[1,0]
	v_pk_add_f32 v[6:7], v[0:1], 0 op_sel_hi:[1,0]
	ds_read_b128 v[0:3], v40 offset:8192
	s_waitcnt lgkmcnt(0)
	v_pk_add_f32 v[4:5], v[4:5], v[2:3]
	v_pk_add_f32 v[6:7], v[6:7], v[0:1]
	ds_read_b128 v[0:3], v40 offset:16384
	s_waitcnt lgkmcnt(0)
	v_pk_add_f32 v[4:5], v[4:5], v[2:3]
	v_pk_add_f32 v[6:7], v[6:7], v[0:1]
	ds_read_b128 v[0:3], v40 offset:24576
	s_waitcnt lgkmcnt(0)
	v_pk_add_f32 v[4:5], v[4:5], v[2:3]
	v_pk_add_f32 v[6:7], v[6:7], v[0:1]
	ds_read_b128 v[0:3], v40 offset:32768
	s_waitcnt lgkmcnt(0)
	v_pk_add_f32 v[4:5], v[4:5], v[2:3]
	v_pk_add_f32 v[6:7], v[6:7], v[0:1]
	ds_read_b128 v[0:3], v40 offset:40960
	s_waitcnt lgkmcnt(0)
	v_pk_add_f32 v[4:5], v[4:5], v[2:3]
	v_pk_add_f32 v[6:7], v[6:7], v[0:1]
	ds_read_b128 v[0:3], v40 offset:49152
	s_waitcnt lgkmcnt(0)
	v_pk_add_f32 v[8:9], v[4:5], v[2:3]
	ds_read_b128 v[2:5], v40 offset:57344
	v_pk_add_f32 v[6:7], v[6:7], v[0:1]
	s_waitcnt lgkmcnt(0)
	v_pk_add_f32 v[0:1], v[8:9], v[4:5]
	v_lshlrev_b32_e32 v5, 6, v42
	v_pk_add_f32 v[2:3], v[6:7], v[2:3]
	global_load_dwordx4 v[6:9], v5, s[8:9] offset:16
	global_load_dwordx4 v[10:13], v5, s[8:9] offset:48
	global_load_dwordx4 v[14:17], v5, s[8:9]
	global_load_dwordx4 v[18:21], v5, s[8:9] offset:32
	v_add_u32_e32 v4, s14, v39
	s_waitcnt vmcnt(1)
	v_mov_b32_e32 v22, v14
	s_waitcnt vmcnt(0)
	v_mov_b32_e32 v23, v18
	v_mov_b32_e32 v18, v15
	v_pk_add_f32 v[14:15], v[22:23], v[18:19]
	v_mov_b32_e32 v18, v16
	v_mov_b32_e32 v19, v20
	v_mov_b32_e32 v20, v17
	v_pk_add_f32 v[16:17], v[18:19], v[20:21]
	s_nop 0
	v_pk_add_f32 v[14:15], v[14:15], v[16:17]
	v_mov_b32_e32 v16, v6
	v_mov_b32_e32 v17, v10
	v_mov_b32_e32 v10, v7
	v_pk_add_f32 v[6:7], v[16:17], v[10:11]
	v_mov_b32_e32 v10, v8
	v_mov_b32_e32 v11, v12
	v_mov_b32_e32 v12, v9
	v_pk_add_f32 v[8:9], v[10:11], v[12:13]
	s_nop 0
	v_pk_add_f32 v[6:7], v[6:7], v[8:9]
	s_nop 0
	v_pk_add_f32 v[6:7], v[14:15], v[6:7]
	s_nop 0
	v_add_f32_e32 v5, v6, v7
	v_fmamk_f32 v5, v5, 0x3a800000, v176
	v_cmp_gt_f32_e32 vcc, s39, v5
	v_mul_f32_e32 v6, 0x4b800000, v5
	s_nop 0
	v_cndmask_b32_e32 v5, v5, v6, vcc
	v_rsq_f32_e32 v5, v5
	s_nop 0
	v_mul_f32_e32 v6, 0x45800000, v5
	v_cndmask_b32_e32 v14, v5, v6, vcc
	v_ashrrev_i32_e32 v5, 31, v4
	v_lshl_add_u64 v[4:5], v[4:5], 0, v[160:161]
	v_lshlrev_b64 v[4:5], 1, v[4:5]
	v_lshl_add_u64 v[6:7], s[18:19], 0, v[4:5]
	v_lshl_add_u64 v[4:5], s[12:13], 0, v[4:5]
	global_load_dwordx2 v[4:5], v[4:5], off
	v_mul_f32_e64 v2, v14, -v2
	global_load_dwordx2 v[8:9], v[6:7], off
	v_mul_f32_e64 v3, v14, -v3
	v_mul_f32_e32 v2, 0x3fb8aa3b, v2
	v_mul_f32_e32 v3, 0x3fb8aa3b, v3
	v_exp_f32_e32 v2, v2
	v_exp_f32_e32 v3, v3
	v_mul_f32_e64 v0, v14, -v0
	v_mul_f32_e64 v1, v14, -v1
	v_mul_f32_e32 v0, 0x3fb8aa3b, v0
	v_pk_add_f32 v[2:3], v[2:3], 1.0 op_sel_hi:[1,0]
	v_mul_f32_e32 v1, 0x3fb8aa3b, v1
	v_exp_f32_e32 v0, v0
	v_exp_f32_e32 v1, v1
	s_waitcnt vmcnt(1)
	v_lshlrev_b32_e32 v10, 16, v4
	v_and_b32_e32 v11, 0xffff0000, v4
	s_waitcnt vmcnt(0)
	v_lshlrev_b32_e32 v12, 16, v8
	v_and_b32_e32 v13, 0xffff0000, v8
	v_pk_add_f32 v[0:1], v[0:1], 1.0 op_sel_hi:[1,0]
	v_rcp_f32_e32 v3, v3
	s_nop 0
	v_rcp_f32_e32 v2, v2
	s_nop 0
	v_pk_fma_f32 v[2:3], v[2:3], v[12:13], v[10:11]
	v_lshlrev_b32_e32 v4, 16, v5
	v_and_b32_e32 v5, 0xffff0000, v5
	v_lshlrev_b32_e32 v8, 16, v9
	v_rcp_f32_e32 v1, v1
	v_and_b32_e32 v9, 0xffff0000, v9
	v_rcp_f32_e32 v0, v0
	s_nop 0
	v_pk_fma_f32 v[0:1], v[0:1], v[8:9], v[4:5]
	v_cvt_pk_bf16_f32 v4, v2, v3
	v_cvt_pk_bf16_f32 v5, v0, v1
	v_pk_mul_f32 v[2:3], v[2:3], v[2:3]
	v_pk_mul_f32 v[0:1], v[0:1], v[0:1]
	global_store_dwordx2 v[6:7], v[4:5], off
	v_add_f32_e32 v0, v0, v1
	v_add_f32_e32 v1, v2, v3
	v_and_b32_e32 v2, 64, v177
	v_add_f32_e32 v0, v1, v0
	v_xor_b32_e32 v1, 32, v177
	v_add_u32_e32 v2, 64, v2
	v_cmp_lt_i32_e32 vcc, v1, v2
	s_nop 1
	v_cndmask_b32_e32 v1, v177, v1, vcc
	v_lshlrev_b32_e32 v1, 2, v1
	ds_bpermute_b32 v1, v1, v0
	s_and_saveexec_b64 s[14:15], s[40:41]
	s_cbranch_execz .LBB0_495
	s_waitcnt lgkmcnt(0)
	v_add_f32_e32 v0, v0, v1
	ds_write_b32 v41, v0

; DI float rowscale(const float* ss, int row) {
;     const f32x4* p = (const f32x4*)(ss + (size_t)row * 16);
;     const f32x4 a = p[0], b = p[1], c = p[2], d = p[3];
;     const float s = (((a.x + a.y) + (a.z + a.w)) + ((b.x + b.y) + (b.z + b.w))) + (((c.x + c.y) + (c.z + c.w)) + ((d.x + d.y) + (d.z + d.w)));
;     return rsqrtf(s * (1.0f / 1024.0f) + EPS);
; }
; DI void rowscales8(const float* ss, int rowbase, int fr, int fq, float (&r)[2][4]) {
;     const int lane = fq * 16 + fr;
;     const float rA = rowscale(ss, rowbase + lane), rB = rowscale(ss, rowbase + 128 + lane);
; #pragma unroll
;     for (int m = 0; m < 4; ++m) { r[0][m] = __shfl(rA, m * 16 + fr); r[1][m] = __shfl(rB, m * 16 + fr); }
; }
;     DI void operator()(const pg8::f32x4 (&acc)[2][2][4][2], const pg8::Unit& u, int wr, int wc, int fr, int fq) const {
;         const int row0 = u.pm * 256 + wr * 64 + fr, col0 = u.pn * 128 + wc * 32 + 8 * fq;
;         float rs[2][4]; rowscales8(ss, u.pm * 256 + wr * 64, fr, fq, rs);
; #pragma unroll
;         for (int ai = 0; ai < 2; ++ai)
; #pragma unroll
;             for (int m = 0; m < 4; ++m) {
;                 const int row = row0 + ai * 128 + m * 16; const float r = rs[ai][m];
;                 float hv[8];
; #pragma unroll
;                 for (int n = 0; n < 2; ++n) { const pg8::f32x4 g = acc[ai][0][m][n] * r, uu = acc[ai][1][m][n] * r;
; #pragma unroll
;                     for (int e = 0; e < 4; ++e) hv[4 * n + e] = g[e] * __frcp_rn(1.0f + __expf(-g[e])) * uu[e]; }
.LBB0_520:
	s_lshl_b32 s9, s16, 8
	s_add_i32 s9, s9, s48
	v_or_b32_e32 v154, s9, v143
	v_ashrrev_i32_e32 v155, 31, v154
	v_lshlrev_b64 v[154:155], 6, v[154:155]
	v_lshl_add_u64 v[158:159], s[4:5], 0, v[154:155]
	global_load_dwordx4 v[154:157], v[158:159], off offset:16
	global_load_dwordx4 v[162:165], v[158:159], off offset:48
	global_load_dwordx4 v[166:169], v[158:159], off
	global_load_dwordx4 v[170:173], v[158:159], off offset:32
	s_mov_b32 s16, 0x3a800000
	v_lshl_or_b32 v152, s17, 7, v147
	v_or_b32_e32 v151, s9, v139
	s_mul_i32 s11, s88, 56
	s_waitcnt vmcnt(0)
	v_mov_b32_e32 v158, v166
	v_mov_b32_e32 v159, v170
	v_mov_b32_e32 v170, v167
	v_mov_b32_e32 v166, v168
	v_mov_b32_e32 v167, v172
	v_mov_b32_e32 v172, v169
	v_pk_add_f32 v[158:159], v[158:159], v[170:171]
	v_pk_add_f32 v[166:167], v[166:167], v[172:173]
	s_nop 0
	v_pk_add_f32 v[158:159], v[158:159], v[166:167]
	v_mov_b32_e32 v166, v154
	v_mov_b32_e32 v167, v162
	v_mov_b32_e32 v162, v155
	v_pk_add_f32 v[154:155], v[166:167], v[162:163]
	v_mov_b32_e32 v162, v156
	v_mov_b32_e32 v163, v164
	v_mov_b32_e32 v164, v157
	v_pk_add_f32 v[156:157], v[162:163], v[164:165]
	s_nop 0
	v_pk_add_f32 v[154:155], v[154:155], v[156:157]
	s_nop 0
	v_pk_add_f32 v[158:159], v[158:159], v[154:155]
	v_add_u32_e32 v154, s9, v145
	v_ashrrev_i32_e32 v155, 31, v154
	v_lshlrev_b64 v[154:155], 6, v[154:155]
	v_lshl_add_u64 v[170:171], s[4:5], 0, v[154:155]
	global_load_dwordx4 v[154:157], v[170:171], off offset:16
	global_load_dwordx4 v[162:165], v[170:171], off offset:48
	global_load_dwordx4 v[166:169], v[170:171], off
	s_nop 0
	global_load_dwordx4 v[170:173], v[170:171], off offset:32
	s_movk_i32 s9, 0x1600
	s_waitcnt vmcnt(1)
	v_mov_b32_e32 v174, v166
	s_waitcnt vmcnt(0)
	v_mov_b32_e32 v175, v170
	v_mov_b32_e32 v170, v167
	v_pk_add_f32 v[166:167], v[174:175], v[170:171]
	v_mov_b32_e32 v170, v168
	v_mov_b32_e32 v171, v172
	v_mov_b32_e32 v172, v169
	v_pk_add_f32 v[168:169], v[170:171], v[172:173]
	s_nop 0
	v_pk_add_f32 v[166:167], v[166:167], v[168:169]
	v_mov_b32_e32 v168, v154
	v_mov_b32_e32 v169, v162
	v_mov_b32_e32 v162, v155
	v_pk_add_f32 v[154:155], v[168:169], v[162:163]
	v_mov_b32_e32 v162, v156
	v_mov_b32_e32 v163, v164
	v_mov_b32_e32 v164, v157
	v_pk_add_f32 v[156:157], v[162:163], v[164:165]
	s_nop 0
	v_pk_add_f32 v[154:155], v[154:155], v[156:157]
	v_mov_b32_e32 v157, v158
	v_pk_add_f32 v[154:155], v[166:167], v[154:155]
	s_nop 0
	v_mov_b32_e32 v156, v154
	v_mov_b32_e32 v158, v155
	v_pk_add_f32 v[154:155], v[156:157], v[158:159]
	s_nop 0
	v_pk_fma_f32 v[154:155], v[154:155], s[16:17], v[176:177] op_sel_hi:[1,0,0]
	s_nop 0
	v_mul_f32_e32 v138, 0x4b800000, v155
	v_cmp_gt_f32_e64 s[42:43], s39, v155
	v_cmp_gt_f32_e32 vcc, s39, v154
	s_nop 0
	v_cndmask_b32_e64 v138, v155, v138, s[42:43]
	v_rsq_f32_e32 v138, v138
	s_nop 0
	v_mul_f32_e32 v140, 0x45800000, v138
	v_cndmask_b32_e64 v138, v138, v140, s[42:43]
	v_mul_f32_e32 v140, 0x4b800000, v154
	v_cndmask_b32_e32 v140, v154, v140, vcc
	v_rsq_f32_e32 v140, v140
	s_nop 0
	v_mul_f32_e32 v142, 0x45800000, v140
	v_cndmask_b32_e32 v153, v140, v142, vcc
	v_and_or_b32 v140, v177, 64, v139
	v_lshlrev_b32_e32 v155, 2, v140
	ds_bpermute_b32 v154, v155, v138
	ds_bpermute_b32 v144, v155, v153
	ds_bpermute_b32 v150, v155, v138 offset:64
	ds_bpermute_b32 v142, v155, v153 offset:64
	ds_bpermute_b32 v148, v155, v138 offset:128
	s_waitcnt lgkmcnt(4)
	v_pk_mul_f32 v[124:125], v[124:125], v[154:155] op_sel_hi:[1,0]
	ds_bpermute_b32 v140, v155, v153 offset:128
	ds_bpermute_b32 v146, v155, v138 offset:192
	ds_bpermute_b32 v138, v155, v153 offset:192
	v_mul_f32_e32 v155, 0xbfb8aa3b, v124
	v_exp_f32_e32 v156, v155
	v_mul_f32_e32 v155, 0xbfb8aa3b, v125
	v_exp_f32_e32 v157, v155
	v_ashrrev_i32_e32 v153, 31, v152
	s_waitcnt lgkmcnt(5)
	v_pk_mul_f32 v[108:109], v[108:109], v[150:151] op_sel_hi:[1,0]
	v_pk_mul_f32 v[104:105], v[104:105], v[150:151] op_sel_hi:[1,0]
	v_pk_add_f32 v[156:157], v[156:157], 1.0 op_sel_hi:[1,0]
	v_pk_mul_f32 v[106:107], v[106:107], v[150:151] op_sel_hi:[1,0]
	v_pk_mul_f32 v[100:101], v[100:101], v[150:151] op_sel_hi:[1,0]
	v_pk_mul_f32 v[96:97], v[96:97], v[150:151] op_sel_hi:[1,0]
	v_pk_mul_f32 v[98:99], v[98:99], v[150:151] op_sel_hi:[1,0]
	v_rcp_f32_e32 v157, v157
	s_waitcnt lgkmcnt(3)
	v_pk_mul_f32 v[92:93], v[92:93], v[148:149] op_sel_hi:[1,0]
	v_pk_mul_f32 v[88:89], v[88:89], v[148:149] op_sel_hi:[1,0]
	v_pk_mul_f32 v[90:91], v[90:91], v[148:149] op_sel_hi:[1,0]
	v_rcp_f32_e32 v156, v156
	s_nop 0
	v_pk_mul_f32 v[124:125], v[124:125], v[156:157]
	v_pk_mul_f32 v[120:121], v[120:121], v[154:155] op_sel_hi:[1,0]
	v_pk_mul_f32 v[84:85], v[84:85], v[148:149] op_sel_hi:[1,0]
	v_pk_mul_f32 v[120:121], v[120:121], v[124:125]
	v_pk_mul_f32 v[124:125], v[126:127], v[154:155] op_sel_hi:[1,0]
	v_pk_mul_f32 v[80:81], v[80:81], v[148:149] op_sel_hi:[1,0]
	v_mul_f32_e32 v126, 0xbfb8aa3b, v124
	v_mul_f32_e32 v127, 0xbfb8aa3b, v125
	v_exp_f32_e32 v126, v126
	v_exp_f32_e32 v127, v127
	v_pk_mul_f32 v[82:83], v[82:83], v[148:149] op_sel_hi:[1,0]
	s_waitcnt lgkmcnt(1)
; DI unsigned pk2(float lo, float hi) { const f32x2_t v = {lo, hi}; const bf16x2_t b = __builtin_convertvector(v, bf16x2_t); return __builtin_bit_cast(unsigned, b); }
;     DI void operator()(const pg8::f32x4 (&acc)[2][2][4][2], const pg8::Unit& u, int wr, int wc, int fr, int fq) const {
;     ...
;             for (int m = 0; m < 4; ++m) {
;                 const int row = row0 + ai * 128 + m * 16; const float r = rs[ai][m];
;                 float hv[8];
; #pragma unroll
;                 for (int n = 0; n < 2; ++n) { const pg8::f32x4 g = acc[ai][0][m][n] * r, uu = acc[ai][1][m][n] * r;
; #pragma unroll
;                     for (int e = 0; e < 4; ++e) hv[4 * n + e] = g[e] * __frcp_rn(1.0f + __expf(-g[e])) * uu[e]; }
;                 u32x4 w; w.x = pk2(hv[0], hv[1]); w.y = pk2(hv[2], hv[3]); w.z = pk2(hv[4], hv[5]); w.w = pk2(hv[6], hv[7]);
;                 *(u32x4*)(H + (size_t)row * DFF + col0) = w;
	v_pk_mul_f32 v[76:77], v[76:77], v[146:147] op_sel_hi:[1,0]
	v_pk_mul_f32 v[72:73], v[72:73], v[146:147] op_sel_hi:[1,0]
	v_pk_add_f32 v[126:127], v[126:127], 1.0 op_sel_hi:[1,0]
	v_pk_mul_f32 v[74:75], v[74:75], v[146:147] op_sel_hi:[1,0]
	v_pk_mul_f32 v[68:69], v[68:69], v[146:147] op_sel_hi:[1,0]
	v_pk_mul_f32 v[64:65], v[64:65], v[146:147] op_sel_hi:[1,0]
	v_pk_mul_f32 v[66:67], v[66:67], v[146:147] op_sel_hi:[1,0]
	v_rcp_f32_e32 v127, v127
	v_pk_mul_f32 v[60:61], v[60:61], v[144:145] op_sel_hi:[1,0]
	v_pk_mul_f32 v[56:57], v[56:57], v[144:145] op_sel_hi:[1,0]
	v_pk_mul_f32 v[58:59], v[58:59], v[144:145] op_sel_hi:[1,0]
	v_rcp_f32_e32 v126, v126
	s_nop 0
	v_pk_mul_f32 v[124:125], v[124:125], v[126:127]
	v_pk_mul_f32 v[122:123], v[122:123], v[154:155] op_sel_hi:[1,0]
	v_pk_mul_f32 v[116:117], v[116:117], v[154:155] op_sel_hi:[1,0]
	v_pk_mul_f32 v[122:123], v[122:123], v[124:125]
	v_mul_f32_e32 v124, 0xbfb8aa3b, v116
	v_mul_f32_e32 v125, 0xbfb8aa3b, v117
	v_exp_f32_e32 v124, v124
	v_exp_f32_e32 v125, v125
	v_pk_mul_f32 v[52:53], v[52:53], v[144:145] op_sel_hi:[1,0]
	v_pk_mul_f32 v[48:49], v[48:49], v[144:145] op_sel_hi:[1,0]
	v_pk_mul_f32 v[50:51], v[50:51], v[144:145] op_sel_hi:[1,0]
	v_pk_add_f32 v[124:125], v[124:125], 1.0 op_sel_hi:[1,0]
	v_pk_mul_f32 v[44:45], v[44:45], v[142:143] op_sel_hi:[1,0]
	v_pk_mul_f32 v[40:41], v[40:41], v[142:143] op_sel_hi:[1,0]
	v_pk_mul_f32 v[42:43], v[42:43], v[142:143] op_sel_hi:[1,0]
	v_pk_mul_f32 v[36:37], v[36:37], v[142:143] op_sel_hi:[1,0]
	v_rcp_f32_e32 v125, v125
	v_pk_mul_f32 v[32:33], v[32:33], v[142:143] op_sel_hi:[1,0]
	v_pk_mul_f32 v[34:35], v[34:35], v[142:143] op_sel_hi:[1,0]
	v_pk_mul_f32 v[28:29], v[28:29], v[140:141] op_sel_hi:[1,0]
	v_rcp_f32_e32 v124, v124
	s_nop 0
	v_pk_mul_f32 v[116:117], v[116:117], v[124:125]
	v_pk_mul_f32 v[112:113], v[112:113], v[154:155] op_sel_hi:[1,0]
	v_pk_mul_f32 v[24:25], v[24:25], v[140:141] op_sel_hi:[1,0]
	v_pk_mul_f32 v[112:113], v[112:113], v[116:117]
	v_pk_mul_f32 v[116:117], v[118:119], v[154:155] op_sel_hi:[1,0]
	v_pk_mul_f32 v[26:27], v[26:27], v[140:141] op_sel_hi:[1,0]
	v_mul_f32_e32 v118, 0xbfb8aa3b, v116
	v_mul_f32_e32 v119, 0xbfb8aa3b, v117
	v_exp_f32_e32 v118, v118
	v_exp_f32_e32 v119, v119
	v_pk_mul_f32 v[20:21], v[20:21], v[140:141] op_sel_hi:[1,0]
	v_pk_mul_f32 v[16:17], v[16:17], v[140:141] op_sel_hi:[1,0]
	v_pk_mul_f32 v[18:19], v[18:19], v[140:141] op_sel_hi:[1,0]
	v_pk_add_f32 v[118:119], v[118:119], 1.0 op_sel_hi:[1,0]
	s_waitcnt lgkmcnt(0)
	v_pk_mul_f32 v[12:13], v[12:13], v[138:139] op_sel_hi:[1,0]
	v_pk_mul_f32 v[8:9], v[8:9], v[138:139] op_sel_hi:[1,0]
	v_pk_mul_f32 v[10:11], v[10:11], v[138:139] op_sel_hi:[1,0]
	v_pk_mul_f32 v[4:5], v[4:5], v[138:139] op_sel_hi:[1,0]
	v_rcp_f32_e32 v119, v119
	v_pk_mul_f32 v[0:1], v[0:1], v[138:139] op_sel_hi:[1,0]
	v_pk_mul_f32 v[2:3], v[2:3], v[138:139] op_sel_hi:[1,0]
	v_rcp_f32_e32 v118, v118
	s_nop 0
	v_pk_mul_f32 v[116:117], v[116:117], v[118:119]
	v_pk_mul_f32 v[114:115], v[114:115], v[154:155] op_sel_hi:[1,0]
	v_cvt_pk_bf16_f32 v118, v112, v113
	v_pk_mul_f32 v[114:115], v[114:115], v[116:117]
	v_mov_b64_e32 v[112:113], s[82:83]
	v_cvt_pk_bf16_f32 v116, v120, v121
	v_cvt_pk_bf16_f32 v119, v114, v115
	v_mad_i64_i32 v[120:121], s[16:17], v151, s9, v[112:113]
	v_lshlrev_b64 v[114:115], 1, v[152:153]
	v_cvt_pk_bf16_f32 v117, v122, v123
	v_lshl_add_u64 v[120:121], v[120:121], 0, v[114:115]
	global_store_dwordx4 v[120:121], v[116:119], off
	s_nop 1
	v_mul_f32_e32 v116, 0xbfb8aa3b, v108
	v_mul_f32_e32 v117, 0xbfb8aa3b, v109
	v_exp_f32_e32 v116, v116
	v_exp_f32_e32 v117, v117
	s_nop 0
	v_pk_add_f32 v[116:117], v[116:117], 1.0 op_sel_hi:[1,0]
	s_nop 0
	s_nop 0
	v_rcp_f32_e32 v117, v117
	s_nop 0
	v_rcp_f32_e32 v116, v116
	s_nop 0
	v_pk_mul_f32 v[108:109], v[108:109], v[116:117]
	s_nop 0
	v_pk_mul_f32 v[104:105], v[104:105], v[108:109]
	v_pk_mul_f32 v[108:109], v[110:111], v[150:151] op_sel_hi:[1,0]
	s_nop 0
	v_mul_f32_e32 v110, 0xbfb8aa3b, v108
	v_mul_f32_e32 v111, 0xbfb8aa3b, v109
	v_exp_f32_e32 v110, v110
	v_exp_f32_e32 v111, v111
	s_nop 0
	v_pk_add_f32 v[110:111], v[110:111], 1.0 op_sel_hi:[1,0]
	s_nop 0
	s_nop 0
	v_rcp_f32_e32 v111, v111
	s_nop 0
	v_rcp_f32_e32 v110, v110
	s_nop 0
	v_pk_mul_f32 v[108:109], v[108:109], v[110:111]
	s_nop 0
	v_pk_mul_f32 v[106:107], v[106:107], v[108:109]
	v_mul_f32_e32 v108, 0xbfb8aa3b, v100
	v_mul_f32_e32 v109, 0xbfb8aa3b, v101
	v_exp_f32_e32 v108, v108
	v_exp_f32_e32 v109, v109
	s_nop 0
	v_pk_add_f32 v[108:109], v[108:109], 1.0 op_sel_hi:[1,0]
	s_nop 0
	s_nop 0
	v_rcp_f32_e32 v109, v109
	s_nop 0
	v_rcp_f32_e32 v108, v108
	s_nop 0
	v_pk_mul_f32 v[100:101], v[100:101], v[108:109]
	s_nop 0
	v_pk_mul_f32 v[100:101], v[96:97], v[100:101]
	v_pk_mul_f32 v[96:97], v[102:103], v[150:151] op_sel_hi:[1,0]
	s_nop 0
	v_mul_f32_e32 v102, 0xbfb8aa3b, v96
	v_mul_f32_e32 v103, 0xbfb8aa3b, v97
	v_exp_f32_e32 v102, v102
	v_exp_f32_e32 v103, v103
	s_nop 0
	v_pk_add_f32 v[102:103], v[102:103], 1.0 op_sel_hi:[1,0]
	s_nop 0
	s_nop 0
	v_rcp_f32_e32 v103, v103
	s_nop 0
	v_rcp_f32_e32 v102, v102
	s_nop 0
	v_pk_mul_f32 v[96:97], v[96:97], v[102:103]
	v_or_b32_e32 v108, 16, v151
	v_pk_mul_f32 v[102:103], v[98:99], v[96:97]
	v_cvt_pk_bf16_f32 v98, v100, v101
	v_mad_i64_i32 v[100:101], s[16:17], v108, s9, v[112:113]
	v_cvt_pk_bf16_f32 v96, v104, v105
	v_cvt_pk_bf16_f32 v97, v106, v107
	v_cvt_pk_bf16_f32 v99, v102, v103
	v_lshl_add_u64 v[100:101], v[100:101], 0, v[114:115]
	global_store_dwordx4 v[100:101], v[96:99], off
	s_nop 1
	v_mul_f32_e32 v96, 0xbfb8aa3b, v92
	v_mul_f32_e32 v97, 0xbfb8aa3b, v93
	v_exp_f32_e32 v96, v96
	v_exp_f32_e32 v97, v97
	s_nop 0
	v_pk_add_f32 v[96:97], v[96:97], 1.0 op_sel_hi:[1,0]
; DI unsigned pk2(float lo, float hi) { const f32x2_t v = {lo, hi}; const bf16x2_t b = __builtin_convertvector(v, bf16x2_t); return __builtin_bit_cast(unsigned, b); }
;     DI void operator()(const pg8::f32x4 (&acc)[2][2][4][2], const pg8::Unit& u, int wr, int wc, int fr, int fq) const {
;     ...
;             for (int m = 0; m < 4; ++m) {
;                 const int row = row0 + ai * 128 + m * 16; const float r = rs[ai][m];
;                 float hv[8];
; #pragma unroll
;                 for (int n = 0; n < 2; ++n) { const pg8::f32x4 g = acc[ai][0][m][n] * r, uu = acc[ai][1][m][n] * r;
; #pragma unroll
;                     for (int e = 0; e < 4; ++e) hv[4 * n + e] = g[e] * __frcp_rn(1.0f + __expf(-g[e])) * uu[e]; }
;                 u32x4 w; w.x = pk2(hv[0], hv[1]); w.y = pk2(hv[2], hv[3]); w.z = pk2(hv[4], hv[5]); w.w = pk2(hv[6], hv[7]);
;                 *(u32x4*)(H + (size_t)row * DFF + col0) = w;
	s_nop 0
	s_nop 0
	v_rcp_f32_e32 v97, v97
	s_nop 0
	v_rcp_f32_e32 v96, v96
	s_nop 0
	v_pk_mul_f32 v[92:93], v[92:93], v[96:97]
	s_nop 0
	v_pk_mul_f32 v[88:89], v[88:89], v[92:93]
	v_pk_mul_f32 v[92:93], v[94:95], v[148:149] op_sel_hi:[1,0]
	s_nop 0
	v_mul_f32_e32 v94, 0xbfb8aa3b, v92
	v_mul_f32_e32 v95, 0xbfb8aa3b, v93
	v_exp_f32_e32 v94, v94
	v_exp_f32_e32 v95, v95
	s_nop 0
	v_pk_add_f32 v[94:95], v[94:95], 1.0 op_sel_hi:[1,0]
	s_nop 0
	s_nop 0
	v_rcp_f32_e32 v95, v95
	s_nop 0
	v_rcp_f32_e32 v94, v94
	s_nop 0
	v_pk_mul_f32 v[92:93], v[92:93], v[94:95]
	s_nop 0
	v_pk_mul_f32 v[90:91], v[90:91], v[92:93]
	v_mul_f32_e32 v92, 0xbfb8aa3b, v84
	v_mul_f32_e32 v93, 0xbfb8aa3b, v85
	v_exp_f32_e32 v92, v92
	v_exp_f32_e32 v93, v93
	s_nop 0
	v_pk_add_f32 v[92:93], v[92:93], 1.0 op_sel_hi:[1,0]
	s_nop 0
	s_nop 0
	v_rcp_f32_e32 v93, v93
	s_nop 0
	v_rcp_f32_e32 v92, v92
	s_nop 0
	v_pk_mul_f32 v[84:85], v[84:85], v[92:93]
	s_nop 0
	v_pk_mul_f32 v[84:85], v[80:81], v[84:85]
	v_pk_mul_f32 v[80:81], v[86:87], v[148:149] op_sel_hi:[1,0]
	s_nop 0
	v_mul_f32_e32 v86, 0xbfb8aa3b, v80
	v_mul_f32_e32 v87, 0xbfb8aa3b, v81
	v_exp_f32_e32 v86, v86
	v_exp_f32_e32 v87, v87
	s_nop 0
	v_pk_add_f32 v[86:87], v[86:87], 1.0 op_sel_hi:[1,0]
	s_nop 0
	s_nop 0
	v_rcp_f32_e32 v87, v87
	s_nop 0
	v_rcp_f32_e32 v86, v86
	s_nop 0
	v_pk_mul_f32 v[80:81], v[80:81], v[86:87]
	v_or_b32_e32 v92, 32, v151
	v_pk_mul_f32 v[86:87], v[82:83], v[80:81]
	v_cvt_pk_bf16_f32 v82, v84, v85
	v_mad_i64_i32 v[84:85], s[16:17], v92, s9, v[112:113]
	v_cvt_pk_bf16_f32 v80, v88, v89
	v_cvt_pk_bf16_f32 v81, v90, v91
	v_cvt_pk_bf16_f32 v83, v86, v87
	v_lshl_add_u64 v[84:85], v[84:85], 0, v[114:115]
	global_store_dwordx4 v[84:85], v[80:83], off
	s_nop 1
	v_mul_f32_e32 v80, 0xbfb8aa3b, v76
	v_mul_f32_e32 v81, 0xbfb8aa3b, v77
	v_exp_f32_e32 v80, v80
	v_exp_f32_e32 v81, v81
	s_nop 0
	v_pk_add_f32 v[80:81], v[80:81], 1.0 op_sel_hi:[1,0]
	s_nop 0
	s_nop 0
	v_rcp_f32_e32 v81, v81
	s_nop 0
	v_rcp_f32_e32 v80, v80
	s_nop 0
	v_pk_mul_f32 v[76:77], v[76:77], v[80:81]
	s_nop 0
	v_pk_mul_f32 v[72:73], v[72:73], v[76:77]
	v_pk_mul_f32 v[76:77], v[78:79], v[146:147] op_sel_hi:[1,0]
	s_nop 0
	v_mul_f32_e32 v78, 0xbfb8aa3b, v76
	v_mul_f32_e32 v79, 0xbfb8aa3b, v77
	v_exp_f32_e32 v78, v78
	v_exp_f32_e32 v79, v79
	s_nop 0
	v_pk_add_f32 v[78:79], v[78:79], 1.0 op_sel_hi:[1,0]
	s_nop 0
	s_nop 0
	v_rcp_f32_e32 v79, v79
	s_nop 0
	v_rcp_f32_e32 v78, v78
	s_nop 0
	v_pk_mul_f32 v[76:77], v[76:77], v[78:79]
	s_nop 0
	v_pk_mul_f32 v[74:75], v[74:75], v[76:77]
	v_mul_f32_e32 v76, 0xbfb8aa3b, v68
	v_mul_f32_e32 v77, 0xbfb8aa3b, v69
	v_exp_f32_e32 v76, v76
	v_exp_f32_e32 v77, v77
	s_nop 0
	v_pk_add_f32 v[76:77], v[76:77], 1.0 op_sel_hi:[1,0]
	s_nop 0
	s_nop 0
	v_rcp_f32_e32 v77, v77
	s_nop 0
	v_rcp_f32_e32 v76, v76
	s_nop 0
	v_pk_mul_f32 v[68:69], v[68:69], v[76:77]
	s_nop 0
	v_pk_mul_f32 v[68:69], v[64:65], v[68:69]
	v_pk_mul_f32 v[64:65], v[70:71], v[146:147] op_sel_hi:[1,0]
	s_nop 0
	v_mul_f32_e32 v70, 0xbfb8aa3b, v64
	v_mul_f32_e32 v71, 0xbfb8aa3b, v65
	v_exp_f32_e32 v70, v70
	v_exp_f32_e32 v71, v71
	s_nop 0
	v_pk_add_f32 v[70:71], v[70:71], 1.0 op_sel_hi:[1,0]
	s_nop 0
	s_nop 0
	v_rcp_f32_e32 v71, v71
	s_nop 0
	v_rcp_f32_e32 v70, v70
	s_nop 0
	v_pk_mul_f32 v[64:65], v[64:65], v[70:71]
	v_or_b32_e32 v76, 48, v151
	v_pk_mul_f32 v[70:71], v[66:67], v[64:65]
	v_cvt_pk_bf16_f32 v66, v68, v69
	v_mad_i64_i32 v[68:69], s[16:17], v76, s9, v[112:113]
	v_cvt_pk_bf16_f32 v64, v72, v73
	v_cvt_pk_bf16_f32 v65, v74, v75
	v_cvt_pk_bf16_f32 v67, v70, v71
	v_lshl_add_u64 v[68:69], v[68:69], 0, v[114:115]
	global_store_dwordx4 v[68:69], v[64:67], off
	s_nop 1
	v_mul_f32_e32 v64, 0xbfb8aa3b, v60
	v_mul_f32_e32 v65, 0xbfb8aa3b, v61
	v_exp_f32_e32 v64, v64
	v_exp_f32_e32 v65, v65
	v_add_u32_e32 v66, 0x80, v151
	v_pk_add_f32 v[64:65], v[64:65], 1.0 op_sel_hi:[1,0]
	s_nop 0
	s_nop 0
	v_rcp_f32_e32 v65, v65
	s_nop 0
	v_rcp_f32_e32 v64, v64
	s_nop 0
	v_pk_mul_f32 v[60:61], v[60:61], v[64:65]
	s_nop 0
	v_pk_mul_f32 v[56:57], v[56:57], v[60:61]
	v_pk_mul_f32 v[60:61], v[62:63], v[144:145] op_sel_hi:[1,0]
	s_nop 0
	v_mul_f32_e32 v62, 0xbfb8aa3b, v60
	v_mul_f32_e32 v63, 0xbfb8aa3b, v61
	v_exp_f32_e32 v62, v62
	v_exp_f32_e32 v63, v63
	s_nop 0
	v_pk_add_f32 v[62:63], v[62:63], 1.0 op_sel_hi:[1,0]
	s_nop 0
	s_nop 0
	v_rcp_f32_e32 v63, v63
	s_nop 0
	v_rcp_f32_e32 v62, v62
	s_nop 0
	v_pk_mul_f32 v[60:61], v[60:61], v[62:63]
	s_nop 0
	v_pk_mul_f32 v[58:59], v[58:59], v[60:61]
	v_mul_f32_e32 v60, 0xbfb8aa3b, v52
	v_mul_f32_e32 v61, 0xbfb8aa3b, v53
	v_exp_f32_e32 v60, v60
	v_exp_f32_e32 v61, v61
	s_nop 0
	v_pk_add_f32 v[60:61], v[60:61], 1.0 op_sel_hi:[1,0]
	s_nop 0
	s_nop 0
	v_rcp_f32_e32 v61, v61
	s_nop 0
	v_rcp_f32_e32 v60, v60
	s_nop 0
	v_pk_mul_f32 v[52:53], v[52:53], v[60:61]
	s_nop 0
	v_pk_mul_f32 v[52:53], v[48:49], v[52:53]
	v_pk_mul_f32 v[48:49], v[54:55], v[144:145] op_sel_hi:[1,0]
	s_nop 0
	v_mul_f32_e32 v54, 0xbfb8aa3b, v48
	v_mul_f32_e32 v55, 0xbfb8aa3b, v49
	v_exp_f32_e32 v54, v54
	v_exp_f32_e32 v55, v55
	s_nop 0
	v_pk_add_f32 v[54:55], v[54:55], 1.0 op_sel_hi:[1,0]
	s_nop 0
	s_nop 0
	v_rcp_f32_e32 v55, v55
	s_nop 0
	v_rcp_f32_e32 v54, v54
	s_nop 0
	v_pk_mul_f32 v[48:49], v[48:49], v[54:55]
	s_nop 0
	v_pk_mul_f32 v[54:55], v[50:51], v[48:49]
	v_cvt_pk_bf16_f32 v50, v52, v53
	v_mad_i64_i32 v[52:53], s[16:17], v66, s9, v[112:113]
	v_cvt_pk_bf16_f32 v48, v56, v57
	v_cvt_pk_bf16_f32 v49, v58, v59
	v_cvt_pk_bf16_f32 v51, v54, v55
	v_lshl_add_u64 v[52:53], v[52:53], 0, v[114:115]
	global_store_dwordx4 v[52:53], v[48:51], off
	s_nop 1
	v_mul_f32_e32 v48, 0xbfb8aa3b, v44
	v_mul_f32_e32 v49, 0xbfb8aa3b, v45
	v_exp_f32_e32 v48, v48
	v_exp_f32_e32 v49, v49
; DI unsigned pk2(float lo, float hi) { const f32x2_t v = {lo, hi}; const bf16x2_t b = __builtin_convertvector(v, bf16x2_t); return __builtin_bit_cast(unsigned, b); }
;     DI void operator()(const pg8::f32x4 (&acc)[2][2][4][2], const pg8::Unit& u, int wr, int wc, int fr, int fq) const {
;     ...
;             for (int m = 0; m < 4; ++m) {
;                 const int row = row0 + ai * 128 + m * 16; const float r = rs[ai][m];
;                 float hv[8];
; #pragma unroll
;                 for (int n = 0; n < 2; ++n) { const pg8::f32x4 g = acc[ai][0][m][n] * r, uu = acc[ai][1][m][n] * r;
; #pragma unroll
;                     for (int e = 0; e < 4; ++e) hv[4 * n + e] = g[e] * __frcp_rn(1.0f + __expf(-g[e])) * uu[e]; }
;                 u32x4 w; w.x = pk2(hv[0], hv[1]); w.y = pk2(hv[2], hv[3]); w.z = pk2(hv[4], hv[5]); w.w = pk2(hv[6], hv[7]);
;                 *(u32x4*)(H + (size_t)row * DFF + col0) = w;
	s_nop 0
	v_pk_add_f32 v[48:49], v[48:49], 1.0 op_sel_hi:[1,0]
	s_nop 0
	s_nop 0
	v_rcp_f32_e32 v49, v49
	s_nop 0
	v_rcp_f32_e32 v48, v48
	s_nop 0
	v_pk_mul_f32 v[44:45], v[44:45], v[48:49]
	s_nop 0
	v_pk_mul_f32 v[40:41], v[40:41], v[44:45]
	v_pk_mul_f32 v[44:45], v[46:47], v[142:143] op_sel_hi:[1,0]
	s_nop 0
	v_mul_f32_e32 v46, 0xbfb8aa3b, v44
	v_mul_f32_e32 v47, 0xbfb8aa3b, v45
	v_exp_f32_e32 v46, v46
	v_exp_f32_e32 v47, v47
	s_nop 0
	v_pk_add_f32 v[46:47], v[46:47], 1.0 op_sel_hi:[1,0]
	s_nop 0
	s_nop 0
	v_rcp_f32_e32 v47, v47
	s_nop 0
	v_rcp_f32_e32 v46, v46
	s_nop 0
	v_pk_mul_f32 v[44:45], v[44:45], v[46:47]
	s_nop 0
	v_pk_mul_f32 v[42:43], v[42:43], v[44:45]
	v_mul_f32_e32 v44, 0xbfb8aa3b, v36
	v_mul_f32_e32 v45, 0xbfb8aa3b, v37
	v_exp_f32_e32 v44, v44
	v_exp_f32_e32 v45, v45
	s_nop 0
	v_pk_add_f32 v[44:45], v[44:45], 1.0 op_sel_hi:[1,0]
	s_nop 0
	s_nop 0
	v_rcp_f32_e32 v45, v45
	s_nop 0
	v_rcp_f32_e32 v44, v44
	s_nop 0
	v_pk_mul_f32 v[36:37], v[36:37], v[44:45]
	s_nop 0
	v_pk_mul_f32 v[36:37], v[32:33], v[36:37]
	v_pk_mul_f32 v[32:33], v[38:39], v[142:143] op_sel_hi:[1,0]
	s_nop 0
	v_mul_f32_e32 v38, 0xbfb8aa3b, v32
	v_mul_f32_e32 v39, 0xbfb8aa3b, v33
	v_exp_f32_e32 v38, v38
	v_exp_f32_e32 v39, v39
	s_nop 0
	v_pk_add_f32 v[38:39], v[38:39], 1.0 op_sel_hi:[1,0]
	s_nop 0
	s_nop 0
	v_rcp_f32_e32 v39, v39
	s_nop 0
	v_rcp_f32_e32 v38, v38
	s_nop 0
	v_pk_mul_f32 v[32:33], v[32:33], v[38:39]
	v_add_u32_e32 v44, 0x90, v151
	v_pk_mul_f32 v[38:39], v[34:35], v[32:33]
	v_cvt_pk_bf16_f32 v34, v36, v37
	v_mad_i64_i32 v[36:37], s[16:17], v44, s9, v[112:113]
	v_cvt_pk_bf16_f32 v32, v40, v41
	v_cvt_pk_bf16_f32 v33, v42, v43
	v_cvt_pk_bf16_f32 v35, v38, v39
	v_lshl_add_u64 v[36:37], v[36:37], 0, v[114:115]
	global_store_dwordx4 v[36:37], v[32:35], off
	s_nop 1
	v_mul_f32_e32 v32, 0xbfb8aa3b, v28
	v_mul_f32_e32 v33, 0xbfb8aa3b, v29
	v_exp_f32_e32 v32, v32
	v_exp_f32_e32 v33, v33
	s_nop 0
	v_pk_add_f32 v[32:33], v[32:33], 1.0 op_sel_hi:[1,0]
	s_nop 0
	s_nop 0
	v_rcp_f32_e32 v33, v33
	s_nop 0
	v_rcp_f32_e32 v32, v32
	s_nop 0
	v_pk_mul_f32 v[28:29], v[28:29], v[32:33]
	s_nop 0
	v_pk_mul_f32 v[24:25], v[24:25], v[28:29]
	v_pk_mul_f32 v[28:29], v[30:31], v[140:141] op_sel_hi:[1,0]
	s_nop 0
	v_mul_f32_e32 v30, 0xbfb8aa3b, v28
	v_mul_f32_e32 v31, 0xbfb8aa3b, v29
	v_exp_f32_e32 v30, v30
	v_exp_f32_e32 v31, v31
	s_nop 0
	v_pk_add_f32 v[30:31], v[30:31], 1.0 op_sel_hi:[1,0]
	s_nop 0
	s_nop 0
	v_rcp_f32_e32 v31, v31
	s_nop 0
	v_rcp_f32_e32 v30, v30
	s_nop 0
	v_pk_mul_f32 v[28:29], v[28:29], v[30:31]
	s_nop 0
	v_pk_mul_f32 v[26:27], v[26:27], v[28:29]
	v_mul_f32_e32 v28, 0xbfb8aa3b, v20
	v_mul_f32_e32 v29, 0xbfb8aa3b, v21
	v_exp_f32_e32 v28, v28
	v_exp_f32_e32 v29, v29
	s_nop 0
	v_pk_add_f32 v[28:29], v[28:29], 1.0 op_sel_hi:[1,0]
	s_nop 0
	s_nop 0
	v_rcp_f32_e32 v29, v29
	s_nop 0
	v_rcp_f32_e32 v28, v28
	s_nop 0
	v_pk_mul_f32 v[20:21], v[20:21], v[28:29]
	s_nop 0
	v_pk_mul_f32 v[20:21], v[16:17], v[20:21]
	v_pk_mul_f32 v[16:17], v[22:23], v[140:141] op_sel_hi:[1,0]
	s_nop 0
	v_mul_f32_e32 v22, 0xbfb8aa3b, v16
	v_mul_f32_e32 v23, 0xbfb8aa3b, v17
	v_exp_f32_e32 v22, v22
	v_exp_f32_e32 v23, v23
	s_nop 0
	v_pk_add_f32 v[22:23], v[22:23], 1.0 op_sel_hi:[1,0]
	s_nop 0
	s_nop 0
	v_rcp_f32_e32 v23, v23
	s_nop 0
	v_rcp_f32_e32 v22, v22
	s_nop 0
	v_pk_mul_f32 v[16:17], v[16:17], v[22:23]
	v_add_u32_e32 v28, 0xa0, v151
	v_pk_mul_f32 v[22:23], v[18:19], v[16:17]
	v_cvt_pk_bf16_f32 v18, v20, v21
	v_mad_i64_i32 v[20:21], s[16:17], v28, s9, v[112:113]
	v_cvt_pk_bf16_f32 v16, v24, v25
	v_cvt_pk_bf16_f32 v17, v26, v27
	v_cvt_pk_bf16_f32 v19, v22, v23
	v_lshl_add_u64 v[20:21], v[20:21], 0, v[114:115]
	global_store_dwordx4 v[20:21], v[16:19], off
	s_nop 1
	v_mul_f32_e32 v16, 0xbfb8aa3b, v12
	v_mul_f32_e32 v17, 0xbfb8aa3b, v13
	v_exp_f32_e32 v16, v16
	v_exp_f32_e32 v17, v17
	s_nop 0
	v_pk_add_f32 v[16:17], v[16:17], 1.0 op_sel_hi:[1,0]
	s_nop 0
	s_nop 0
	v_rcp_f32_e32 v17, v17
	s_nop 0
	v_rcp_f32_e32 v16, v16
	s_nop 0
	v_pk_mul_f32 v[12:13], v[12:13], v[16:17]
	s_nop 0
	v_pk_mul_f32 v[8:9], v[8:9], v[12:13]
	v_pk_mul_f32 v[12:13], v[14:15], v[138:139] op_sel_hi:[1,0]
	s_nop 0
	v_mul_f32_e32 v14, 0xbfb8aa3b, v12
	v_mul_f32_e32 v15, 0xbfb8aa3b, v13
	v_exp_f32_e32 v14, v14
	v_exp_f32_e32 v15, v15
	s_nop 0
	v_pk_add_f32 v[14:15], v[14:15], 1.0 op_sel_hi:[1,0]
	s_nop 0
	s_nop 0
	v_rcp_f32_e32 v15, v15
	s_nop 0
	v_rcp_f32_e32 v14, v14
	s_nop 0
	v_pk_mul_f32 v[12:13], v[12:13], v[14:15]
	s_nop 0
	v_pk_mul_f32 v[10:11], v[10:11], v[12:13]
	v_mul_f32_e32 v12, 0xbfb8aa3b, v4
	v_mul_f32_e32 v13, 0xbfb8aa3b, v5
	v_exp_f32_e32 v12, v12
	v_exp_f32_e32 v13, v13
	s_nop 0
	v_pk_add_f32 v[12:13], v[12:13], 1.0 op_sel_hi:[1,0]
	s_nop 0
	s_nop 0
	v_rcp_f32_e32 v13, v13
	s_nop 0
	v_rcp_f32_e32 v12, v12
	s_nop 0
	v_pk_mul_f32 v[4:5], v[4:5], v[12:13]
	s_nop 0
	v_pk_mul_f32 v[4:5], v[0:1], v[4:5]
	v_pk_mul_f32 v[0:1], v[6:7], v[138:139] op_sel_hi:[1,0]
	s_nop 0
	v_mul_f32_e32 v6, 0xbfb8aa3b, v0
	v_mul_f32_e32 v7, 0xbfb8aa3b, v1
	v_exp_f32_e32 v6, v6
	v_exp_f32_e32 v7, v7
	s_nop 0
	v_pk_add_f32 v[6:7], v[6:7], 1.0 op_sel_hi:[1,0]
	s_nop 0
	s_nop 0
	v_rcp_f32_e32 v7, v7
	s_nop 0
	v_rcp_f32_e32 v6, v6
	s_nop 0
	v_pk_mul_f32 v[0:1], v[0:1], v[6:7]
	v_add_u32_e32 v12, 0xb0, v151
	v_pk_mul_f32 v[6:7], v[2:3], v[0:1]
	v_cvt_pk_bf16_f32 v2, v4, v5
	v_mad_i64_i32 v[4:5], s[16:17], v12, s9, v[112:113]
	v_cvt_pk_bf16_f32 v0, v8, v9
	v_cvt_pk_bf16_f32 v1, v10, v11
	v_cvt_pk_bf16_f32 v3, v6, v7
	v_lshl_add_u64 v[4:5], v[4:5], 0, v[114:115]
	s_mov_b64 s[16:17], -1
	s_andn2_b64 vcc, exec, s[40:41]
	global_store_dwordx4 v[4:5], v[0:3], off
	s_cbranch_vccnz .LBB0_509
	s_andn2_b64 vcc, exec, s[2:3]
	s_cbranch_vccnz .LBB0_508
	s_barrier
	s_branch .LBB0_508
